# v12 + A1 epilogue: eight rinv loads issued up front, per-row vmcnt(0) drains removed (stores stay in flight while the next row computes)
# speedup vs baseline: 1.0072x; 1.0012x over previous
.LBB0_452:
	v_and_b32_e32 v145, 64, v223
	v_xor_b32_e32 v144, 16, v223
	v_add_u32_e32 v145, 64, v145
	v_cmp_lt_i32_e32 vcc, v144, v145
	s_add_i32 s0, s47, -16
	v_lshl_or_b32 v3, s0, 8, v176
	v_cndmask_b32_e32 v144, v223, v144, vcc
	v_lshlrev_b32_e32 v179, 2, v144
	v_xor_b32_e32 v144, 32, v223
	v_cmp_lt_i32_e32 vcc, v144, v145
	s_lshl_b32 s0, s0, 2
	s_or_b32 s94, s0, s43
	v_cndmask_b32_e32 v144, v223, v144, vcc
	v_lshlrev_b32_e32 v178, 2, v144
	v_lshl_add_u64 v[144:145], v[142:143], 2, s[16:17]
	global_load_dword v150, v[144:145], off
	global_load_dword v201, v[144:145], off offset:64
	global_load_dword v202, v[144:145], off offset:128
	global_load_dword v203, v[144:145], off offset:192
	global_load_dword v204, v[144:145], off offset:512
	global_load_dword v205, v[144:145], off offset:576
	global_load_dword v206, v[144:145], off offset:640
	global_load_dword v207, v[144:145], off offset:704
	s_mov_b32 s0, 0xbb7be14b
	s_mov_b32 s2, 0xbc40d0ac
	s_mov_b32 s28, 0x3cb76c34
	s_mov_b32 s30, 0xbd17b858
	s_mov_b32 s48, 0x3d6537d1
	s_mov_b32 s50, 0xbdacab04
	s_mov_b32 s52, 0x3e342bfa
	v_lshlrev_b64 v[146:147], 12, v[142:143]
	v_lshl_add_u64 v[148:149], s[12:13], 0, v[146:147]
	v_lshlrev_b32_e32 v146, 1, v3
	v_mov_b32_e32 v147, v2
	v_lshl_add_u64 v[148:149], v[148:149], 0, v[146:147]
	s_waitcnt vmcnt(0)
	v_pk_mul_f32 v[156:157], v[128:129], v[150:151] op_sel_hi:[1,0]
	s_nop 0
	v_med3_f32 v158, v156, -4.0, 4.0
	v_med3_f32 v159, v157, -4.0, 4.0
	v_pk_mul_f32 v[152:153], v[158:159], v[158:159]
	v_pk_mul_f32 v[154:155], v[130:131], v[150:151] op_sel_hi:[1,0]
	v_pk_fma_f32 v[160:161], v[152:153], s[72:73], -1.0 op_sel_hi:[1,0,0]
	v_mov_b64_e32 v[152:153], s[0:1]
	v_pk_fma_f32 v[162:163], v[160:161], s[74:75], v[152:153] op_sel_hi:[1,0,0]
	s_mov_b32 s0, 0x3bcff2a2
	v_pk_fma_f32 v[162:163], v[160:161], v[162:163], s[0:1] op_sel_hi:[1,1,0]
	s_nop 0
	v_pk_fma_f32 v[162:163], v[160:161], v[162:163], s[2:3] op_sel_hi:[1,1,0]
	s_nop 0
	v_pk_fma_f32 v[162:163], v[160:161], v[162:163], s[28:29] op_sel_hi:[1,1,0]
	s_nop 0
	v_pk_fma_f32 v[162:163], v[160:161], v[162:163], s[30:31] op_sel_hi:[1,1,0]
	s_nop 0
	v_pk_fma_f32 v[162:163], v[160:161], v[162:163], s[48:49] op_sel_hi:[1,1,0]
	s_nop 0
	v_pk_fma_f32 v[162:163], v[160:161], v[162:163], s[50:51] op_sel_hi:[1,1,0]
	s_nop 0
	v_pk_fma_f32 v[160:161], v[160:161], v[162:163], s[52:53] op_sel_hi:[1,1,0]
	s_nop 0
	v_pk_fma_f32 v[158:159], v[158:159], v[160:161], 0.5 op_sel_hi:[1,1,0]
	s_nop 0
	v_pk_mul_f32 v[166:167], v[156:157], v[158:159]
	v_med3_f32 v156, v154, -4.0, 4.0
	v_med3_f32 v157, v155, -4.0, 4.0
	v_pk_mul_f32 v[158:159], v[156:157], v[156:157]
	s_nop 0
	v_pk_fma_f32 v[158:159], v[158:159], s[72:73], -1.0 op_sel_hi:[1,0,0]
	s_nop 0
	v_pk_fma_f32 v[160:161], v[158:159], s[74:75], v[152:153] op_sel_hi:[1,0,0]
	s_nop 0
	v_pk_fma_f32 v[160:161], v[158:159], v[160:161], s[0:1] op_sel_hi:[1,1,0]
	s_nop 0
	v_pk_fma_f32 v[160:161], v[158:159], v[160:161], s[2:3] op_sel_hi:[1,1,0]
	s_nop 0
	v_pk_fma_f32 v[160:161], v[158:159], v[160:161], s[28:29] op_sel_hi:[1,1,0]
	s_nop 0
	v_pk_fma_f32 v[160:161], v[158:159], v[160:161], s[30:31] op_sel_hi:[1,1,0]
	s_nop 0
	v_pk_fma_f32 v[160:161], v[158:159], v[160:161], s[48:49] op_sel_hi:[1,1,0]
	s_nop 0
	v_pk_fma_f32 v[160:161], v[158:159], v[160:161], s[50:51] op_sel_hi:[1,1,0]
	s_nop 0
	v_pk_fma_f32 v[158:159], v[158:159], v[160:161], s[52:53] op_sel_hi:[1,1,0]
	s_nop 0
	v_pk_fma_f32 v[156:157], v[156:157], v[158:159], 0.5 op_sel_hi:[1,1,0]
	s_nop 0
	v_pk_mul_f32 v[168:169], v[154:155], v[156:157]
	v_pk_mul_f32 v[156:157], v[120:121], v[150:151] op_sel_hi:[1,0]
	v_pk_mul_f32 v[154:155], v[122:123], v[150:151] op_sel_hi:[1,0]
	v_med3_f32 v158, v156, -4.0, 4.0
	v_med3_f32 v159, v157, -4.0, 4.0
	v_pk_mul_f32 v[160:161], v[158:159], v[158:159]
	s_nop 0
	v_pk_fma_f32 v[160:161], v[160:161], s[72:73], -1.0 op_sel_hi:[1,0,0]
	s_nop 0
	v_pk_fma_f32 v[162:163], v[160:161], s[74:75], v[152:153] op_sel_hi:[1,0,0]
	s_nop 0
	v_pk_fma_f32 v[162:163], v[160:161], v[162:163], s[0:1] op_sel_hi:[1,1,0]
	s_nop 0
	v_pk_fma_f32 v[162:163], v[160:161], v[162:163], s[2:3] op_sel_hi:[1,1,0]
	s_nop 0
	v_pk_fma_f32 v[162:163], v[160:161], v[162:163], s[28:29] op_sel_hi:[1,1,0]
	s_nop 0
	v_pk_fma_f32 v[162:163], v[160:161], v[162:163], s[30:31] op_sel_hi:[1,1,0]
	s_nop 0
	v_pk_fma_f32 v[162:163], v[160:161], v[162:163], s[48:49] op_sel_hi:[1,1,0]
	s_nop 0
	v_pk_fma_f32 v[162:163], v[160:161], v[162:163], s[50:51] op_sel_hi:[1,1,0]
	s_nop 0
	v_pk_fma_f32 v[160:161], v[160:161], v[162:163], s[52:53] op_sel_hi:[1,1,0]
	s_nop 0
	v_pk_fma_f32 v[160:161], v[158:159], v[160:161], 0.5 op_sel_hi:[1,1,0]
	v_med3_f32 v158, v154, -4.0, 4.0
	v_med3_f32 v159, v155, -4.0, 4.0
	v_pk_mul_f32 v[162:163], v[158:159], v[158:159]
	v_pk_mul_f32 v[170:171], v[156:157], v[160:161]
	v_pk_fma_f32 v[162:163], v[162:163], s[72:73], -1.0 op_sel_hi:[1,0,0]
	v_pk_fma_f32 v[156:157], v[156:157], v[160:161], v[170:171] op_sel:[0,0,1] op_sel_hi:[1,1,0]
	v_pk_fma_f32 v[164:165], v[162:163], s[74:75], v[152:153] op_sel_hi:[1,0,0]
	s_nop 0
	v_pk_fma_f32 v[164:165], v[162:163], v[164:165], s[0:1] op_sel_hi:[1,1,0]
	s_nop 0
	v_pk_fma_f32 v[164:165], v[162:163], v[164:165], s[2:3] op_sel_hi:[1,1,0]
	s_nop 0
	v_pk_fma_f32 v[164:165], v[162:163], v[164:165], s[28:29] op_sel_hi:[1,1,0]
	s_nop 0
	v_pk_fma_f32 v[164:165], v[162:163], v[164:165], s[30:31] op_sel_hi:[1,1,0]
	s_nop 0
	v_pk_fma_f32 v[164:165], v[162:163], v[164:165], s[48:49] op_sel_hi:[1,1,0]
	s_nop 0
	v_pk_fma_f32 v[164:165], v[162:163], v[164:165], s[50:51] op_sel_hi:[1,1,0]
	s_nop 0
	v_pk_fma_f32 v[162:163], v[162:163], v[164:165], s[52:53] op_sel_hi:[1,1,0]
	v_mov_b32_e32 v164, v167
	v_mov_b32_e32 v165, v169
	v_pk_fma_f32 v[158:159], v[158:159], v[162:163], 0.5 op_sel_hi:[1,1,0]
	v_mov_b32_e32 v162, v166
	v_mov_b32_e32 v163, v168
	v_pk_mul_f32 v[160:161], v[164:165], v[164:165]
	v_pk_mul_f32 v[158:159], v[154:155], v[158:159]
	v_pk_fma_f32 v[160:161], v[162:163], v[162:163], v[160:161]
	v_cvt_pk_bf16_f32 v166, v166, v167
	v_pk_add_f32 v[160:161], v[160:161], v[160:161] op_sel_hi:[0,1]
	v_cvt_pk_bf16_f32 v167, v168, v169
	v_cvt_pk_bf16_f32 v168, v170, v171
	v_cvt_pk_bf16_f32 v169, v158, v159
	v_mul_f32_e32 v160, v170, v170
	global_store_dwordx4 v[148:149], v[166:169], off
	v_pk_add_f32 v[154:155], v[162:163], v[164:165]
	v_pk_fma_f32 v[162:163], v[170:171], v[170:171], v[160:161] op_sel_hi:[1,1,0]
	v_pk_mul_f32 v[168:169], v[124:125], v[150:151] op_sel_hi:[1,0]
	v_pk_mul_f32 v[166:167], v[126:127], v[150:151] op_sel_hi:[1,0]
	v_med3_f32 v170, v168, -4.0, 4.0
	v_med3_f32 v171, v169, -4.0, 4.0
	v_pk_mul_f32 v[172:173], v[170:171], v[170:171]
	v_pk_mul_f32 v[164:165], v[158:159], v[158:159]
	v_pk_fma_f32 v[172:173], v[172:173], s[72:73], -1.0 op_sel_hi:[1,0,0]
	v_pk_add_f32 v[154:155], v[154:155], v[154:155] op_sel:[0,1] op_sel_hi:[1,0]
	v_pk_fma_f32 v[180:181], v[172:173], s[74:75], v[152:153] op_sel_hi:[1,0,0]
	s_nop 0
	v_pk_fma_f32 v[180:181], v[172:173], v[180:181], s[0:1] op_sel_hi:[1,1,0]
	s_nop 0
	v_pk_fma_f32 v[180:181], v[172:173], v[180:181], s[2:3] op_sel_hi:[1,1,0]
	s_nop 0
	v_pk_fma_f32 v[180:181], v[172:173], v[180:181], s[28:29] op_sel_hi:[1,1,0]
	s_nop 0
	v_pk_fma_f32 v[180:181], v[172:173], v[180:181], s[30:31] op_sel_hi:[1,1,0]
	s_nop 0
	v_pk_fma_f32 v[180:181], v[172:173], v[180:181], s[48:49] op_sel_hi:[1,1,0]
	s_nop 0
	v_pk_fma_f32 v[180:181], v[172:173], v[180:181], s[50:51] op_sel_hi:[1,1,0]
	s_nop 0
	v_pk_fma_f32 v[172:173], v[172:173], v[180:181], s[52:53] op_sel_hi:[1,1,0]
	s_nop 0
	v_pk_fma_f32 v[170:171], v[170:171], v[172:173], 0.5 op_sel_hi:[1,1,0]
	s_nop 0
	v_pk_mul_f32 v[168:169], v[168:169], v[170:171]
	v_med3_f32 v170, v166, -4.0, 4.0
	v_med3_f32 v171, v167, -4.0, 4.0
	v_pk_mul_f32 v[172:173], v[170:171], v[170:171]
	s_nop 0
	v_pk_fma_f32 v[172:173], v[172:173], s[72:73], -1.0 op_sel_hi:[1,0,0]
	s_nop 0
	v_pk_fma_f32 v[180:181], v[172:173], s[74:75], v[152:153] op_sel_hi:[1,0,0]
	s_nop 0
	v_pk_fma_f32 v[180:181], v[172:173], v[180:181], s[0:1] op_sel_hi:[1,1,0]
	s_nop 0
	v_pk_fma_f32 v[180:181], v[172:173], v[180:181], s[2:3] op_sel_hi:[1,1,0]
	s_nop 0
	v_pk_fma_f32 v[180:181], v[172:173], v[180:181], s[28:29] op_sel_hi:[1,1,0]
	s_nop 0
	v_pk_fma_f32 v[180:181], v[172:173], v[180:181], s[30:31] op_sel_hi:[1,1,0]
	s_nop 0
	v_pk_fma_f32 v[180:181], v[172:173], v[180:181], s[48:49] op_sel_hi:[1,1,0]
	s_nop 0
	v_pk_fma_f32 v[180:181], v[172:173], v[180:181], s[50:51] op_sel_hi:[1,1,0]
	s_nop 0
	v_pk_fma_f32 v[172:173], v[172:173], v[180:181], s[52:53] op_sel_hi:[1,1,0]
	s_nop 0
	v_pk_fma_f32 v[170:171], v[170:171], v[172:173], 0.5 op_sel_hi:[1,1,0]
	s_nop 0
	v_pk_mul_f32 v[166:167], v[166:167], v[170:171]
	v_pk_mul_f32 v[170:171], v[118:119], v[150:151] op_sel_hi:[1,0]
	v_pk_mul_f32 v[150:151], v[116:117], v[150:151] op_sel_hi:[1,0]
	s_nop 0
	v_med3_f32 v172, v150, -4.0, 4.0
	v_med3_f32 v173, v151, -4.0, 4.0
	v_pk_mul_f32 v[180:181], v[172:173], v[172:173]
	s_nop 0
	v_pk_fma_f32 v[180:181], v[180:181], s[72:73], -1.0 op_sel_hi:[1,0,0]
	s_nop 0
	v_pk_fma_f32 v[182:183], v[180:181], s[74:75], v[152:153] op_sel_hi:[1,0,0]
	s_nop 0
	v_pk_fma_f32 v[182:183], v[180:181], v[182:183], s[0:1] op_sel_hi:[1,1,0]
	s_nop 0
	v_pk_fma_f32 v[182:183], v[180:181], v[182:183], s[2:3] op_sel_hi:[1,1,0]
	s_nop 0
	v_pk_fma_f32 v[182:183], v[180:181], v[182:183], s[28:29] op_sel_hi:[1,1,0]
	s_nop 0
	v_pk_fma_f32 v[182:183], v[180:181], v[182:183], s[30:31] op_sel_hi:[1,1,0]
	s_nop 0
	v_pk_fma_f32 v[182:183], v[180:181], v[182:183], s[48:49] op_sel_hi:[1,1,0]
	s_nop 0
	v_pk_fma_f32 v[182:183], v[180:181], v[182:183], s[50:51] op_sel_hi:[1,1,0]
	s_nop 0
	v_pk_fma_f32 v[180:181], v[180:181], v[182:183], s[52:53] op_sel_hi:[1,1,0]
	v_med3_f32 v182, v170, -4.0, 4.0
	v_med3_f32 v183, v171, -4.0, 4.0
	v_pk_mul_f32 v[184:185], v[182:183], v[182:183]
	v_pk_fma_f32 v[172:173], v[172:173], v[180:181], 0.5 op_sel_hi:[1,1,0]
	v_pk_fma_f32 v[184:185], v[184:185], s[72:73], -1.0 op_sel_hi:[1,0,0]
	v_pk_mul_f32 v[180:181], v[150:151], v[172:173]
	v_pk_fma_f32 v[152:153], v[184:185], s[74:75], v[152:153] op_sel_hi:[1,0,0]
	v_pk_fma_f32 v[172:173], v[150:151], v[172:173], v[180:181] op_sel:[0,0,1] op_sel_hi:[1,1,0]
	v_pk_fma_f32 v[152:153], v[184:185], v[152:153], s[0:1] op_sel_hi:[1,1,0]
	v_mul_f32_e32 v150, v168, v168
	v_pk_fma_f32 v[152:153], v[184:185], v[152:153], s[2:3] op_sel_hi:[1,1,0]
	v_pk_mul_f32 v[188:189], v[180:181], v[180:181]
	v_pk_fma_f32 v[152:153], v[184:185], v[152:153], s[28:29] op_sel_hi:[1,1,0]
	v_mov_b32_e32 v173, v164
	v_pk_fma_f32 v[152:153], v[184:185], v[152:153], s[30:31] op_sel_hi:[1,1,0]
	v_mov_b32_e32 v157, v188
	v_pk_fma_f32 v[152:153], v[184:185], v[152:153], s[48:49] op_sel_hi:[1,1,0]
	v_mov_b32_e32 v155, v189
	v_pk_fma_f32 v[152:153], v[184:185], v[152:153], s[50:51] op_sel_hi:[1,1,0]
	s_nop 0
	v_pk_fma_f32 v[152:153], v[184:185], v[152:153], s[52:53] op_sel_hi:[1,1,0]
	v_pk_fma_f32 v[184:185], v[168:169], v[168:169], v[150:151] op_sel_hi:[1,1,0]
	v_pk_fma_f32 v[152:153], v[182:183], v[152:153], 0.5 op_sel_hi:[1,1,0]
	v_mov_b32_e32 v182, v169
	v_pk_mul_f32 v[170:171], v[170:171], v[152:153]
	v_mov_b32_e32 v152, v168
	v_mov_b32_e32 v153, v166
	v_mov_b32_e32 v183, v167
	v_pk_add_f32 v[152:153], v[152:153], v[182:183]
	v_mul_f32_e32 v150, v166, v166
	v_pk_add_f32 v[182:183], v[152:153], v[152:153] op_sel:[0,1] op_sel_hi:[1,0]
	v_pk_fma_f32 v[186:187], v[166:167], v[166:167], v[150:151] op_sel_hi:[1,1,0]
	v_mul_f32_e32 v150, v170, v170
	v_pk_fma_f32 v[190:191], v[170:171], v[170:171], v[150:151] op_sel_hi:[1,1,0]
	v_cvt_pk_bf16_f32 v150, v168, v169
	v_cvt_pk_bf16_f32 v151, v166, v167
	v_cvt_pk_bf16_f32 v152, v180, v181
	v_cvt_pk_bf16_f32 v153, v170, v171
	v_mov_b32_e32 v183, v165
	v_mov_b32_e32 v162, v170
	v_mov_b32_e32 v160, v171
	global_store_dwordx4 v[148:149], v[150:153], off offset:256
	v_pk_add_f32 v[148:149], v[172:173], v[182:183]
	v_mov_b32_e32 v184, v158
	v_pk_add_f32 v[150:151], v[162:163], v[160:161]
	v_mov_b32_e32 v186, v159
	v_pk_add_f32 v[148:149], v[148:149], v[150:151]
	v_pk_add_f32 v[150:151], v[184:185], v[186:187]
	v_pk_add_f32 v[152:153], v[156:157], v[154:155]
	v_mov_b32_e32 v3, v191
	v_pk_add_f32 v[150:151], v[152:153], v[150:151]
	s_nop 0
	v_pk_add_f32 v[150:151], v[150:151], v[2:3]
	s_nop 0
	v_pk_add_f32 v[148:149], v[148:149], v[150:151]
	ds_bpermute_b32 v150, v179, v148
	ds_bpermute_b32 v151, v179, v149
	s_waitcnt lgkmcnt(0)
	v_pk_add_f32 v[148:149], v[148:149], v[150:151]
	ds_bpermute_b32 v150, v178, v148
	ds_bpermute_b32 v151, v178, v149
	s_and_saveexec_b64 s[0:1], s[4:5]
	s_cbranch_execz .LBB0_454
	v_lshlrev_b64 v[152:153], 8, v[142:143]
	s_waitcnt lgkmcnt(0)
	v_pk_add_f32 v[148:149], v[148:149], v[150:151]
	v_lshl_add_u64 v[150:151], s[14:15], 0, v[152:153]
	v_lshl_add_u64 v[150:151], s[94:95], 3, v[150:151]
	global_store_dwordx2 v[150:151], v[148:149], off
.LBB0_454:
	s_or_b64 exec, exec, s[0:1]
	v_or_b32_e32 v148, 16, v142
	v_ashrrev_i32_e32 v149, 31, v148
	s_waitcnt lgkmcnt(0)
	v_lshl_add_u64 v[150:151], v[148:149], 2, s[16:17]
	s_nop 1
	v_mov_b32_e32 v152, v201
	s_mov_b32 s0, 0xbb7be14b
	v_lshlrev_b64 v[150:151], 12, v[148:149]
	v_lshl_add_u64 v[150:151], s[12:13], 0, v[150:151]
	v_lshl_add_u64 v[150:151], v[150:151], 0, v[146:147]
	v_pk_mul_f32 v[158:159], v[112:113], v[152:153] op_sel_hi:[1,0]
	s_nop 0
	v_med3_f32 v160, v158, -4.0, 4.0
	v_med3_f32 v161, v159, -4.0, 4.0
	v_pk_mul_f32 v[154:155], v[160:161], v[160:161]
	v_pk_mul_f32 v[156:157], v[114:115], v[152:153] op_sel_hi:[1,0]
	v_pk_fma_f32 v[162:163], v[154:155], s[72:73], -1.0 op_sel_hi:[1,0,0]
	v_mov_b64_e32 v[154:155], s[0:1]
	v_pk_fma_f32 v[164:165], v[162:163], s[74:75], v[154:155] op_sel_hi:[1,0,0]
	s_mov_b32 s0, 0x3bcff2a2
	v_pk_fma_f32 v[164:165], v[162:163], v[164:165], s[0:1] op_sel_hi:[1,1,0]
	s_nop 0
	v_pk_fma_f32 v[164:165], v[162:163], v[164:165], s[2:3] op_sel_hi:[1,1,0]
	s_nop 0
	v_pk_fma_f32 v[164:165], v[162:163], v[164:165], s[28:29] op_sel_hi:[1,1,0]
	s_nop 0
	v_pk_fma_f32 v[164:165], v[162:163], v[164:165], s[30:31] op_sel_hi:[1,1,0]
	s_nop 0
	v_pk_fma_f32 v[164:165], v[162:163], v[164:165], s[48:49] op_sel_hi:[1,1,0]
	s_nop 0
	v_pk_fma_f32 v[164:165], v[162:163], v[164:165], s[50:51] op_sel_hi:[1,1,0]
	s_nop 0
	v_pk_fma_f32 v[162:163], v[162:163], v[164:165], s[52:53] op_sel_hi:[1,1,0]
	s_nop 0
	v_pk_fma_f32 v[160:161], v[160:161], v[162:163], 0.5 op_sel_hi:[1,1,0]
	s_nop 0
	v_pk_mul_f32 v[168:169], v[158:159], v[160:161]
	v_med3_f32 v158, v156, -4.0, 4.0
	v_med3_f32 v159, v157, -4.0, 4.0
	v_pk_mul_f32 v[160:161], v[158:159], v[158:159]
	s_nop 0
	v_pk_fma_f32 v[160:161], v[160:161], s[72:73], -1.0 op_sel_hi:[1,0,0]
	s_nop 0
	v_pk_fma_f32 v[162:163], v[160:161], s[74:75], v[154:155] op_sel_hi:[1,0,0]
	s_nop 0
	v_pk_fma_f32 v[162:163], v[160:161], v[162:163], s[0:1] op_sel_hi:[1,1,0]
	s_nop 0
	v_pk_fma_f32 v[162:163], v[160:161], v[162:163], s[2:3] op_sel_hi:[1,1,0]
	s_nop 0
	v_pk_fma_f32 v[162:163], v[160:161], v[162:163], s[28:29] op_sel_hi:[1,1,0]
	s_nop 0
	v_pk_fma_f32 v[162:163], v[160:161], v[162:163], s[30:31] op_sel_hi:[1,1,0]
	s_nop 0
	v_pk_fma_f32 v[162:163], v[160:161], v[162:163], s[48:49] op_sel_hi:[1,1,0]
	s_nop 0
	v_pk_fma_f32 v[162:163], v[160:161], v[162:163], s[50:51] op_sel_hi:[1,1,0]
	s_nop 0
	v_pk_fma_f32 v[160:161], v[160:161], v[162:163], s[52:53] op_sel_hi:[1,1,0]
	s_nop 0
	v_pk_fma_f32 v[158:159], v[158:159], v[160:161], 0.5 op_sel_hi:[1,1,0]
	s_nop 0
	v_pk_mul_f32 v[170:171], v[156:157], v[158:159]
	v_pk_mul_f32 v[158:159], v[104:105], v[152:153] op_sel_hi:[1,0]
	v_pk_mul_f32 v[156:157], v[106:107], v[152:153] op_sel_hi:[1,0]
	v_med3_f32 v160, v158, -4.0, 4.0
	v_med3_f32 v161, v159, -4.0, 4.0
	v_pk_mul_f32 v[162:163], v[160:161], v[160:161]
	s_nop 0
	v_pk_fma_f32 v[162:163], v[162:163], s[72:73], -1.0 op_sel_hi:[1,0,0]
	s_nop 0
	v_pk_fma_f32 v[164:165], v[162:163], s[74:75], v[154:155] op_sel_hi:[1,0,0]
	s_nop 0
	v_pk_fma_f32 v[164:165], v[162:163], v[164:165], s[0:1] op_sel_hi:[1,1,0]
	s_nop 0
	v_pk_fma_f32 v[164:165], v[162:163], v[164:165], s[2:3] op_sel_hi:[1,1,0]
	s_nop 0
	v_pk_fma_f32 v[164:165], v[162:163], v[164:165], s[28:29] op_sel_hi:[1,1,0]
	s_nop 0
	v_pk_fma_f32 v[164:165], v[162:163], v[164:165], s[30:31] op_sel_hi:[1,1,0]
	s_nop 0
	v_pk_fma_f32 v[164:165], v[162:163], v[164:165], s[48:49] op_sel_hi:[1,1,0]
	s_nop 0
	v_pk_fma_f32 v[164:165], v[162:163], v[164:165], s[50:51] op_sel_hi:[1,1,0]
	s_nop 0
	v_pk_fma_f32 v[162:163], v[162:163], v[164:165], s[52:53] op_sel_hi:[1,1,0]
	s_nop 0
	v_pk_fma_f32 v[162:163], v[160:161], v[162:163], 0.5 op_sel_hi:[1,1,0]
	v_med3_f32 v160, v156, -4.0, 4.0
	v_med3_f32 v161, v157, -4.0, 4.0
	v_pk_mul_f32 v[164:165], v[160:161], v[160:161]
	v_pk_mul_f32 v[172:173], v[158:159], v[162:163]
	v_pk_fma_f32 v[164:165], v[164:165], s[72:73], -1.0 op_sel_hi:[1,0,0]
	v_pk_fma_f32 v[158:159], v[158:159], v[162:163], v[172:173] op_sel:[0,0,1] op_sel_hi:[1,1,0]
	v_pk_fma_f32 v[166:167], v[164:165], s[74:75], v[154:155] op_sel_hi:[1,0,0]
	s_nop 0
	v_pk_fma_f32 v[166:167], v[164:165], v[166:167], s[0:1] op_sel_hi:[1,1,0]
	s_nop 0
	v_pk_fma_f32 v[166:167], v[164:165], v[166:167], s[2:3] op_sel_hi:[1,1,0]
	s_nop 0
	v_pk_fma_f32 v[166:167], v[164:165], v[166:167], s[28:29] op_sel_hi:[1,1,0]
	s_nop 0
	v_pk_fma_f32 v[166:167], v[164:165], v[166:167], s[30:31] op_sel_hi:[1,1,0]
	s_nop 0
	v_pk_fma_f32 v[166:167], v[164:165], v[166:167], s[48:49] op_sel_hi:[1,1,0]
	s_nop 0
	v_pk_fma_f32 v[166:167], v[164:165], v[166:167], s[50:51] op_sel_hi:[1,1,0]
	s_nop 0
	v_pk_fma_f32 v[164:165], v[164:165], v[166:167], s[52:53] op_sel_hi:[1,1,0]
	v_mov_b32_e32 v166, v169
	v_mov_b32_e32 v167, v171
	v_pk_fma_f32 v[160:161], v[160:161], v[164:165], 0.5 op_sel_hi:[1,1,0]
	v_mov_b32_e32 v164, v168
	v_mov_b32_e32 v165, v170
	v_pk_mul_f32 v[162:163], v[166:167], v[166:167]
	v_pk_mul_f32 v[160:161], v[156:157], v[160:161]
	v_pk_fma_f32 v[162:163], v[164:165], v[164:165], v[162:163]
	v_cvt_pk_bf16_f32 v168, v168, v169
	v_pk_add_f32 v[162:163], v[162:163], v[162:163] op_sel_hi:[0,1]
	v_cvt_pk_bf16_f32 v169, v170, v171
	v_cvt_pk_bf16_f32 v170, v172, v173
	v_cvt_pk_bf16_f32 v171, v160, v161
	v_mul_f32_e32 v162, v172, v172
	global_store_dwordx4 v[150:151], v[168:171], off
	v_pk_add_f32 v[156:157], v[164:165], v[166:167]
	v_pk_fma_f32 v[164:165], v[172:173], v[172:173], v[162:163] op_sel_hi:[1,1,0]
	v_pk_mul_f32 v[168:169], v[108:109], v[152:153] op_sel_hi:[1,0]
	v_pk_mul_f32 v[170:171], v[110:111], v[152:153] op_sel_hi:[1,0]
	v_med3_f32 v172, v168, -4.0, 4.0
	v_med3_f32 v173, v169, -4.0, 4.0
	v_pk_mul_f32 v[180:181], v[172:173], v[172:173]
	v_pk_mul_f32 v[166:167], v[160:161], v[160:161]
	v_pk_fma_f32 v[180:181], v[180:181], s[72:73], -1.0 op_sel_hi:[1,0,0]
	v_pk_add_f32 v[156:157], v[156:157], v[156:157] op_sel:[0,1] op_sel_hi:[1,0]
	v_pk_fma_f32 v[182:183], v[180:181], s[74:75], v[154:155] op_sel_hi:[1,0,0]
	s_nop 0
	v_pk_fma_f32 v[182:183], v[180:181], v[182:183], s[0:1] op_sel_hi:[1,1,0]
	s_nop 0
	v_pk_fma_f32 v[182:183], v[180:181], v[182:183], s[2:3] op_sel_hi:[1,1,0]
	s_nop 0
	v_pk_fma_f32 v[182:183], v[180:181], v[182:183], s[28:29] op_sel_hi:[1,1,0]
	s_nop 0
	v_pk_fma_f32 v[182:183], v[180:181], v[182:183], s[30:31] op_sel_hi:[1,1,0]
	s_nop 0
	v_pk_fma_f32 v[182:183], v[180:181], v[182:183], s[48:49] op_sel_hi:[1,1,0]
	s_nop 0
	v_pk_fma_f32 v[182:183], v[180:181], v[182:183], s[50:51] op_sel_hi:[1,1,0]
	s_nop 0
	v_pk_fma_f32 v[180:181], v[180:181], v[182:183], s[52:53] op_sel_hi:[1,1,0]
	s_nop 0
	v_pk_fma_f32 v[172:173], v[172:173], v[180:181], 0.5 op_sel_hi:[1,1,0]
	s_nop 0
	v_pk_mul_f32 v[168:169], v[168:169], v[172:173]
	v_med3_f32 v172, v170, -4.0, 4.0
	v_med3_f32 v173, v171, -4.0, 4.0
	v_pk_mul_f32 v[180:181], v[172:173], v[172:173]
	s_nop 0
	v_pk_fma_f32 v[180:181], v[180:181], s[72:73], -1.0 op_sel_hi:[1,0,0]
	s_nop 0
	v_pk_fma_f32 v[182:183], v[180:181], s[74:75], v[154:155] op_sel_hi:[1,0,0]
	s_nop 0
	v_pk_fma_f32 v[182:183], v[180:181], v[182:183], s[0:1] op_sel_hi:[1,1,0]
	s_nop 0
	v_pk_fma_f32 v[182:183], v[180:181], v[182:183], s[2:3] op_sel_hi:[1,1,0]
	s_nop 0
	v_pk_fma_f32 v[182:183], v[180:181], v[182:183], s[28:29] op_sel_hi:[1,1,0]
	s_nop 0
	v_pk_fma_f32 v[182:183], v[180:181], v[182:183], s[30:31] op_sel_hi:[1,1,0]
	s_nop 0
	v_pk_fma_f32 v[182:183], v[180:181], v[182:183], s[48:49] op_sel_hi:[1,1,0]
	s_nop 0
	v_pk_fma_f32 v[182:183], v[180:181], v[182:183], s[50:51] op_sel_hi:[1,1,0]
	s_nop 0
	v_pk_fma_f32 v[180:181], v[180:181], v[182:183], s[52:53] op_sel_hi:[1,1,0]
	s_nop 0
	v_pk_fma_f32 v[172:173], v[172:173], v[180:181], 0.5 op_sel_hi:[1,1,0]
	s_nop 0
	v_pk_mul_f32 v[170:171], v[170:171], v[172:173]
	v_pk_mul_f32 v[172:173], v[102:103], v[152:153] op_sel_hi:[1,0]
	v_pk_mul_f32 v[152:153], v[100:101], v[152:153] op_sel_hi:[1,0]
	s_nop 0
	v_med3_f32 v180, v152, -4.0, 4.0
	v_med3_f32 v181, v153, -4.0, 4.0
	v_pk_mul_f32 v[182:183], v[180:181], v[180:181]
	s_nop 0
	v_pk_fma_f32 v[182:183], v[182:183], s[72:73], -1.0 op_sel_hi:[1,0,0]
	s_nop 0
	v_pk_fma_f32 v[184:185], v[182:183], s[74:75], v[154:155] op_sel_hi:[1,0,0]
	s_nop 0
	v_pk_fma_f32 v[184:185], v[182:183], v[184:185], s[0:1] op_sel_hi:[1,1,0]
	s_nop 0
	v_pk_fma_f32 v[184:185], v[182:183], v[184:185], s[2:3] op_sel_hi:[1,1,0]
	s_nop 0
	v_pk_fma_f32 v[184:185], v[182:183], v[184:185], s[28:29] op_sel_hi:[1,1,0]
	s_nop 0
	v_pk_fma_f32 v[184:185], v[182:183], v[184:185], s[30:31] op_sel_hi:[1,1,0]
	s_nop 0
	v_pk_fma_f32 v[184:185], v[182:183], v[184:185], s[48:49] op_sel_hi:[1,1,0]
	s_nop 0
	v_pk_fma_f32 v[184:185], v[182:183], v[184:185], s[50:51] op_sel_hi:[1,1,0]
	s_nop 0
	v_pk_fma_f32 v[182:183], v[182:183], v[184:185], s[52:53] op_sel_hi:[1,1,0]
	v_med3_f32 v184, v172, -4.0, 4.0
	v_med3_f32 v185, v173, -4.0, 4.0
	v_pk_mul_f32 v[186:187], v[184:185], v[184:185]
	v_pk_fma_f32 v[180:181], v[180:181], v[182:183], 0.5 op_sel_hi:[1,1,0]
	v_pk_fma_f32 v[186:187], v[186:187], s[72:73], -1.0 op_sel_hi:[1,0,0]
	v_pk_mul_f32 v[182:183], v[152:153], v[180:181]
	v_pk_fma_f32 v[154:155], v[186:187], s[74:75], v[154:155] op_sel_hi:[1,0,0]
	v_pk_fma_f32 v[180:181], v[152:153], v[180:181], v[182:183] op_sel:[0,0,1] op_sel_hi:[1,1,0]
	v_pk_fma_f32 v[154:155], v[186:187], v[154:155], s[0:1] op_sel_hi:[1,1,0]
	v_mul_f32_e32 v152, v168, v168
	v_pk_fma_f32 v[154:155], v[186:187], v[154:155], s[2:3] op_sel_hi:[1,1,0]
	v_pk_mul_f32 v[190:191], v[182:183], v[182:183]
	v_pk_fma_f32 v[154:155], v[186:187], v[154:155], s[28:29] op_sel_hi:[1,1,0]
	v_mov_b32_e32 v181, v166
	v_pk_fma_f32 v[154:155], v[186:187], v[154:155], s[30:31] op_sel_hi:[1,1,0]
	v_mov_b32_e32 v159, v190
	v_pk_fma_f32 v[154:155], v[186:187], v[154:155], s[48:49] op_sel_hi:[1,1,0]
	v_mov_b32_e32 v157, v191
	v_pk_fma_f32 v[154:155], v[186:187], v[154:155], s[50:51] op_sel_hi:[1,1,0]
	s_nop 0
	v_pk_fma_f32 v[154:155], v[186:187], v[154:155], s[52:53] op_sel_hi:[1,1,0]
	v_pk_fma_f32 v[186:187], v[168:169], v[168:169], v[152:153] op_sel_hi:[1,1,0]
	v_pk_fma_f32 v[154:155], v[184:185], v[154:155], 0.5 op_sel_hi:[1,1,0]
	v_mov_b32_e32 v184, v169
	v_pk_mul_f32 v[172:173], v[172:173], v[154:155]
	v_mov_b32_e32 v154, v168
	v_mov_b32_e32 v155, v170
	v_mov_b32_e32 v185, v171
	v_pk_add_f32 v[154:155], v[154:155], v[184:185]
	v_mul_f32_e32 v152, v170, v170
	v_pk_add_f32 v[184:185], v[154:155], v[154:155] op_sel:[0,1] op_sel_hi:[1,0]
	v_pk_fma_f32 v[188:189], v[170:171], v[170:171], v[152:153] op_sel_hi:[1,1,0]
	v_mul_f32_e32 v152, v172, v172
	v_pk_fma_f32 v[192:193], v[172:173], v[172:173], v[152:153] op_sel_hi:[1,1,0]
	v_cvt_pk_bf16_f32 v152, v168, v169
	v_cvt_pk_bf16_f32 v153, v170, v171
	v_cvt_pk_bf16_f32 v154, v182, v183
	v_cvt_pk_bf16_f32 v155, v172, v173
	v_mov_b32_e32 v185, v167
	v_mov_b32_e32 v164, v172
	v_mov_b32_e32 v162, v173
	global_store_dwordx4 v[150:151], v[152:155], off offset:256
	v_pk_add_f32 v[150:151], v[180:181], v[184:185]
	v_mov_b32_e32 v186, v160
	v_pk_add_f32 v[152:153], v[164:165], v[162:163]
	v_mov_b32_e32 v188, v161
	v_pk_add_f32 v[150:151], v[150:151], v[152:153]
	v_pk_add_f32 v[152:153], v[186:187], v[188:189]
	v_pk_add_f32 v[154:155], v[158:159], v[156:157]
	v_mov_b32_e32 v3, v193
	v_pk_add_f32 v[152:153], v[154:155], v[152:153]
	s_nop 0
	v_pk_add_f32 v[152:153], v[152:153], v[2:3]
	s_nop 0
	v_pk_add_f32 v[150:151], v[150:151], v[152:153]
	ds_bpermute_b32 v152, v179, v150
	ds_bpermute_b32 v153, v179, v151
	s_waitcnt lgkmcnt(0)
	v_pk_add_f32 v[150:151], v[150:151], v[152:153]
	ds_bpermute_b32 v152, v178, v150
	ds_bpermute_b32 v153, v178, v151
	s_and_saveexec_b64 s[0:1], s[4:5]
	s_cbranch_execz .LBB0_456
	v_lshlrev_b64 v[148:149], 8, v[148:149]
	v_lshl_add_u64 v[148:149], s[14:15], 0, v[148:149]
	s_waitcnt lgkmcnt(0)
	v_pk_add_f32 v[150:151], v[150:151], v[152:153]
	v_lshl_add_u64 v[148:149], s[94:95], 3, v[148:149]
	global_store_dwordx2 v[148:149], v[150:151], off
.LBB0_456:
	s_or_b64 exec, exec, s[0:1]
	v_or_b32_e32 v148, 32, v142
	v_ashrrev_i32_e32 v149, 31, v148
	v_lshl_add_u64 v[150:151], v[148:149], 2, s[16:17]
	s_waitcnt lgkmcnt(1)
	s_nop 1
	v_mov_b32_e32 v152, v202
	s_mov_b32 s0, 0xbb7be14b
	v_lshlrev_b64 v[150:151], 12, v[148:149]
	v_lshl_add_u64 v[150:151], s[12:13], 0, v[150:151]
	v_mov_b32_e32 v147, v2
	v_lshl_add_u64 v[150:151], v[150:151], 0, v[146:147]
	s_waitcnt lgkmcnt(0)
	v_pk_mul_f32 v[158:159], v[96:97], v[152:153] op_sel_hi:[1,0]
	s_nop 0
	v_med3_f32 v160, v158, -4.0, 4.0
	v_med3_f32 v161, v159, -4.0, 4.0
	v_pk_mul_f32 v[154:155], v[160:161], v[160:161]
	v_pk_mul_f32 v[156:157], v[98:99], v[152:153] op_sel_hi:[1,0]
	v_pk_fma_f32 v[162:163], v[154:155], s[72:73], -1.0 op_sel_hi:[1,0,0]
	v_mov_b64_e32 v[154:155], s[0:1]
	v_pk_fma_f32 v[164:165], v[162:163], s[74:75], v[154:155] op_sel_hi:[1,0,0]
	s_mov_b32 s0, 0x3bcff2a2
	v_pk_fma_f32 v[164:165], v[162:163], v[164:165], s[0:1] op_sel_hi:[1,1,0]
	s_nop 0
	v_pk_fma_f32 v[164:165], v[162:163], v[164:165], s[2:3] op_sel_hi:[1,1,0]
	s_nop 0
	v_pk_fma_f32 v[164:165], v[162:163], v[164:165], s[28:29] op_sel_hi:[1,1,0]
	s_nop 0
	v_pk_fma_f32 v[164:165], v[162:163], v[164:165], s[30:31] op_sel_hi:[1,1,0]
	s_nop 0
	v_pk_fma_f32 v[164:165], v[162:163], v[164:165], s[48:49] op_sel_hi:[1,1,0]
	s_nop 0
	v_pk_fma_f32 v[164:165], v[162:163], v[164:165], s[50:51] op_sel_hi:[1,1,0]
	s_nop 0
	v_pk_fma_f32 v[162:163], v[162:163], v[164:165], s[52:53] op_sel_hi:[1,1,0]
	s_nop 0
	v_pk_fma_f32 v[160:161], v[160:161], v[162:163], 0.5 op_sel_hi:[1,1,0]
	s_nop 0
	v_pk_mul_f32 v[168:169], v[158:159], v[160:161]
	v_med3_f32 v158, v156, -4.0, 4.0
	v_med3_f32 v159, v157, -4.0, 4.0
	v_pk_mul_f32 v[160:161], v[158:159], v[158:159]
	s_nop 0
	v_pk_fma_f32 v[160:161], v[160:161], s[72:73], -1.0 op_sel_hi:[1,0,0]
	s_nop 0
	v_pk_fma_f32 v[162:163], v[160:161], s[74:75], v[154:155] op_sel_hi:[1,0,0]
	s_nop 0
	v_pk_fma_f32 v[162:163], v[160:161], v[162:163], s[0:1] op_sel_hi:[1,1,0]
	s_nop 0
	v_pk_fma_f32 v[162:163], v[160:161], v[162:163], s[2:3] op_sel_hi:[1,1,0]
	s_nop 0
	v_pk_fma_f32 v[162:163], v[160:161], v[162:163], s[28:29] op_sel_hi:[1,1,0]
	s_nop 0
	v_pk_fma_f32 v[162:163], v[160:161], v[162:163], s[30:31] op_sel_hi:[1,1,0]
	s_nop 0
	v_pk_fma_f32 v[162:163], v[160:161], v[162:163], s[48:49] op_sel_hi:[1,1,0]
	s_nop 0
	v_pk_fma_f32 v[162:163], v[160:161], v[162:163], s[50:51] op_sel_hi:[1,1,0]
	s_nop 0
	v_pk_fma_f32 v[160:161], v[160:161], v[162:163], s[52:53] op_sel_hi:[1,1,0]
	s_nop 0
	v_pk_fma_f32 v[158:159], v[158:159], v[160:161], 0.5 op_sel_hi:[1,1,0]
	s_nop 0
	v_pk_mul_f32 v[170:171], v[156:157], v[158:159]
	v_pk_mul_f32 v[158:159], v[88:89], v[152:153] op_sel_hi:[1,0]
	v_pk_mul_f32 v[156:157], v[90:91], v[152:153] op_sel_hi:[1,0]
	v_med3_f32 v160, v158, -4.0, 4.0
	v_med3_f32 v161, v159, -4.0, 4.0
	v_pk_mul_f32 v[162:163], v[160:161], v[160:161]
	s_nop 0
	v_pk_fma_f32 v[162:163], v[162:163], s[72:73], -1.0 op_sel_hi:[1,0,0]
	s_nop 0
	v_pk_fma_f32 v[164:165], v[162:163], s[74:75], v[154:155] op_sel_hi:[1,0,0]
	s_nop 0
	v_pk_fma_f32 v[164:165], v[162:163], v[164:165], s[0:1] op_sel_hi:[1,1,0]
	s_nop 0
	v_pk_fma_f32 v[164:165], v[162:163], v[164:165], s[2:3] op_sel_hi:[1,1,0]
	s_nop 0
	v_pk_fma_f32 v[164:165], v[162:163], v[164:165], s[28:29] op_sel_hi:[1,1,0]
	s_nop 0
	v_pk_fma_f32 v[164:165], v[162:163], v[164:165], s[30:31] op_sel_hi:[1,1,0]
	s_nop 0
	v_pk_fma_f32 v[164:165], v[162:163], v[164:165], s[48:49] op_sel_hi:[1,1,0]
	s_nop 0
	v_pk_fma_f32 v[164:165], v[162:163], v[164:165], s[50:51] op_sel_hi:[1,1,0]
	s_nop 0
	v_pk_fma_f32 v[162:163], v[162:163], v[164:165], s[52:53] op_sel_hi:[1,1,0]
	s_nop 0
	v_pk_fma_f32 v[162:163], v[160:161], v[162:163], 0.5 op_sel_hi:[1,1,0]
	v_med3_f32 v160, v156, -4.0, 4.0
	v_med3_f32 v161, v157, -4.0, 4.0
	v_pk_mul_f32 v[164:165], v[160:161], v[160:161]
	v_pk_mul_f32 v[172:173], v[158:159], v[162:163]
	v_pk_fma_f32 v[164:165], v[164:165], s[72:73], -1.0 op_sel_hi:[1,0,0]
	v_pk_fma_f32 v[158:159], v[158:159], v[162:163], v[172:173] op_sel:[0,0,1] op_sel_hi:[1,1,0]
	v_pk_fma_f32 v[166:167], v[164:165], s[74:75], v[154:155] op_sel_hi:[1,0,0]
	s_nop 0
	v_pk_fma_f32 v[166:167], v[164:165], v[166:167], s[0:1] op_sel_hi:[1,1,0]
	s_nop 0
	v_pk_fma_f32 v[166:167], v[164:165], v[166:167], s[2:3] op_sel_hi:[1,1,0]
	s_nop 0
	v_pk_fma_f32 v[166:167], v[164:165], v[166:167], s[28:29] op_sel_hi:[1,1,0]
	s_nop 0
	v_pk_fma_f32 v[166:167], v[164:165], v[166:167], s[30:31] op_sel_hi:[1,1,0]
	s_nop 0
	v_pk_fma_f32 v[166:167], v[164:165], v[166:167], s[48:49] op_sel_hi:[1,1,0]
	s_nop 0
	v_pk_fma_f32 v[166:167], v[164:165], v[166:167], s[50:51] op_sel_hi:[1,1,0]
	s_nop 0
	v_pk_fma_f32 v[164:165], v[164:165], v[166:167], s[52:53] op_sel_hi:[1,1,0]
	v_mov_b32_e32 v166, v169
	v_mov_b32_e32 v167, v171
	v_pk_fma_f32 v[160:161], v[160:161], v[164:165], 0.5 op_sel_hi:[1,1,0]
	v_mov_b32_e32 v164, v168
	v_mov_b32_e32 v165, v170
	v_pk_mul_f32 v[162:163], v[166:167], v[166:167]
	v_pk_mul_f32 v[160:161], v[156:157], v[160:161]
	v_pk_fma_f32 v[162:163], v[164:165], v[164:165], v[162:163]
	v_cvt_pk_bf16_f32 v168, v168, v169
	v_pk_add_f32 v[162:163], v[162:163], v[162:163] op_sel_hi:[0,1]
	v_cvt_pk_bf16_f32 v169, v170, v171
	v_cvt_pk_bf16_f32 v170, v172, v173
	v_cvt_pk_bf16_f32 v171, v160, v161
	v_mul_f32_e32 v162, v172, v172
	global_store_dwordx4 v[150:151], v[168:171], off
	v_pk_add_f32 v[156:157], v[164:165], v[166:167]
	v_pk_fma_f32 v[164:165], v[172:173], v[172:173], v[162:163] op_sel_hi:[1,1,0]
	v_pk_mul_f32 v[168:169], v[92:93], v[152:153] op_sel_hi:[1,0]
	v_pk_mul_f32 v[170:171], v[94:95], v[152:153] op_sel_hi:[1,0]
	v_med3_f32 v172, v168, -4.0, 4.0
	v_med3_f32 v173, v169, -4.0, 4.0
	v_pk_mul_f32 v[180:181], v[172:173], v[172:173]
	v_pk_mul_f32 v[166:167], v[160:161], v[160:161]
	v_pk_fma_f32 v[180:181], v[180:181], s[72:73], -1.0 op_sel_hi:[1,0,0]
	v_pk_add_f32 v[156:157], v[156:157], v[156:157] op_sel:[0,1] op_sel_hi:[1,0]
	v_pk_fma_f32 v[182:183], v[180:181], s[74:75], v[154:155] op_sel_hi:[1,0,0]
	s_nop 0
	v_pk_fma_f32 v[182:183], v[180:181], v[182:183], s[0:1] op_sel_hi:[1,1,0]
	s_nop 0
	v_pk_fma_f32 v[182:183], v[180:181], v[182:183], s[2:3] op_sel_hi:[1,1,0]
	s_nop 0
	v_pk_fma_f32 v[182:183], v[180:181], v[182:183], s[28:29] op_sel_hi:[1,1,0]
	s_nop 0
	v_pk_fma_f32 v[182:183], v[180:181], v[182:183], s[30:31] op_sel_hi:[1,1,0]
	s_nop 0
	v_pk_fma_f32 v[182:183], v[180:181], v[182:183], s[48:49] op_sel_hi:[1,1,0]
	s_nop 0
	v_pk_fma_f32 v[182:183], v[180:181], v[182:183], s[50:51] op_sel_hi:[1,1,0]
	s_nop 0
	v_pk_fma_f32 v[180:181], v[180:181], v[182:183], s[52:53] op_sel_hi:[1,1,0]
	s_nop 0
	v_pk_fma_f32 v[172:173], v[172:173], v[180:181], 0.5 op_sel_hi:[1,1,0]
	s_nop 0
	v_pk_mul_f32 v[168:169], v[168:169], v[172:173]
	v_med3_f32 v172, v170, -4.0, 4.0
	v_med3_f32 v173, v171, -4.0, 4.0
	v_pk_mul_f32 v[180:181], v[172:173], v[172:173]
	s_nop 0
	v_pk_fma_f32 v[180:181], v[180:181], s[72:73], -1.0 op_sel_hi:[1,0,0]
	s_nop 0
	v_pk_fma_f32 v[182:183], v[180:181], s[74:75], v[154:155] op_sel_hi:[1,0,0]
	s_nop 0
	v_pk_fma_f32 v[182:183], v[180:181], v[182:183], s[0:1] op_sel_hi:[1,1,0]
	s_nop 0
	v_pk_fma_f32 v[182:183], v[180:181], v[182:183], s[2:3] op_sel_hi:[1,1,0]
	s_nop 0
	v_pk_fma_f32 v[182:183], v[180:181], v[182:183], s[28:29] op_sel_hi:[1,1,0]
	s_nop 0
	v_pk_fma_f32 v[182:183], v[180:181], v[182:183], s[30:31] op_sel_hi:[1,1,0]
	s_nop 0
	v_pk_fma_f32 v[182:183], v[180:181], v[182:183], s[48:49] op_sel_hi:[1,1,0]
	s_nop 0
	v_pk_fma_f32 v[182:183], v[180:181], v[182:183], s[50:51] op_sel_hi:[1,1,0]
	s_nop 0
	v_pk_fma_f32 v[180:181], v[180:181], v[182:183], s[52:53] op_sel_hi:[1,1,0]
	s_nop 0
	v_pk_fma_f32 v[172:173], v[172:173], v[180:181], 0.5 op_sel_hi:[1,1,0]
	s_nop 0
	v_pk_mul_f32 v[170:171], v[170:171], v[172:173]
	v_pk_mul_f32 v[172:173], v[86:87], v[152:153] op_sel_hi:[1,0]
	v_pk_mul_f32 v[152:153], v[84:85], v[152:153] op_sel_hi:[1,0]
	s_nop 0
	v_med3_f32 v180, v152, -4.0, 4.0
	v_med3_f32 v181, v153, -4.0, 4.0
	v_pk_mul_f32 v[182:183], v[180:181], v[180:181]
	s_nop 0
	v_pk_fma_f32 v[182:183], v[182:183], s[72:73], -1.0 op_sel_hi:[1,0,0]
	s_nop 0
	v_pk_fma_f32 v[184:185], v[182:183], s[74:75], v[154:155] op_sel_hi:[1,0,0]
	s_nop 0
	v_pk_fma_f32 v[184:185], v[182:183], v[184:185], s[0:1] op_sel_hi:[1,1,0]
	s_nop 0
	v_pk_fma_f32 v[184:185], v[182:183], v[184:185], s[2:3] op_sel_hi:[1,1,0]
	s_nop 0
	v_pk_fma_f32 v[184:185], v[182:183], v[184:185], s[28:29] op_sel_hi:[1,1,0]
	s_nop 0
	v_pk_fma_f32 v[184:185], v[182:183], v[184:185], s[30:31] op_sel_hi:[1,1,0]
	s_nop 0
	v_pk_fma_f32 v[184:185], v[182:183], v[184:185], s[48:49] op_sel_hi:[1,1,0]
	s_nop 0
	v_pk_fma_f32 v[184:185], v[182:183], v[184:185], s[50:51] op_sel_hi:[1,1,0]
	s_nop 0
	v_pk_fma_f32 v[182:183], v[182:183], v[184:185], s[52:53] op_sel_hi:[1,1,0]
	v_med3_f32 v184, v172, -4.0, 4.0
	v_med3_f32 v185, v173, -4.0, 4.0
	v_pk_mul_f32 v[186:187], v[184:185], v[184:185]
	v_pk_fma_f32 v[180:181], v[180:181], v[182:183], 0.5 op_sel_hi:[1,1,0]
	v_pk_fma_f32 v[186:187], v[186:187], s[72:73], -1.0 op_sel_hi:[1,0,0]
	v_pk_mul_f32 v[182:183], v[152:153], v[180:181]
	v_pk_fma_f32 v[154:155], v[186:187], s[74:75], v[154:155] op_sel_hi:[1,0,0]
	v_pk_fma_f32 v[180:181], v[152:153], v[180:181], v[182:183] op_sel:[0,0,1] op_sel_hi:[1,1,0]
	v_pk_fma_f32 v[154:155], v[186:187], v[154:155], s[0:1] op_sel_hi:[1,1,0]
	v_mul_f32_e32 v152, v168, v168
	v_pk_fma_f32 v[154:155], v[186:187], v[154:155], s[2:3] op_sel_hi:[1,1,0]
	v_pk_mul_f32 v[190:191], v[182:183], v[182:183]
	v_pk_fma_f32 v[154:155], v[186:187], v[154:155], s[28:29] op_sel_hi:[1,1,0]
	v_mov_b32_e32 v181, v166
	v_pk_fma_f32 v[154:155], v[186:187], v[154:155], s[30:31] op_sel_hi:[1,1,0]
	v_mov_b32_e32 v159, v190
	v_pk_fma_f32 v[154:155], v[186:187], v[154:155], s[48:49] op_sel_hi:[1,1,0]
	v_mov_b32_e32 v157, v191
	v_pk_fma_f32 v[154:155], v[186:187], v[154:155], s[50:51] op_sel_hi:[1,1,0]
	s_nop 0
	v_pk_fma_f32 v[154:155], v[186:187], v[154:155], s[52:53] op_sel_hi:[1,1,0]
	v_pk_fma_f32 v[186:187], v[168:169], v[168:169], v[152:153] op_sel_hi:[1,1,0]
	v_pk_fma_f32 v[154:155], v[184:185], v[154:155], 0.5 op_sel_hi:[1,1,0]
	v_mov_b32_e32 v184, v169
	v_pk_mul_f32 v[172:173], v[172:173], v[154:155]
	v_mov_b32_e32 v154, v168
	v_mov_b32_e32 v155, v170
	v_mov_b32_e32 v185, v171
	v_pk_add_f32 v[154:155], v[154:155], v[184:185]
	v_mul_f32_e32 v152, v170, v170
	v_pk_add_f32 v[184:185], v[154:155], v[154:155] op_sel:[0,1] op_sel_hi:[1,0]
	v_pk_fma_f32 v[188:189], v[170:171], v[170:171], v[152:153] op_sel_hi:[1,1,0]
	v_mul_f32_e32 v152, v172, v172
	v_pk_fma_f32 v[192:193], v[172:173], v[172:173], v[152:153] op_sel_hi:[1,1,0]
	v_cvt_pk_bf16_f32 v152, v168, v169
	v_cvt_pk_bf16_f32 v153, v170, v171
	v_cvt_pk_bf16_f32 v154, v182, v183
	v_cvt_pk_bf16_f32 v155, v172, v173
	v_mov_b32_e32 v185, v167
	v_mov_b32_e32 v164, v172
	v_mov_b32_e32 v162, v173
	global_store_dwordx4 v[150:151], v[152:155], off offset:256
	v_pk_add_f32 v[150:151], v[180:181], v[184:185]
	v_mov_b32_e32 v186, v160
	v_pk_add_f32 v[152:153], v[164:165], v[162:163]
	v_mov_b32_e32 v188, v161
	v_pk_add_f32 v[150:151], v[150:151], v[152:153]
	v_pk_add_f32 v[152:153], v[186:187], v[188:189]
	v_pk_add_f32 v[154:155], v[158:159], v[156:157]
	v_mov_b32_e32 v3, v193
	v_pk_add_f32 v[152:153], v[154:155], v[152:153]
	s_nop 0
	v_pk_add_f32 v[152:153], v[152:153], v[2:3]
	s_nop 0
	v_pk_add_f32 v[150:151], v[150:151], v[152:153]
	ds_bpermute_b32 v152, v179, v150
	ds_bpermute_b32 v153, v179, v151
	s_waitcnt lgkmcnt(0)
	v_pk_add_f32 v[150:151], v[150:151], v[152:153]
	ds_bpermute_b32 v152, v178, v150
	ds_bpermute_b32 v153, v178, v151
	s_and_saveexec_b64 s[0:1], s[4:5]
	s_cbranch_execz .LBB0_458
	v_lshlrev_b64 v[148:149], 8, v[148:149]
	v_lshl_add_u64 v[148:149], s[14:15], 0, v[148:149]
	s_waitcnt lgkmcnt(0)
	v_pk_add_f32 v[150:151], v[150:151], v[152:153]
	v_lshl_add_u64 v[148:149], s[94:95], 3, v[148:149]
	global_store_dwordx2 v[148:149], v[150:151], off
.LBB0_458:
	s_or_b64 exec, exec, s[0:1]
	v_or_b32_e32 v148, 48, v142
	v_ashrrev_i32_e32 v149, 31, v148
	v_lshl_add_u64 v[150:151], v[148:149], 2, s[16:17]
	s_waitcnt lgkmcnt(1)
	s_nop 1
	v_mov_b32_e32 v152, v203
	s_mov_b32 s0, 0xbb7be14b
	v_lshlrev_b64 v[150:151], 12, v[148:149]
	v_lshl_add_u64 v[150:151], s[12:13], 0, v[150:151]
	v_lshl_add_u64 v[150:151], v[150:151], 0, v[146:147]
	s_waitcnt lgkmcnt(0)
	v_pk_mul_f32 v[158:159], v[80:81], v[152:153] op_sel_hi:[1,0]
	s_nop 0
	v_med3_f32 v160, v158, -4.0, 4.0
	v_med3_f32 v161, v159, -4.0, 4.0
	v_pk_mul_f32 v[154:155], v[160:161], v[160:161]
	v_pk_mul_f32 v[156:157], v[82:83], v[152:153] op_sel_hi:[1,0]
	v_pk_fma_f32 v[162:163], v[154:155], s[72:73], -1.0 op_sel_hi:[1,0,0]
	v_mov_b64_e32 v[154:155], s[0:1]
	v_pk_fma_f32 v[164:165], v[162:163], s[74:75], v[154:155] op_sel_hi:[1,0,0]
	s_mov_b32 s0, 0x3bcff2a2
	v_pk_fma_f32 v[164:165], v[162:163], v[164:165], s[0:1] op_sel_hi:[1,1,0]
	s_nop 0
	v_pk_fma_f32 v[164:165], v[162:163], v[164:165], s[2:3] op_sel_hi:[1,1,0]
	s_nop 0
	v_pk_fma_f32 v[164:165], v[162:163], v[164:165], s[28:29] op_sel_hi:[1,1,0]
	s_nop 0
	v_pk_fma_f32 v[164:165], v[162:163], v[164:165], s[30:31] op_sel_hi:[1,1,0]
	s_nop 0
	v_pk_fma_f32 v[164:165], v[162:163], v[164:165], s[48:49] op_sel_hi:[1,1,0]
	s_nop 0
	v_pk_fma_f32 v[164:165], v[162:163], v[164:165], s[50:51] op_sel_hi:[1,1,0]
	s_nop 0
	v_pk_fma_f32 v[162:163], v[162:163], v[164:165], s[52:53] op_sel_hi:[1,1,0]
	s_nop 0
	v_pk_fma_f32 v[160:161], v[160:161], v[162:163], 0.5 op_sel_hi:[1,1,0]
	s_nop 0
	v_pk_mul_f32 v[168:169], v[158:159], v[160:161]
	v_med3_f32 v158, v156, -4.0, 4.0
	v_med3_f32 v159, v157, -4.0, 4.0
	v_pk_mul_f32 v[160:161], v[158:159], v[158:159]
	s_nop 0
	v_pk_fma_f32 v[160:161], v[160:161], s[72:73], -1.0 op_sel_hi:[1,0,0]
	s_nop 0
	v_pk_fma_f32 v[162:163], v[160:161], s[74:75], v[154:155] op_sel_hi:[1,0,0]
	s_nop 0
	v_pk_fma_f32 v[162:163], v[160:161], v[162:163], s[0:1] op_sel_hi:[1,1,0]
	s_nop 0
	v_pk_fma_f32 v[162:163], v[160:161], v[162:163], s[2:3] op_sel_hi:[1,1,0]
	s_nop 0
	v_pk_fma_f32 v[162:163], v[160:161], v[162:163], s[28:29] op_sel_hi:[1,1,0]
	s_nop 0
	v_pk_fma_f32 v[162:163], v[160:161], v[162:163], s[30:31] op_sel_hi:[1,1,0]
	s_nop 0
	v_pk_fma_f32 v[162:163], v[160:161], v[162:163], s[48:49] op_sel_hi:[1,1,0]
	s_nop 0
	v_pk_fma_f32 v[162:163], v[160:161], v[162:163], s[50:51] op_sel_hi:[1,1,0]
	s_nop 0
	v_pk_fma_f32 v[160:161], v[160:161], v[162:163], s[52:53] op_sel_hi:[1,1,0]
	s_nop 0
	v_pk_fma_f32 v[158:159], v[158:159], v[160:161], 0.5 op_sel_hi:[1,1,0]
	s_nop 0
	v_pk_mul_f32 v[170:171], v[156:157], v[158:159]
	v_pk_mul_f32 v[158:159], v[72:73], v[152:153] op_sel_hi:[1,0]
	v_pk_mul_f32 v[156:157], v[74:75], v[152:153] op_sel_hi:[1,0]
	v_med3_f32 v160, v158, -4.0, 4.0
	v_med3_f32 v161, v159, -4.0, 4.0
	v_pk_mul_f32 v[162:163], v[160:161], v[160:161]
	s_nop 0
	v_pk_fma_f32 v[162:163], v[162:163], s[72:73], -1.0 op_sel_hi:[1,0,0]
	s_nop 0
	v_pk_fma_f32 v[164:165], v[162:163], s[74:75], v[154:155] op_sel_hi:[1,0,0]
	s_nop 0
	v_pk_fma_f32 v[164:165], v[162:163], v[164:165], s[0:1] op_sel_hi:[1,1,0]
	s_nop 0
	v_pk_fma_f32 v[164:165], v[162:163], v[164:165], s[2:3] op_sel_hi:[1,1,0]
	s_nop 0
	v_pk_fma_f32 v[164:165], v[162:163], v[164:165], s[28:29] op_sel_hi:[1,1,0]
	s_nop 0
	v_pk_fma_f32 v[164:165], v[162:163], v[164:165], s[30:31] op_sel_hi:[1,1,0]
	s_nop 0
	v_pk_fma_f32 v[164:165], v[162:163], v[164:165], s[48:49] op_sel_hi:[1,1,0]
	s_nop 0
	v_pk_fma_f32 v[164:165], v[162:163], v[164:165], s[50:51] op_sel_hi:[1,1,0]
	s_nop 0
	v_pk_fma_f32 v[162:163], v[162:163], v[164:165], s[52:53] op_sel_hi:[1,1,0]
	s_nop 0
	v_pk_fma_f32 v[162:163], v[160:161], v[162:163], 0.5 op_sel_hi:[1,1,0]
	v_med3_f32 v160, v156, -4.0, 4.0
	v_med3_f32 v161, v157, -4.0, 4.0
	v_pk_mul_f32 v[164:165], v[160:161], v[160:161]
	v_pk_mul_f32 v[172:173], v[158:159], v[162:163]
	v_pk_fma_f32 v[164:165], v[164:165], s[72:73], -1.0 op_sel_hi:[1,0,0]
	v_pk_fma_f32 v[158:159], v[158:159], v[162:163], v[172:173] op_sel:[0,0,1] op_sel_hi:[1,1,0]
	v_pk_fma_f32 v[166:167], v[164:165], s[74:75], v[154:155] op_sel_hi:[1,0,0]
	s_nop 0
	v_pk_fma_f32 v[166:167], v[164:165], v[166:167], s[0:1] op_sel_hi:[1,1,0]
	s_nop 0
	v_pk_fma_f32 v[166:167], v[164:165], v[166:167], s[2:3] op_sel_hi:[1,1,0]
	s_nop 0
	v_pk_fma_f32 v[166:167], v[164:165], v[166:167], s[28:29] op_sel_hi:[1,1,0]
	s_nop 0
	v_pk_fma_f32 v[166:167], v[164:165], v[166:167], s[30:31] op_sel_hi:[1,1,0]
	s_nop 0
	v_pk_fma_f32 v[166:167], v[164:165], v[166:167], s[48:49] op_sel_hi:[1,1,0]
	s_nop 0
	v_pk_fma_f32 v[166:167], v[164:165], v[166:167], s[50:51] op_sel_hi:[1,1,0]
	s_nop 0
	v_pk_fma_f32 v[164:165], v[164:165], v[166:167], s[52:53] op_sel_hi:[1,1,0]
	v_mov_b32_e32 v166, v169
	v_mov_b32_e32 v167, v171
	v_pk_fma_f32 v[160:161], v[160:161], v[164:165], 0.5 op_sel_hi:[1,1,0]
	v_mov_b32_e32 v164, v168
	v_mov_b32_e32 v165, v170
	v_pk_mul_f32 v[162:163], v[166:167], v[166:167]
	v_pk_mul_f32 v[160:161], v[156:157], v[160:161]
	v_pk_fma_f32 v[162:163], v[164:165], v[164:165], v[162:163]
	v_cvt_pk_bf16_f32 v168, v168, v169
	v_pk_add_f32 v[162:163], v[162:163], v[162:163] op_sel_hi:[0,1]
	v_cvt_pk_bf16_f32 v169, v170, v171
	v_cvt_pk_bf16_f32 v170, v172, v173
	v_cvt_pk_bf16_f32 v171, v160, v161
	v_mul_f32_e32 v162, v172, v172
	global_store_dwordx4 v[150:151], v[168:171], off
	v_pk_add_f32 v[156:157], v[164:165], v[166:167]
	v_pk_fma_f32 v[164:165], v[172:173], v[172:173], v[162:163] op_sel_hi:[1,1,0]
	v_pk_mul_f32 v[168:169], v[76:77], v[152:153] op_sel_hi:[1,0]
	v_pk_mul_f32 v[170:171], v[78:79], v[152:153] op_sel_hi:[1,0]
	v_med3_f32 v172, v168, -4.0, 4.0
	v_med3_f32 v173, v169, -4.0, 4.0
	v_pk_mul_f32 v[180:181], v[172:173], v[172:173]
	v_pk_mul_f32 v[166:167], v[160:161], v[160:161]
	v_pk_fma_f32 v[180:181], v[180:181], s[72:73], -1.0 op_sel_hi:[1,0,0]
	v_pk_add_f32 v[156:157], v[156:157], v[156:157] op_sel:[0,1] op_sel_hi:[1,0]
	v_pk_fma_f32 v[182:183], v[180:181], s[74:75], v[154:155] op_sel_hi:[1,0,0]
	s_nop 0
	v_pk_fma_f32 v[182:183], v[180:181], v[182:183], s[0:1] op_sel_hi:[1,1,0]
	s_nop 0
	v_pk_fma_f32 v[182:183], v[180:181], v[182:183], s[2:3] op_sel_hi:[1,1,0]
	s_nop 0
	v_pk_fma_f32 v[182:183], v[180:181], v[182:183], s[28:29] op_sel_hi:[1,1,0]
	s_nop 0
	v_pk_fma_f32 v[182:183], v[180:181], v[182:183], s[30:31] op_sel_hi:[1,1,0]
	s_nop 0
	v_pk_fma_f32 v[182:183], v[180:181], v[182:183], s[48:49] op_sel_hi:[1,1,0]
	s_nop 0
	v_pk_fma_f32 v[182:183], v[180:181], v[182:183], s[50:51] op_sel_hi:[1,1,0]
	s_nop 0
	v_pk_fma_f32 v[180:181], v[180:181], v[182:183], s[52:53] op_sel_hi:[1,1,0]
	s_nop 0
	v_pk_fma_f32 v[172:173], v[172:173], v[180:181], 0.5 op_sel_hi:[1,1,0]
	s_nop 0
	v_pk_mul_f32 v[168:169], v[168:169], v[172:173]
	v_med3_f32 v172, v170, -4.0, 4.0
	v_med3_f32 v173, v171, -4.0, 4.0
	v_pk_mul_f32 v[180:181], v[172:173], v[172:173]
	s_nop 0
	v_pk_fma_f32 v[180:181], v[180:181], s[72:73], -1.0 op_sel_hi:[1,0,0]
	s_nop 0
	v_pk_fma_f32 v[182:183], v[180:181], s[74:75], v[154:155] op_sel_hi:[1,0,0]
	s_nop 0
	v_pk_fma_f32 v[182:183], v[180:181], v[182:183], s[0:1] op_sel_hi:[1,1,0]
	s_nop 0
	v_pk_fma_f32 v[182:183], v[180:181], v[182:183], s[2:3] op_sel_hi:[1,1,0]
	s_nop 0
	v_pk_fma_f32 v[182:183], v[180:181], v[182:183], s[28:29] op_sel_hi:[1,1,0]
	s_nop 0
	v_pk_fma_f32 v[182:183], v[180:181], v[182:183], s[30:31] op_sel_hi:[1,1,0]
	s_nop 0
	v_pk_fma_f32 v[182:183], v[180:181], v[182:183], s[48:49] op_sel_hi:[1,1,0]
	s_nop 0
	v_pk_fma_f32 v[182:183], v[180:181], v[182:183], s[50:51] op_sel_hi:[1,1,0]
	s_nop 0
	v_pk_fma_f32 v[180:181], v[180:181], v[182:183], s[52:53] op_sel_hi:[1,1,0]
	s_nop 0
	v_pk_fma_f32 v[172:173], v[172:173], v[180:181], 0.5 op_sel_hi:[1,1,0]
	s_nop 0
	v_pk_mul_f32 v[170:171], v[170:171], v[172:173]
	v_pk_mul_f32 v[172:173], v[70:71], v[152:153] op_sel_hi:[1,0]
	v_pk_mul_f32 v[152:153], v[68:69], v[152:153] op_sel_hi:[1,0]
	s_nop 0
	v_med3_f32 v180, v152, -4.0, 4.0
	v_med3_f32 v181, v153, -4.0, 4.0
	v_pk_mul_f32 v[182:183], v[180:181], v[180:181]
	s_nop 0
	v_pk_fma_f32 v[182:183], v[182:183], s[72:73], -1.0 op_sel_hi:[1,0,0]
	s_nop 0
	v_pk_fma_f32 v[184:185], v[182:183], s[74:75], v[154:155] op_sel_hi:[1,0,0]
	s_nop 0
	v_pk_fma_f32 v[184:185], v[182:183], v[184:185], s[0:1] op_sel_hi:[1,1,0]
	s_nop 0
	v_pk_fma_f32 v[184:185], v[182:183], v[184:185], s[2:3] op_sel_hi:[1,1,0]
	s_nop 0
	v_pk_fma_f32 v[184:185], v[182:183], v[184:185], s[28:29] op_sel_hi:[1,1,0]
	s_nop 0
	v_pk_fma_f32 v[184:185], v[182:183], v[184:185], s[30:31] op_sel_hi:[1,1,0]
	s_nop 0
	v_pk_fma_f32 v[184:185], v[182:183], v[184:185], s[48:49] op_sel_hi:[1,1,0]
	s_nop 0
	v_pk_fma_f32 v[184:185], v[182:183], v[184:185], s[50:51] op_sel_hi:[1,1,0]
	s_nop 0
	v_pk_fma_f32 v[182:183], v[182:183], v[184:185], s[52:53] op_sel_hi:[1,1,0]
	v_med3_f32 v184, v172, -4.0, 4.0
	v_med3_f32 v185, v173, -4.0, 4.0
	v_pk_mul_f32 v[186:187], v[184:185], v[184:185]
	v_pk_fma_f32 v[180:181], v[180:181], v[182:183], 0.5 op_sel_hi:[1,1,0]
	v_pk_fma_f32 v[186:187], v[186:187], s[72:73], -1.0 op_sel_hi:[1,0,0]
	v_pk_mul_f32 v[182:183], v[152:153], v[180:181]
	v_pk_fma_f32 v[154:155], v[186:187], s[74:75], v[154:155] op_sel_hi:[1,0,0]
	v_pk_fma_f32 v[180:181], v[152:153], v[180:181], v[182:183] op_sel:[0,0,1] op_sel_hi:[1,1,0]
	v_pk_fma_f32 v[154:155], v[186:187], v[154:155], s[0:1] op_sel_hi:[1,1,0]
	v_mul_f32_e32 v152, v168, v168
	v_pk_fma_f32 v[154:155], v[186:187], v[154:155], s[2:3] op_sel_hi:[1,1,0]
	v_pk_mul_f32 v[190:191], v[182:183], v[182:183]
	v_pk_fma_f32 v[154:155], v[186:187], v[154:155], s[28:29] op_sel_hi:[1,1,0]
	v_mov_b32_e32 v181, v166
	v_pk_fma_f32 v[154:155], v[186:187], v[154:155], s[30:31] op_sel_hi:[1,1,0]
	v_mov_b32_e32 v159, v190
	v_pk_fma_f32 v[154:155], v[186:187], v[154:155], s[48:49] op_sel_hi:[1,1,0]
	v_mov_b32_e32 v157, v191
	v_pk_fma_f32 v[154:155], v[186:187], v[154:155], s[50:51] op_sel_hi:[1,1,0]
	s_nop 0
	v_pk_fma_f32 v[154:155], v[186:187], v[154:155], s[52:53] op_sel_hi:[1,1,0]
	v_pk_fma_f32 v[186:187], v[168:169], v[168:169], v[152:153] op_sel_hi:[1,1,0]
	v_pk_fma_f32 v[154:155], v[184:185], v[154:155], 0.5 op_sel_hi:[1,1,0]
	v_mov_b32_e32 v184, v169
	v_pk_mul_f32 v[172:173], v[172:173], v[154:155]
	v_mov_b32_e32 v154, v168
	v_mov_b32_e32 v155, v170
	v_mov_b32_e32 v185, v171
	v_pk_add_f32 v[154:155], v[154:155], v[184:185]
	v_mul_f32_e32 v152, v170, v170
	v_pk_add_f32 v[184:185], v[154:155], v[154:155] op_sel:[0,1] op_sel_hi:[1,0]
	v_pk_fma_f32 v[188:189], v[170:171], v[170:171], v[152:153] op_sel_hi:[1,1,0]
	v_mul_f32_e32 v152, v172, v172
	v_pk_fma_f32 v[192:193], v[172:173], v[172:173], v[152:153] op_sel_hi:[1,1,0]
	v_cvt_pk_bf16_f32 v152, v168, v169
	v_cvt_pk_bf16_f32 v153, v170, v171
	v_cvt_pk_bf16_f32 v154, v182, v183
	v_cvt_pk_bf16_f32 v155, v172, v173
	v_mov_b32_e32 v185, v167
	v_mov_b32_e32 v164, v172
	v_mov_b32_e32 v162, v173
	global_store_dwordx4 v[150:151], v[152:155], off offset:256
	v_pk_add_f32 v[150:151], v[180:181], v[184:185]
	v_mov_b32_e32 v186, v160
	v_pk_add_f32 v[152:153], v[164:165], v[162:163]
	v_mov_b32_e32 v188, v161
	v_pk_add_f32 v[150:151], v[150:151], v[152:153]
	v_pk_add_f32 v[152:153], v[186:187], v[188:189]
	v_pk_add_f32 v[154:155], v[158:159], v[156:157]
	v_mov_b32_e32 v3, v193
	v_pk_add_f32 v[152:153], v[154:155], v[152:153]
	s_nop 0
	v_pk_add_f32 v[152:153], v[152:153], v[2:3]
	s_nop 0
	v_pk_add_f32 v[150:151], v[150:151], v[152:153]
	ds_bpermute_b32 v152, v179, v150
	ds_bpermute_b32 v153, v179, v151
	s_waitcnt lgkmcnt(0)
	v_pk_add_f32 v[150:151], v[150:151], v[152:153]
	ds_bpermute_b32 v152, v178, v150
	ds_bpermute_b32 v153, v178, v151
	s_and_saveexec_b64 s[0:1], s[4:5]
	s_cbranch_execz .LBB0_460
	v_lshlrev_b64 v[148:149], 8, v[148:149]
	v_lshl_add_u64 v[148:149], s[14:15], 0, v[148:149]
	s_waitcnt lgkmcnt(0)
	v_pk_add_f32 v[150:151], v[150:151], v[152:153]
	v_lshl_add_u64 v[148:149], s[94:95], 3, v[148:149]
	global_store_dwordx2 v[148:149], v[150:151], off
.LBB0_460:
	s_or_b64 exec, exec, s[0:1]
	s_waitcnt lgkmcnt(1)
	s_nop 1
	v_mov_b32_e32 v152, v204
	s_mov_b32 s0, 0xbb7be14b
	v_add_u32_e32 v148, 0x80, v142
	v_ashrrev_i32_e32 v149, 31, v148
	v_lshlrev_b64 v[150:151], 12, v[148:149]
	v_lshl_add_u64 v[150:151], s[12:13], 0, v[150:151]
	v_mov_b32_e32 v147, v2
	v_lshl_add_u64 v[150:151], v[150:151], 0, v[146:147]
	s_waitcnt lgkmcnt(0)
	v_pk_mul_f32 v[158:159], v[64:65], v[152:153] op_sel_hi:[1,0]
	s_nop 0
	v_med3_f32 v160, v158, -4.0, 4.0
	v_med3_f32 v161, v159, -4.0, 4.0
	v_pk_mul_f32 v[154:155], v[160:161], v[160:161]
	v_pk_mul_f32 v[156:157], v[66:67], v[152:153] op_sel_hi:[1,0]
	v_pk_fma_f32 v[162:163], v[154:155], s[72:73], -1.0 op_sel_hi:[1,0,0]
	v_mov_b64_e32 v[154:155], s[0:1]
	v_pk_fma_f32 v[164:165], v[162:163], s[74:75], v[154:155] op_sel_hi:[1,0,0]
	s_mov_b32 s0, 0x3bcff2a2
	v_pk_fma_f32 v[164:165], v[162:163], v[164:165], s[0:1] op_sel_hi:[1,1,0]
	s_nop 0
	v_pk_fma_f32 v[164:165], v[162:163], v[164:165], s[2:3] op_sel_hi:[1,1,0]
	s_nop 0
	v_pk_fma_f32 v[164:165], v[162:163], v[164:165], s[28:29] op_sel_hi:[1,1,0]
	s_nop 0
	v_pk_fma_f32 v[164:165], v[162:163], v[164:165], s[30:31] op_sel_hi:[1,1,0]
	s_nop 0
	v_pk_fma_f32 v[164:165], v[162:163], v[164:165], s[48:49] op_sel_hi:[1,1,0]
	s_nop 0
	v_pk_fma_f32 v[164:165], v[162:163], v[164:165], s[50:51] op_sel_hi:[1,1,0]
	s_nop 0
	v_pk_fma_f32 v[162:163], v[162:163], v[164:165], s[52:53] op_sel_hi:[1,1,0]
	s_nop 0
	v_pk_fma_f32 v[160:161], v[160:161], v[162:163], 0.5 op_sel_hi:[1,1,0]
	s_nop 0
	v_pk_mul_f32 v[168:169], v[158:159], v[160:161]
	v_med3_f32 v158, v156, -4.0, 4.0
	v_med3_f32 v159, v157, -4.0, 4.0
	v_pk_mul_f32 v[160:161], v[158:159], v[158:159]
	s_nop 0
	v_pk_fma_f32 v[160:161], v[160:161], s[72:73], -1.0 op_sel_hi:[1,0,0]
	s_nop 0
	v_pk_fma_f32 v[162:163], v[160:161], s[74:75], v[154:155] op_sel_hi:[1,0,0]
	s_nop 0
	v_pk_fma_f32 v[162:163], v[160:161], v[162:163], s[0:1] op_sel_hi:[1,1,0]
	s_nop 0
	v_pk_fma_f32 v[162:163], v[160:161], v[162:163], s[2:3] op_sel_hi:[1,1,0]
	s_nop 0
	v_pk_fma_f32 v[162:163], v[160:161], v[162:163], s[28:29] op_sel_hi:[1,1,0]
	s_nop 0
	v_pk_fma_f32 v[162:163], v[160:161], v[162:163], s[30:31] op_sel_hi:[1,1,0]
	s_nop 0
	v_pk_fma_f32 v[162:163], v[160:161], v[162:163], s[48:49] op_sel_hi:[1,1,0]
	s_nop 0
	v_pk_fma_f32 v[162:163], v[160:161], v[162:163], s[50:51] op_sel_hi:[1,1,0]
	s_nop 0
	v_pk_fma_f32 v[160:161], v[160:161], v[162:163], s[52:53] op_sel_hi:[1,1,0]
	s_nop 0
	v_pk_fma_f32 v[158:159], v[158:159], v[160:161], 0.5 op_sel_hi:[1,1,0]
	s_nop 0
	v_pk_mul_f32 v[170:171], v[156:157], v[158:159]
	v_pk_mul_f32 v[158:159], v[56:57], v[152:153] op_sel_hi:[1,0]
	v_pk_mul_f32 v[156:157], v[58:59], v[152:153] op_sel_hi:[1,0]
	v_med3_f32 v160, v158, -4.0, 4.0
	v_med3_f32 v161, v159, -4.0, 4.0
	v_pk_mul_f32 v[162:163], v[160:161], v[160:161]
	s_nop 0
	v_pk_fma_f32 v[162:163], v[162:163], s[72:73], -1.0 op_sel_hi:[1,0,0]
	s_nop 0
	v_pk_fma_f32 v[164:165], v[162:163], s[74:75], v[154:155] op_sel_hi:[1,0,0]
	s_nop 0
	v_pk_fma_f32 v[164:165], v[162:163], v[164:165], s[0:1] op_sel_hi:[1,1,0]
	s_nop 0
	v_pk_fma_f32 v[164:165], v[162:163], v[164:165], s[2:3] op_sel_hi:[1,1,0]
	s_nop 0
	v_pk_fma_f32 v[164:165], v[162:163], v[164:165], s[28:29] op_sel_hi:[1,1,0]
	s_nop 0
	v_pk_fma_f32 v[164:165], v[162:163], v[164:165], s[30:31] op_sel_hi:[1,1,0]
	s_nop 0
	v_pk_fma_f32 v[164:165], v[162:163], v[164:165], s[48:49] op_sel_hi:[1,1,0]
	s_nop 0
	v_pk_fma_f32 v[164:165], v[162:163], v[164:165], s[50:51] op_sel_hi:[1,1,0]
	s_nop 0
	v_pk_fma_f32 v[162:163], v[162:163], v[164:165], s[52:53] op_sel_hi:[1,1,0]
	s_nop 0
	v_pk_fma_f32 v[162:163], v[160:161], v[162:163], 0.5 op_sel_hi:[1,1,0]
	v_med3_f32 v160, v156, -4.0, 4.0
	v_med3_f32 v161, v157, -4.0, 4.0
	v_pk_mul_f32 v[164:165], v[160:161], v[160:161]
	v_pk_mul_f32 v[172:173], v[158:159], v[162:163]
	v_pk_fma_f32 v[164:165], v[164:165], s[72:73], -1.0 op_sel_hi:[1,0,0]
	v_pk_fma_f32 v[158:159], v[158:159], v[162:163], v[172:173] op_sel:[0,0,1] op_sel_hi:[1,1,0]
	v_pk_fma_f32 v[166:167], v[164:165], s[74:75], v[154:155] op_sel_hi:[1,0,0]
	s_nop 0
	v_pk_fma_f32 v[166:167], v[164:165], v[166:167], s[0:1] op_sel_hi:[1,1,0]
	s_nop 0
	v_pk_fma_f32 v[166:167], v[164:165], v[166:167], s[2:3] op_sel_hi:[1,1,0]
	s_nop 0
	v_pk_fma_f32 v[166:167], v[164:165], v[166:167], s[28:29] op_sel_hi:[1,1,0]
	s_nop 0
	v_pk_fma_f32 v[166:167], v[164:165], v[166:167], s[30:31] op_sel_hi:[1,1,0]
	s_nop 0
	v_pk_fma_f32 v[166:167], v[164:165], v[166:167], s[48:49] op_sel_hi:[1,1,0]
	s_nop 0
	v_pk_fma_f32 v[166:167], v[164:165], v[166:167], s[50:51] op_sel_hi:[1,1,0]
	s_nop 0
	v_pk_fma_f32 v[164:165], v[164:165], v[166:167], s[52:53] op_sel_hi:[1,1,0]
	v_mov_b32_e32 v166, v169
	v_mov_b32_e32 v167, v171
	v_pk_fma_f32 v[160:161], v[160:161], v[164:165], 0.5 op_sel_hi:[1,1,0]
	v_mov_b32_e32 v164, v168
	v_mov_b32_e32 v165, v170
	v_pk_mul_f32 v[162:163], v[166:167], v[166:167]
	v_pk_mul_f32 v[160:161], v[156:157], v[160:161]
	v_pk_fma_f32 v[162:163], v[164:165], v[164:165], v[162:163]
	v_cvt_pk_bf16_f32 v168, v168, v169
	v_pk_add_f32 v[162:163], v[162:163], v[162:163] op_sel_hi:[0,1]
	v_cvt_pk_bf16_f32 v169, v170, v171
	v_cvt_pk_bf16_f32 v170, v172, v173
	v_cvt_pk_bf16_f32 v171, v160, v161
	v_mul_f32_e32 v162, v172, v172
	global_store_dwordx4 v[150:151], v[168:171], off
	v_pk_add_f32 v[156:157], v[164:165], v[166:167]
	v_pk_fma_f32 v[164:165], v[172:173], v[172:173], v[162:163] op_sel_hi:[1,1,0]
	v_pk_mul_f32 v[170:171], v[60:61], v[152:153] op_sel_hi:[1,0]
	v_pk_mul_f32 v[168:169], v[62:63], v[152:153] op_sel_hi:[1,0]
	v_med3_f32 v172, v170, -4.0, 4.0
	v_med3_f32 v173, v171, -4.0, 4.0
	v_pk_mul_f32 v[180:181], v[172:173], v[172:173]
	v_pk_mul_f32 v[166:167], v[160:161], v[160:161]
	v_pk_fma_f32 v[180:181], v[180:181], s[72:73], -1.0 op_sel_hi:[1,0,0]
	v_pk_add_f32 v[156:157], v[156:157], v[156:157] op_sel:[0,1] op_sel_hi:[1,0]
	v_pk_fma_f32 v[182:183], v[180:181], s[74:75], v[154:155] op_sel_hi:[1,0,0]
	s_nop 0
	v_pk_fma_f32 v[182:183], v[180:181], v[182:183], s[0:1] op_sel_hi:[1,1,0]
	s_nop 0
	v_pk_fma_f32 v[182:183], v[180:181], v[182:183], s[2:3] op_sel_hi:[1,1,0]
	s_nop 0
	v_pk_fma_f32 v[182:183], v[180:181], v[182:183], s[28:29] op_sel_hi:[1,1,0]
	s_nop 0
	v_pk_fma_f32 v[182:183], v[180:181], v[182:183], s[30:31] op_sel_hi:[1,1,0]
	s_nop 0
	v_pk_fma_f32 v[182:183], v[180:181], v[182:183], s[48:49] op_sel_hi:[1,1,0]
	s_nop 0
	v_pk_fma_f32 v[182:183], v[180:181], v[182:183], s[50:51] op_sel_hi:[1,1,0]
	s_nop 0
	v_pk_fma_f32 v[180:181], v[180:181], v[182:183], s[52:53] op_sel_hi:[1,1,0]
	s_nop 0
	v_pk_fma_f32 v[172:173], v[172:173], v[180:181], 0.5 op_sel_hi:[1,1,0]
	s_nop 0
	v_pk_mul_f32 v[170:171], v[170:171], v[172:173]
	v_med3_f32 v172, v168, -4.0, 4.0
	v_med3_f32 v173, v169, -4.0, 4.0
	v_pk_mul_f32 v[180:181], v[172:173], v[172:173]
	s_nop 0
	v_pk_fma_f32 v[180:181], v[180:181], s[72:73], -1.0 op_sel_hi:[1,0,0]
	s_nop 0
	v_pk_fma_f32 v[182:183], v[180:181], s[74:75], v[154:155] op_sel_hi:[1,0,0]
	s_nop 0
	v_pk_fma_f32 v[182:183], v[180:181], v[182:183], s[0:1] op_sel_hi:[1,1,0]
	s_nop 0
	v_pk_fma_f32 v[182:183], v[180:181], v[182:183], s[2:3] op_sel_hi:[1,1,0]
	s_nop 0
	v_pk_fma_f32 v[182:183], v[180:181], v[182:183], s[28:29] op_sel_hi:[1,1,0]
	s_nop 0
	v_pk_fma_f32 v[182:183], v[180:181], v[182:183], s[30:31] op_sel_hi:[1,1,0]
	s_nop 0
	v_pk_fma_f32 v[182:183], v[180:181], v[182:183], s[48:49] op_sel_hi:[1,1,0]
	s_nop 0
	v_pk_fma_f32 v[182:183], v[180:181], v[182:183], s[50:51] op_sel_hi:[1,1,0]
	s_nop 0
	v_pk_fma_f32 v[180:181], v[180:181], v[182:183], s[52:53] op_sel_hi:[1,1,0]
	s_nop 0
	v_pk_fma_f32 v[172:173], v[172:173], v[180:181], 0.5 op_sel_hi:[1,1,0]
	s_nop 0
	v_pk_mul_f32 v[168:169], v[168:169], v[172:173]
	v_pk_mul_f32 v[172:173], v[54:55], v[152:153] op_sel_hi:[1,0]
	v_pk_mul_f32 v[152:153], v[52:53], v[152:153] op_sel_hi:[1,0]
	s_nop 0
	v_med3_f32 v180, v152, -4.0, 4.0
	v_med3_f32 v181, v153, -4.0, 4.0
	v_pk_mul_f32 v[182:183], v[180:181], v[180:181]
	s_nop 0
	v_pk_fma_f32 v[182:183], v[182:183], s[72:73], -1.0 op_sel_hi:[1,0,0]
	s_nop 0
	v_pk_fma_f32 v[184:185], v[182:183], s[74:75], v[154:155] op_sel_hi:[1,0,0]
	s_nop 0
	v_pk_fma_f32 v[184:185], v[182:183], v[184:185], s[0:1] op_sel_hi:[1,1,0]
	s_nop 0
	v_pk_fma_f32 v[184:185], v[182:183], v[184:185], s[2:3] op_sel_hi:[1,1,0]
	s_nop 0
	v_pk_fma_f32 v[184:185], v[182:183], v[184:185], s[28:29] op_sel_hi:[1,1,0]
	s_nop 0
	v_pk_fma_f32 v[184:185], v[182:183], v[184:185], s[30:31] op_sel_hi:[1,1,0]
	s_nop 0
	v_pk_fma_f32 v[184:185], v[182:183], v[184:185], s[48:49] op_sel_hi:[1,1,0]
	s_nop 0
	v_pk_fma_f32 v[184:185], v[182:183], v[184:185], s[50:51] op_sel_hi:[1,1,0]
	s_nop 0
	v_pk_fma_f32 v[182:183], v[182:183], v[184:185], s[52:53] op_sel_hi:[1,1,0]
	v_med3_f32 v184, v172, -4.0, 4.0
	v_med3_f32 v185, v173, -4.0, 4.0
	v_pk_mul_f32 v[186:187], v[184:185], v[184:185]
	v_pk_fma_f32 v[180:181], v[180:181], v[182:183], 0.5 op_sel_hi:[1,1,0]
	v_pk_fma_f32 v[186:187], v[186:187], s[72:73], -1.0 op_sel_hi:[1,0,0]
	v_pk_mul_f32 v[182:183], v[152:153], v[180:181]
	v_pk_fma_f32 v[154:155], v[186:187], s[74:75], v[154:155] op_sel_hi:[1,0,0]
	v_pk_fma_f32 v[180:181], v[152:153], v[180:181], v[182:183] op_sel:[0,0,1] op_sel_hi:[1,1,0]
	v_pk_fma_f32 v[154:155], v[186:187], v[154:155], s[0:1] op_sel_hi:[1,1,0]
	v_mul_f32_e32 v152, v170, v170
	v_pk_fma_f32 v[154:155], v[186:187], v[154:155], s[2:3] op_sel_hi:[1,1,0]
	v_pk_mul_f32 v[190:191], v[182:183], v[182:183]
	v_pk_fma_f32 v[154:155], v[186:187], v[154:155], s[28:29] op_sel_hi:[1,1,0]
	v_mov_b32_e32 v181, v166
	v_pk_fma_f32 v[154:155], v[186:187], v[154:155], s[30:31] op_sel_hi:[1,1,0]
	v_mov_b32_e32 v159, v190
	v_pk_fma_f32 v[154:155], v[186:187], v[154:155], s[48:49] op_sel_hi:[1,1,0]
	v_mov_b32_e32 v157, v191
	v_pk_fma_f32 v[154:155], v[186:187], v[154:155], s[50:51] op_sel_hi:[1,1,0]
	s_nop 0
	v_pk_fma_f32 v[154:155], v[186:187], v[154:155], s[52:53] op_sel_hi:[1,1,0]
	v_pk_fma_f32 v[186:187], v[170:171], v[170:171], v[152:153] op_sel_hi:[1,1,0]
	v_pk_fma_f32 v[154:155], v[184:185], v[154:155], 0.5 op_sel_hi:[1,1,0]
	v_mov_b32_e32 v184, v171
	v_pk_mul_f32 v[172:173], v[172:173], v[154:155]
	v_mov_b32_e32 v154, v170
	v_mov_b32_e32 v155, v168
	v_mov_b32_e32 v185, v169
	v_pk_add_f32 v[154:155], v[154:155], v[184:185]
	v_mul_f32_e32 v152, v168, v168
	v_pk_add_f32 v[184:185], v[154:155], v[154:155] op_sel:[0,1] op_sel_hi:[1,0]
	v_pk_fma_f32 v[188:189], v[168:169], v[168:169], v[152:153] op_sel_hi:[1,1,0]
	v_mul_f32_e32 v152, v172, v172
	v_pk_fma_f32 v[192:193], v[172:173], v[172:173], v[152:153] op_sel_hi:[1,1,0]
	v_cvt_pk_bf16_f32 v152, v170, v171
	v_cvt_pk_bf16_f32 v153, v168, v169
	v_cvt_pk_bf16_f32 v154, v182, v183
	v_cvt_pk_bf16_f32 v155, v172, v173
	v_mov_b32_e32 v185, v167
	v_mov_b32_e32 v164, v172
	v_mov_b32_e32 v162, v173
	global_store_dwordx4 v[150:151], v[152:155], off offset:256
	v_pk_add_f32 v[150:151], v[180:181], v[184:185]
	v_mov_b32_e32 v186, v160
	v_pk_add_f32 v[152:153], v[164:165], v[162:163]
	v_mov_b32_e32 v188, v161
	v_pk_add_f32 v[150:151], v[150:151], v[152:153]
	v_pk_add_f32 v[152:153], v[186:187], v[188:189]
	v_pk_add_f32 v[154:155], v[158:159], v[156:157]
	v_mov_b32_e32 v3, v193
	v_pk_add_f32 v[152:153], v[154:155], v[152:153]
	s_nop 0
	v_pk_add_f32 v[152:153], v[152:153], v[2:3]
	s_nop 0
	v_pk_add_f32 v[150:151], v[150:151], v[152:153]
	ds_bpermute_b32 v152, v179, v150
	ds_bpermute_b32 v153, v179, v151
	s_waitcnt lgkmcnt(0)
	v_pk_add_f32 v[150:151], v[150:151], v[152:153]
	ds_bpermute_b32 v152, v178, v150
	ds_bpermute_b32 v153, v178, v151
	s_and_saveexec_b64 s[0:1], s[4:5]
	s_cbranch_execz .LBB0_462
	v_lshlrev_b64 v[148:149], 8, v[148:149]
	v_lshl_add_u64 v[148:149], s[14:15], 0, v[148:149]
	s_waitcnt lgkmcnt(0)
	v_pk_add_f32 v[150:151], v[150:151], v[152:153]
	v_lshl_add_u64 v[148:149], s[94:95], 3, v[148:149]
	global_store_dwordx2 v[148:149], v[150:151], off
.LBB0_462:
	s_or_b64 exec, exec, s[0:1]
	s_waitcnt lgkmcnt(1)
	s_nop 1
	v_mov_b32_e32 v152, v205
	s_mov_b32 s0, 0xbb7be14b
	v_add_u32_e32 v148, 0x90, v142
	v_ashrrev_i32_e32 v149, 31, v148
	v_lshlrev_b64 v[150:151], 12, v[148:149]
	v_lshl_add_u64 v[150:151], s[12:13], 0, v[150:151]
	v_lshl_add_u64 v[150:151], v[150:151], 0, v[146:147]
	s_waitcnt lgkmcnt(0)
	v_pk_mul_f32 v[158:159], v[48:49], v[152:153] op_sel_hi:[1,0]
	s_nop 0
	v_med3_f32 v160, v158, -4.0, 4.0
	v_med3_f32 v161, v159, -4.0, 4.0
	v_pk_mul_f32 v[154:155], v[160:161], v[160:161]
	v_pk_mul_f32 v[156:157], v[50:51], v[152:153] op_sel_hi:[1,0]
	v_pk_fma_f32 v[162:163], v[154:155], s[72:73], -1.0 op_sel_hi:[1,0,0]
	v_mov_b64_e32 v[154:155], s[0:1]
	v_pk_fma_f32 v[164:165], v[162:163], s[74:75], v[154:155] op_sel_hi:[1,0,0]
	s_mov_b32 s0, 0x3bcff2a2
	v_pk_fma_f32 v[164:165], v[162:163], v[164:165], s[0:1] op_sel_hi:[1,1,0]
	s_nop 0
	v_pk_fma_f32 v[164:165], v[162:163], v[164:165], s[2:3] op_sel_hi:[1,1,0]
	s_nop 0
	v_pk_fma_f32 v[164:165], v[162:163], v[164:165], s[28:29] op_sel_hi:[1,1,0]
	s_nop 0
	v_pk_fma_f32 v[164:165], v[162:163], v[164:165], s[30:31] op_sel_hi:[1,1,0]
	s_nop 0
	v_pk_fma_f32 v[164:165], v[162:163], v[164:165], s[48:49] op_sel_hi:[1,1,0]
	s_nop 0
	v_pk_fma_f32 v[164:165], v[162:163], v[164:165], s[50:51] op_sel_hi:[1,1,0]
	s_nop 0
	v_pk_fma_f32 v[162:163], v[162:163], v[164:165], s[52:53] op_sel_hi:[1,1,0]
	s_nop 0
	v_pk_fma_f32 v[160:161], v[160:161], v[162:163], 0.5 op_sel_hi:[1,1,0]
	s_nop 0
	v_pk_mul_f32 v[168:169], v[158:159], v[160:161]
	v_med3_f32 v158, v156, -4.0, 4.0
	v_med3_f32 v159, v157, -4.0, 4.0
	v_pk_mul_f32 v[160:161], v[158:159], v[158:159]
	s_nop 0
	v_pk_fma_f32 v[160:161], v[160:161], s[72:73], -1.0 op_sel_hi:[1,0,0]
	s_nop 0
	v_pk_fma_f32 v[162:163], v[160:161], s[74:75], v[154:155] op_sel_hi:[1,0,0]
	s_nop 0
	v_pk_fma_f32 v[162:163], v[160:161], v[162:163], s[0:1] op_sel_hi:[1,1,0]
	s_nop 0
	v_pk_fma_f32 v[162:163], v[160:161], v[162:163], s[2:3] op_sel_hi:[1,1,0]
	s_nop 0
	v_pk_fma_f32 v[162:163], v[160:161], v[162:163], s[28:29] op_sel_hi:[1,1,0]
	s_nop 0
	v_pk_fma_f32 v[162:163], v[160:161], v[162:163], s[30:31] op_sel_hi:[1,1,0]
	s_nop 0
	v_pk_fma_f32 v[162:163], v[160:161], v[162:163], s[48:49] op_sel_hi:[1,1,0]
	s_nop 0
	v_pk_fma_f32 v[162:163], v[160:161], v[162:163], s[50:51] op_sel_hi:[1,1,0]
	s_nop 0
	v_pk_fma_f32 v[160:161], v[160:161], v[162:163], s[52:53] op_sel_hi:[1,1,0]
	s_nop 0
	v_pk_fma_f32 v[158:159], v[158:159], v[160:161], 0.5 op_sel_hi:[1,1,0]
	s_nop 0
	v_pk_mul_f32 v[170:171], v[156:157], v[158:159]
	v_pk_mul_f32 v[158:159], v[40:41], v[152:153] op_sel_hi:[1,0]
	v_pk_mul_f32 v[156:157], v[42:43], v[152:153] op_sel_hi:[1,0]
	v_med3_f32 v160, v158, -4.0, 4.0
	v_med3_f32 v161, v159, -4.0, 4.0
	v_pk_mul_f32 v[162:163], v[160:161], v[160:161]
	s_nop 0
	v_pk_fma_f32 v[162:163], v[162:163], s[72:73], -1.0 op_sel_hi:[1,0,0]
	s_nop 0
	v_pk_fma_f32 v[164:165], v[162:163], s[74:75], v[154:155] op_sel_hi:[1,0,0]
	s_nop 0
	v_pk_fma_f32 v[164:165], v[162:163], v[164:165], s[0:1] op_sel_hi:[1,1,0]
	s_nop 0
	v_pk_fma_f32 v[164:165], v[162:163], v[164:165], s[2:3] op_sel_hi:[1,1,0]
	s_nop 0
	v_pk_fma_f32 v[164:165], v[162:163], v[164:165], s[28:29] op_sel_hi:[1,1,0]
	s_nop 0
	v_pk_fma_f32 v[164:165], v[162:163], v[164:165], s[30:31] op_sel_hi:[1,1,0]
	s_nop 0
	v_pk_fma_f32 v[164:165], v[162:163], v[164:165], s[48:49] op_sel_hi:[1,1,0]
	s_nop 0
	v_pk_fma_f32 v[164:165], v[162:163], v[164:165], s[50:51] op_sel_hi:[1,1,0]
	s_nop 0
	v_pk_fma_f32 v[162:163], v[162:163], v[164:165], s[52:53] op_sel_hi:[1,1,0]
	s_nop 0
	v_pk_fma_f32 v[162:163], v[160:161], v[162:163], 0.5 op_sel_hi:[1,1,0]
	v_med3_f32 v160, v156, -4.0, 4.0
	v_med3_f32 v161, v157, -4.0, 4.0
	v_pk_mul_f32 v[164:165], v[160:161], v[160:161]
	v_pk_mul_f32 v[172:173], v[158:159], v[162:163]
	v_pk_fma_f32 v[164:165], v[164:165], s[72:73], -1.0 op_sel_hi:[1,0,0]
	v_pk_fma_f32 v[158:159], v[158:159], v[162:163], v[172:173] op_sel:[0,0,1] op_sel_hi:[1,1,0]
	v_pk_fma_f32 v[166:167], v[164:165], s[74:75], v[154:155] op_sel_hi:[1,0,0]
	s_nop 0
	v_pk_fma_f32 v[166:167], v[164:165], v[166:167], s[0:1] op_sel_hi:[1,1,0]
	s_nop 0
	v_pk_fma_f32 v[166:167], v[164:165], v[166:167], s[2:3] op_sel_hi:[1,1,0]
	s_nop 0
	v_pk_fma_f32 v[166:167], v[164:165], v[166:167], s[28:29] op_sel_hi:[1,1,0]
	s_nop 0
	v_pk_fma_f32 v[166:167], v[164:165], v[166:167], s[30:31] op_sel_hi:[1,1,0]
	s_nop 0
	v_pk_fma_f32 v[166:167], v[164:165], v[166:167], s[48:49] op_sel_hi:[1,1,0]
	s_nop 0
	v_pk_fma_f32 v[166:167], v[164:165], v[166:167], s[50:51] op_sel_hi:[1,1,0]
	s_nop 0
	v_pk_fma_f32 v[164:165], v[164:165], v[166:167], s[52:53] op_sel_hi:[1,1,0]
	v_mov_b32_e32 v166, v169
	v_mov_b32_e32 v167, v171
	v_pk_fma_f32 v[160:161], v[160:161], v[164:165], 0.5 op_sel_hi:[1,1,0]
	v_mov_b32_e32 v164, v168
	v_mov_b32_e32 v165, v170
	v_pk_mul_f32 v[162:163], v[166:167], v[166:167]
	v_pk_mul_f32 v[160:161], v[156:157], v[160:161]
	v_pk_fma_f32 v[162:163], v[164:165], v[164:165], v[162:163]
	v_cvt_pk_bf16_f32 v168, v168, v169
	v_pk_add_f32 v[162:163], v[162:163], v[162:163] op_sel_hi:[0,1]
	v_cvt_pk_bf16_f32 v169, v170, v171
	v_cvt_pk_bf16_f32 v170, v172, v173
	v_cvt_pk_bf16_f32 v171, v160, v161
	v_mul_f32_e32 v162, v172, v172
	global_store_dwordx4 v[150:151], v[168:171], off
	v_pk_add_f32 v[156:157], v[164:165], v[166:167]
	v_pk_fma_f32 v[164:165], v[172:173], v[172:173], v[162:163] op_sel_hi:[1,1,0]
	v_pk_mul_f32 v[170:171], v[44:45], v[152:153] op_sel_hi:[1,0]
	v_pk_mul_f32 v[168:169], v[46:47], v[152:153] op_sel_hi:[1,0]
	v_med3_f32 v172, v170, -4.0, 4.0
	v_med3_f32 v173, v171, -4.0, 4.0
	v_pk_mul_f32 v[180:181], v[172:173], v[172:173]
	v_pk_mul_f32 v[166:167], v[160:161], v[160:161]
	v_pk_fma_f32 v[180:181], v[180:181], s[72:73], -1.0 op_sel_hi:[1,0,0]
	v_pk_add_f32 v[156:157], v[156:157], v[156:157] op_sel:[0,1] op_sel_hi:[1,0]
	v_pk_fma_f32 v[182:183], v[180:181], s[74:75], v[154:155] op_sel_hi:[1,0,0]
	s_nop 0
	v_pk_fma_f32 v[182:183], v[180:181], v[182:183], s[0:1] op_sel_hi:[1,1,0]
	s_nop 0
	v_pk_fma_f32 v[182:183], v[180:181], v[182:183], s[2:3] op_sel_hi:[1,1,0]
	s_nop 0
	v_pk_fma_f32 v[182:183], v[180:181], v[182:183], s[28:29] op_sel_hi:[1,1,0]
	s_nop 0
	v_pk_fma_f32 v[182:183], v[180:181], v[182:183], s[30:31] op_sel_hi:[1,1,0]
	s_nop 0
	v_pk_fma_f32 v[182:183], v[180:181], v[182:183], s[48:49] op_sel_hi:[1,1,0]
	s_nop 0
	v_pk_fma_f32 v[182:183], v[180:181], v[182:183], s[50:51] op_sel_hi:[1,1,0]
	s_nop 0
	v_pk_fma_f32 v[180:181], v[180:181], v[182:183], s[52:53] op_sel_hi:[1,1,0]
	s_nop 0
	v_pk_fma_f32 v[172:173], v[172:173], v[180:181], 0.5 op_sel_hi:[1,1,0]
	s_nop 0
	v_pk_mul_f32 v[170:171], v[170:171], v[172:173]
	v_med3_f32 v172, v168, -4.0, 4.0
	v_med3_f32 v173, v169, -4.0, 4.0
	v_pk_mul_f32 v[180:181], v[172:173], v[172:173]
	s_nop 0
	v_pk_fma_f32 v[180:181], v[180:181], s[72:73], -1.0 op_sel_hi:[1,0,0]
	s_nop 0
	v_pk_fma_f32 v[182:183], v[180:181], s[74:75], v[154:155] op_sel_hi:[1,0,0]
	s_nop 0
	v_pk_fma_f32 v[182:183], v[180:181], v[182:183], s[0:1] op_sel_hi:[1,1,0]
	s_nop 0
	v_pk_fma_f32 v[182:183], v[180:181], v[182:183], s[2:3] op_sel_hi:[1,1,0]
	s_nop 0
	v_pk_fma_f32 v[182:183], v[180:181], v[182:183], s[28:29] op_sel_hi:[1,1,0]
	s_nop 0
	v_pk_fma_f32 v[182:183], v[180:181], v[182:183], s[30:31] op_sel_hi:[1,1,0]
	s_nop 0
	v_pk_fma_f32 v[182:183], v[180:181], v[182:183], s[48:49] op_sel_hi:[1,1,0]
	s_nop 0
	v_pk_fma_f32 v[182:183], v[180:181], v[182:183], s[50:51] op_sel_hi:[1,1,0]
	s_nop 0
	v_pk_fma_f32 v[180:181], v[180:181], v[182:183], s[52:53] op_sel_hi:[1,1,0]
	s_nop 0
	v_pk_fma_f32 v[172:173], v[172:173], v[180:181], 0.5 op_sel_hi:[1,1,0]
	s_nop 0
	v_pk_mul_f32 v[168:169], v[168:169], v[172:173]
	v_pk_mul_f32 v[172:173], v[38:39], v[152:153] op_sel_hi:[1,0]
	v_pk_mul_f32 v[152:153], v[36:37], v[152:153] op_sel_hi:[1,0]
	s_nop 0
	v_med3_f32 v180, v152, -4.0, 4.0
	v_med3_f32 v181, v153, -4.0, 4.0
	v_pk_mul_f32 v[182:183], v[180:181], v[180:181]
	s_nop 0
	v_pk_fma_f32 v[182:183], v[182:183], s[72:73], -1.0 op_sel_hi:[1,0,0]
	s_nop 0
	v_pk_fma_f32 v[184:185], v[182:183], s[74:75], v[154:155] op_sel_hi:[1,0,0]
	s_nop 0
	v_pk_fma_f32 v[184:185], v[182:183], v[184:185], s[0:1] op_sel_hi:[1,1,0]
	s_nop 0
	v_pk_fma_f32 v[184:185], v[182:183], v[184:185], s[2:3] op_sel_hi:[1,1,0]
	s_nop 0
	v_pk_fma_f32 v[184:185], v[182:183], v[184:185], s[28:29] op_sel_hi:[1,1,0]
	s_nop 0
	v_pk_fma_f32 v[184:185], v[182:183], v[184:185], s[30:31] op_sel_hi:[1,1,0]
	s_nop 0
	v_pk_fma_f32 v[184:185], v[182:183], v[184:185], s[48:49] op_sel_hi:[1,1,0]
	s_nop 0
	v_pk_fma_f32 v[184:185], v[182:183], v[184:185], s[50:51] op_sel_hi:[1,1,0]
	s_nop 0
	v_pk_fma_f32 v[182:183], v[182:183], v[184:185], s[52:53] op_sel_hi:[1,1,0]
	v_med3_f32 v184, v172, -4.0, 4.0
	v_med3_f32 v185, v173, -4.0, 4.0
	v_pk_mul_f32 v[186:187], v[184:185], v[184:185]
	v_pk_fma_f32 v[180:181], v[180:181], v[182:183], 0.5 op_sel_hi:[1,1,0]
	v_pk_fma_f32 v[186:187], v[186:187], s[72:73], -1.0 op_sel_hi:[1,0,0]
	v_pk_mul_f32 v[182:183], v[152:153], v[180:181]
	v_pk_fma_f32 v[154:155], v[186:187], s[74:75], v[154:155] op_sel_hi:[1,0,0]
	v_pk_fma_f32 v[180:181], v[152:153], v[180:181], v[182:183] op_sel:[0,0,1] op_sel_hi:[1,1,0]
	v_pk_fma_f32 v[154:155], v[186:187], v[154:155], s[0:1] op_sel_hi:[1,1,0]
	v_mul_f32_e32 v152, v170, v170
	v_pk_fma_f32 v[154:155], v[186:187], v[154:155], s[2:3] op_sel_hi:[1,1,0]
	v_pk_mul_f32 v[190:191], v[182:183], v[182:183]
	v_pk_fma_f32 v[154:155], v[186:187], v[154:155], s[28:29] op_sel_hi:[1,1,0]
	v_mov_b32_e32 v181, v166
	v_pk_fma_f32 v[154:155], v[186:187], v[154:155], s[30:31] op_sel_hi:[1,1,0]
	v_mov_b32_e32 v159, v190
	v_pk_fma_f32 v[154:155], v[186:187], v[154:155], s[48:49] op_sel_hi:[1,1,0]
	v_mov_b32_e32 v157, v191
	v_pk_fma_f32 v[154:155], v[186:187], v[154:155], s[50:51] op_sel_hi:[1,1,0]
	s_nop 0
	v_pk_fma_f32 v[154:155], v[186:187], v[154:155], s[52:53] op_sel_hi:[1,1,0]
	v_pk_fma_f32 v[186:187], v[170:171], v[170:171], v[152:153] op_sel_hi:[1,1,0]
	v_pk_fma_f32 v[154:155], v[184:185], v[154:155], 0.5 op_sel_hi:[1,1,0]
	v_mov_b32_e32 v184, v171
	v_pk_mul_f32 v[172:173], v[172:173], v[154:155]
	v_mov_b32_e32 v154, v170
	v_mov_b32_e32 v155, v168
	v_mov_b32_e32 v185, v169
	v_pk_add_f32 v[154:155], v[154:155], v[184:185]
	v_mul_f32_e32 v152, v168, v168
	v_pk_add_f32 v[184:185], v[154:155], v[154:155] op_sel:[0,1] op_sel_hi:[1,0]
	v_pk_fma_f32 v[188:189], v[168:169], v[168:169], v[152:153] op_sel_hi:[1,1,0]
	v_mul_f32_e32 v152, v172, v172
	v_pk_fma_f32 v[192:193], v[172:173], v[172:173], v[152:153] op_sel_hi:[1,1,0]
	v_cvt_pk_bf16_f32 v152, v170, v171
	v_cvt_pk_bf16_f32 v153, v168, v169
	v_cvt_pk_bf16_f32 v154, v182, v183
	v_cvt_pk_bf16_f32 v155, v172, v173
	v_mov_b32_e32 v185, v167
	v_mov_b32_e32 v164, v172
	v_mov_b32_e32 v162, v173
	global_store_dwordx4 v[150:151], v[152:155], off offset:256
	v_pk_add_f32 v[150:151], v[180:181], v[184:185]
	v_mov_b32_e32 v186, v160
	v_pk_add_f32 v[152:153], v[164:165], v[162:163]
	v_mov_b32_e32 v188, v161
	v_pk_add_f32 v[150:151], v[150:151], v[152:153]
	v_pk_add_f32 v[152:153], v[186:187], v[188:189]
	v_pk_add_f32 v[154:155], v[158:159], v[156:157]
	v_mov_b32_e32 v3, v193
	v_pk_add_f32 v[152:153], v[154:155], v[152:153]
	s_nop 0
	v_pk_add_f32 v[152:153], v[152:153], v[2:3]
	s_nop 0
	v_pk_add_f32 v[150:151], v[150:151], v[152:153]
	ds_bpermute_b32 v152, v179, v150
	ds_bpermute_b32 v153, v179, v151
	s_waitcnt lgkmcnt(0)
	v_pk_add_f32 v[150:151], v[150:151], v[152:153]
	ds_bpermute_b32 v152, v178, v150
	ds_bpermute_b32 v153, v178, v151
	s_and_saveexec_b64 s[0:1], s[4:5]
	s_cbranch_execz .LBB0_464
	v_lshlrev_b64 v[148:149], 8, v[148:149]
	v_lshl_add_u64 v[148:149], s[14:15], 0, v[148:149]
	s_waitcnt lgkmcnt(0)
	v_pk_add_f32 v[150:151], v[150:151], v[152:153]
	v_lshl_add_u64 v[148:149], s[94:95], 3, v[148:149]
	global_store_dwordx2 v[148:149], v[150:151], off
.LBB0_464:
	s_or_b64 exec, exec, s[0:1]
	s_waitcnt lgkmcnt(1)
	s_nop 1
	v_mov_b32_e32 v152, v206
	s_mov_b32 s0, 0xbb7be14b
	v_add_u32_e32 v148, 0xa0, v142
	v_ashrrev_i32_e32 v149, 31, v148
	v_lshlrev_b64 v[150:151], 12, v[148:149]
	v_lshl_add_u64 v[150:151], s[12:13], 0, v[150:151]
	v_mov_b32_e32 v147, v2
	v_lshl_add_u64 v[150:151], v[150:151], 0, v[146:147]
	s_waitcnt lgkmcnt(0)
	v_pk_mul_f32 v[158:159], v[32:33], v[152:153] op_sel_hi:[1,0]
	s_nop 0
	v_med3_f32 v160, v158, -4.0, 4.0
	v_med3_f32 v161, v159, -4.0, 4.0
	v_pk_mul_f32 v[154:155], v[160:161], v[160:161]
	v_pk_mul_f32 v[156:157], v[34:35], v[152:153] op_sel_hi:[1,0]
	v_pk_fma_f32 v[162:163], v[154:155], s[72:73], -1.0 op_sel_hi:[1,0,0]
	v_mov_b64_e32 v[154:155], s[0:1]
	v_pk_fma_f32 v[164:165], v[162:163], s[74:75], v[154:155] op_sel_hi:[1,0,0]
	s_mov_b32 s0, 0x3bcff2a2
	v_pk_fma_f32 v[164:165], v[162:163], v[164:165], s[0:1] op_sel_hi:[1,1,0]
	s_nop 0
	v_pk_fma_f32 v[164:165], v[162:163], v[164:165], s[2:3] op_sel_hi:[1,1,0]
	s_nop 0
	v_pk_fma_f32 v[164:165], v[162:163], v[164:165], s[28:29] op_sel_hi:[1,1,0]
	s_nop 0
	v_pk_fma_f32 v[164:165], v[162:163], v[164:165], s[30:31] op_sel_hi:[1,1,0]
	s_nop 0
	v_pk_fma_f32 v[164:165], v[162:163], v[164:165], s[48:49] op_sel_hi:[1,1,0]
	s_nop 0
	v_pk_fma_f32 v[164:165], v[162:163], v[164:165], s[50:51] op_sel_hi:[1,1,0]
	s_nop 0
	v_pk_fma_f32 v[162:163], v[162:163], v[164:165], s[52:53] op_sel_hi:[1,1,0]
	s_nop 0
	v_pk_fma_f32 v[160:161], v[160:161], v[162:163], 0.5 op_sel_hi:[1,1,0]
	s_nop 0
	v_pk_mul_f32 v[168:169], v[158:159], v[160:161]
	v_med3_f32 v158, v156, -4.0, 4.0
	v_med3_f32 v159, v157, -4.0, 4.0
	v_pk_mul_f32 v[160:161], v[158:159], v[158:159]
	s_nop 0
	v_pk_fma_f32 v[160:161], v[160:161], s[72:73], -1.0 op_sel_hi:[1,0,0]
	s_nop 0
	v_pk_fma_f32 v[162:163], v[160:161], s[74:75], v[154:155] op_sel_hi:[1,0,0]
	s_nop 0
	v_pk_fma_f32 v[162:163], v[160:161], v[162:163], s[0:1] op_sel_hi:[1,1,0]
	s_nop 0
	v_pk_fma_f32 v[162:163], v[160:161], v[162:163], s[2:3] op_sel_hi:[1,1,0]
	s_nop 0
	v_pk_fma_f32 v[162:163], v[160:161], v[162:163], s[28:29] op_sel_hi:[1,1,0]
	s_nop 0
	v_pk_fma_f32 v[162:163], v[160:161], v[162:163], s[30:31] op_sel_hi:[1,1,0]
	s_nop 0
	v_pk_fma_f32 v[162:163], v[160:161], v[162:163], s[48:49] op_sel_hi:[1,1,0]
	s_nop 0
	v_pk_fma_f32 v[162:163], v[160:161], v[162:163], s[50:51] op_sel_hi:[1,1,0]
	s_nop 0
	v_pk_fma_f32 v[160:161], v[160:161], v[162:163], s[52:53] op_sel_hi:[1,1,0]
	s_nop 0
	v_pk_fma_f32 v[158:159], v[158:159], v[160:161], 0.5 op_sel_hi:[1,1,0]
	s_nop 0
	v_pk_mul_f32 v[170:171], v[156:157], v[158:159]
	v_pk_mul_f32 v[158:159], v[24:25], v[152:153] op_sel_hi:[1,0]
	v_pk_mul_f32 v[156:157], v[26:27], v[152:153] op_sel_hi:[1,0]
	v_med3_f32 v160, v158, -4.0, 4.0
	v_med3_f32 v161, v159, -4.0, 4.0
	v_pk_mul_f32 v[162:163], v[160:161], v[160:161]
	s_nop 0
	v_pk_fma_f32 v[162:163], v[162:163], s[72:73], -1.0 op_sel_hi:[1,0,0]
	s_nop 0
	v_pk_fma_f32 v[164:165], v[162:163], s[74:75], v[154:155] op_sel_hi:[1,0,0]
	s_nop 0
	v_pk_fma_f32 v[164:165], v[162:163], v[164:165], s[0:1] op_sel_hi:[1,1,0]
	s_nop 0
	v_pk_fma_f32 v[164:165], v[162:163], v[164:165], s[2:3] op_sel_hi:[1,1,0]
	s_nop 0
	v_pk_fma_f32 v[164:165], v[162:163], v[164:165], s[28:29] op_sel_hi:[1,1,0]
	s_nop 0
	v_pk_fma_f32 v[164:165], v[162:163], v[164:165], s[30:31] op_sel_hi:[1,1,0]
	s_nop 0
	v_pk_fma_f32 v[164:165], v[162:163], v[164:165], s[48:49] op_sel_hi:[1,1,0]
	s_nop 0
	v_pk_fma_f32 v[164:165], v[162:163], v[164:165], s[50:51] op_sel_hi:[1,1,0]
	s_nop 0
	v_pk_fma_f32 v[162:163], v[162:163], v[164:165], s[52:53] op_sel_hi:[1,1,0]
	s_nop 0
	v_pk_fma_f32 v[162:163], v[160:161], v[162:163], 0.5 op_sel_hi:[1,1,0]
	v_med3_f32 v160, v156, -4.0, 4.0
	v_med3_f32 v161, v157, -4.0, 4.0
	v_pk_mul_f32 v[164:165], v[160:161], v[160:161]
	v_pk_mul_f32 v[172:173], v[158:159], v[162:163]
	v_pk_fma_f32 v[164:165], v[164:165], s[72:73], -1.0 op_sel_hi:[1,0,0]
	v_pk_fma_f32 v[158:159], v[158:159], v[162:163], v[172:173] op_sel:[0,0,1] op_sel_hi:[1,1,0]
	v_pk_fma_f32 v[166:167], v[164:165], s[74:75], v[154:155] op_sel_hi:[1,0,0]
	s_nop 0
	v_pk_fma_f32 v[166:167], v[164:165], v[166:167], s[0:1] op_sel_hi:[1,1,0]
	s_nop 0
	v_pk_fma_f32 v[166:167], v[164:165], v[166:167], s[2:3] op_sel_hi:[1,1,0]
	s_nop 0
	v_pk_fma_f32 v[166:167], v[164:165], v[166:167], s[28:29] op_sel_hi:[1,1,0]
	s_nop 0
	v_pk_fma_f32 v[166:167], v[164:165], v[166:167], s[30:31] op_sel_hi:[1,1,0]
	s_nop 0
	v_pk_fma_f32 v[166:167], v[164:165], v[166:167], s[48:49] op_sel_hi:[1,1,0]
	s_nop 0
	v_pk_fma_f32 v[166:167], v[164:165], v[166:167], s[50:51] op_sel_hi:[1,1,0]
	s_nop 0
	v_pk_fma_f32 v[164:165], v[164:165], v[166:167], s[52:53] op_sel_hi:[1,1,0]
	v_mov_b32_e32 v166, v169
	v_mov_b32_e32 v167, v171
	v_pk_fma_f32 v[160:161], v[160:161], v[164:165], 0.5 op_sel_hi:[1,1,0]
	v_mov_b32_e32 v164, v168
	v_mov_b32_e32 v165, v170
	v_pk_mul_f32 v[162:163], v[166:167], v[166:167]
	v_pk_mul_f32 v[160:161], v[156:157], v[160:161]
	v_pk_fma_f32 v[162:163], v[164:165], v[164:165], v[162:163]
	v_cvt_pk_bf16_f32 v168, v168, v169
	v_pk_add_f32 v[162:163], v[162:163], v[162:163] op_sel_hi:[0,1]
	v_cvt_pk_bf16_f32 v169, v170, v171
	v_cvt_pk_bf16_f32 v170, v172, v173
	v_cvt_pk_bf16_f32 v171, v160, v161
	v_mul_f32_e32 v162, v172, v172
	global_store_dwordx4 v[150:151], v[168:171], off
	v_pk_add_f32 v[156:157], v[164:165], v[166:167]
	v_pk_fma_f32 v[164:165], v[172:173], v[172:173], v[162:163] op_sel_hi:[1,1,0]
	v_pk_mul_f32 v[170:171], v[28:29], v[152:153] op_sel_hi:[1,0]
	v_pk_mul_f32 v[168:169], v[30:31], v[152:153] op_sel_hi:[1,0]
	v_med3_f32 v172, v170, -4.0, 4.0
	v_med3_f32 v173, v171, -4.0, 4.0
	v_pk_mul_f32 v[180:181], v[172:173], v[172:173]
	v_pk_mul_f32 v[166:167], v[160:161], v[160:161]
	v_pk_fma_f32 v[180:181], v[180:181], s[72:73], -1.0 op_sel_hi:[1,0,0]
	v_pk_add_f32 v[156:157], v[156:157], v[156:157] op_sel:[0,1] op_sel_hi:[1,0]
	v_pk_fma_f32 v[182:183], v[180:181], s[74:75], v[154:155] op_sel_hi:[1,0,0]
	s_nop 0
	v_pk_fma_f32 v[182:183], v[180:181], v[182:183], s[0:1] op_sel_hi:[1,1,0]
	s_nop 0
	v_pk_fma_f32 v[182:183], v[180:181], v[182:183], s[2:3] op_sel_hi:[1,1,0]
	s_nop 0
	v_pk_fma_f32 v[182:183], v[180:181], v[182:183], s[28:29] op_sel_hi:[1,1,0]
	s_nop 0
	v_pk_fma_f32 v[182:183], v[180:181], v[182:183], s[30:31] op_sel_hi:[1,1,0]
	s_nop 0
	v_pk_fma_f32 v[182:183], v[180:181], v[182:183], s[48:49] op_sel_hi:[1,1,0]
	s_nop 0
	v_pk_fma_f32 v[182:183], v[180:181], v[182:183], s[50:51] op_sel_hi:[1,1,0]
	s_nop 0
	v_pk_fma_f32 v[180:181], v[180:181], v[182:183], s[52:53] op_sel_hi:[1,1,0]
	s_nop 0
	v_pk_fma_f32 v[172:173], v[172:173], v[180:181], 0.5 op_sel_hi:[1,1,0]
	s_nop 0
	v_pk_mul_f32 v[170:171], v[170:171], v[172:173]
	v_med3_f32 v172, v168, -4.0, 4.0
	v_med3_f32 v173, v169, -4.0, 4.0
	v_pk_mul_f32 v[180:181], v[172:173], v[172:173]
	s_nop 0
	v_pk_fma_f32 v[180:181], v[180:181], s[72:73], -1.0 op_sel_hi:[1,0,0]
	s_nop 0
	v_pk_fma_f32 v[182:183], v[180:181], s[74:75], v[154:155] op_sel_hi:[1,0,0]
	s_nop 0
	v_pk_fma_f32 v[182:183], v[180:181], v[182:183], s[0:1] op_sel_hi:[1,1,0]
	s_nop 0
	v_pk_fma_f32 v[182:183], v[180:181], v[182:183], s[2:3] op_sel_hi:[1,1,0]
	s_nop 0
	v_pk_fma_f32 v[182:183], v[180:181], v[182:183], s[28:29] op_sel_hi:[1,1,0]
	s_nop 0
	v_pk_fma_f32 v[182:183], v[180:181], v[182:183], s[30:31] op_sel_hi:[1,1,0]
	s_nop 0
	v_pk_fma_f32 v[182:183], v[180:181], v[182:183], s[48:49] op_sel_hi:[1,1,0]
	s_nop 0
	v_pk_fma_f32 v[182:183], v[180:181], v[182:183], s[50:51] op_sel_hi:[1,1,0]
	s_nop 0
	v_pk_fma_f32 v[180:181], v[180:181], v[182:183], s[52:53] op_sel_hi:[1,1,0]
	s_nop 0
	v_pk_fma_f32 v[172:173], v[172:173], v[180:181], 0.5 op_sel_hi:[1,1,0]
	s_nop 0
	v_pk_mul_f32 v[168:169], v[168:169], v[172:173]
	v_pk_mul_f32 v[172:173], v[22:23], v[152:153] op_sel_hi:[1,0]
	v_pk_mul_f32 v[152:153], v[20:21], v[152:153] op_sel_hi:[1,0]
	s_nop 0
	v_med3_f32 v180, v152, -4.0, 4.0
	v_med3_f32 v181, v153, -4.0, 4.0
	v_pk_mul_f32 v[182:183], v[180:181], v[180:181]
	s_nop 0
	v_pk_fma_f32 v[182:183], v[182:183], s[72:73], -1.0 op_sel_hi:[1,0,0]
	s_nop 0
	v_pk_fma_f32 v[184:185], v[182:183], s[74:75], v[154:155] op_sel_hi:[1,0,0]
	s_nop 0
	v_pk_fma_f32 v[184:185], v[182:183], v[184:185], s[0:1] op_sel_hi:[1,1,0]
	s_nop 0
	v_pk_fma_f32 v[184:185], v[182:183], v[184:185], s[2:3] op_sel_hi:[1,1,0]
	s_nop 0
	v_pk_fma_f32 v[184:185], v[182:183], v[184:185], s[28:29] op_sel_hi:[1,1,0]
	s_nop 0
	v_pk_fma_f32 v[184:185], v[182:183], v[184:185], s[30:31] op_sel_hi:[1,1,0]
	s_nop 0
	v_pk_fma_f32 v[184:185], v[182:183], v[184:185], s[48:49] op_sel_hi:[1,1,0]
	s_nop 0
	v_pk_fma_f32 v[184:185], v[182:183], v[184:185], s[50:51] op_sel_hi:[1,1,0]
	s_nop 0
	v_pk_fma_f32 v[182:183], v[182:183], v[184:185], s[52:53] op_sel_hi:[1,1,0]
	v_med3_f32 v184, v172, -4.0, 4.0
	v_med3_f32 v185, v173, -4.0, 4.0
	v_pk_mul_f32 v[186:187], v[184:185], v[184:185]
	v_pk_fma_f32 v[180:181], v[180:181], v[182:183], 0.5 op_sel_hi:[1,1,0]
	v_pk_fma_f32 v[186:187], v[186:187], s[72:73], -1.0 op_sel_hi:[1,0,0]
	v_pk_mul_f32 v[182:183], v[152:153], v[180:181]
	v_pk_fma_f32 v[154:155], v[186:187], s[74:75], v[154:155] op_sel_hi:[1,0,0]
	v_pk_fma_f32 v[180:181], v[152:153], v[180:181], v[182:183] op_sel:[0,0,1] op_sel_hi:[1,1,0]
	v_pk_fma_f32 v[154:155], v[186:187], v[154:155], s[0:1] op_sel_hi:[1,1,0]
	v_mul_f32_e32 v152, v170, v170
	v_pk_fma_f32 v[154:155], v[186:187], v[154:155], s[2:3] op_sel_hi:[1,1,0]
	v_pk_mul_f32 v[190:191], v[182:183], v[182:183]
	v_pk_fma_f32 v[154:155], v[186:187], v[154:155], s[28:29] op_sel_hi:[1,1,0]
	v_mov_b32_e32 v181, v166
	v_pk_fma_f32 v[154:155], v[186:187], v[154:155], s[30:31] op_sel_hi:[1,1,0]
	v_mov_b32_e32 v159, v190
	v_pk_fma_f32 v[154:155], v[186:187], v[154:155], s[48:49] op_sel_hi:[1,1,0]
	v_mov_b32_e32 v157, v191
	v_pk_fma_f32 v[154:155], v[186:187], v[154:155], s[50:51] op_sel_hi:[1,1,0]
	s_nop 0
	v_pk_fma_f32 v[154:155], v[186:187], v[154:155], s[52:53] op_sel_hi:[1,1,0]
	v_pk_fma_f32 v[186:187], v[170:171], v[170:171], v[152:153] op_sel_hi:[1,1,0]
	v_pk_fma_f32 v[154:155], v[184:185], v[154:155], 0.5 op_sel_hi:[1,1,0]
	v_mov_b32_e32 v184, v171
	v_pk_mul_f32 v[172:173], v[172:173], v[154:155]
	v_mov_b32_e32 v154, v170
	v_mov_b32_e32 v155, v168
	v_mov_b32_e32 v185, v169
	v_pk_add_f32 v[154:155], v[154:155], v[184:185]
	v_mul_f32_e32 v152, v168, v168
	v_pk_add_f32 v[184:185], v[154:155], v[154:155] op_sel:[0,1] op_sel_hi:[1,0]
	v_pk_fma_f32 v[188:189], v[168:169], v[168:169], v[152:153] op_sel_hi:[1,1,0]
	v_mul_f32_e32 v152, v172, v172
	v_pk_fma_f32 v[192:193], v[172:173], v[172:173], v[152:153] op_sel_hi:[1,1,0]
	v_cvt_pk_bf16_f32 v152, v170, v171
	v_cvt_pk_bf16_f32 v153, v168, v169
	v_cvt_pk_bf16_f32 v154, v182, v183
	v_cvt_pk_bf16_f32 v155, v172, v173
	v_mov_b32_e32 v185, v167
	v_mov_b32_e32 v164, v172
	v_mov_b32_e32 v162, v173
	global_store_dwordx4 v[150:151], v[152:155], off offset:256
	v_pk_add_f32 v[150:151], v[180:181], v[184:185]
	v_mov_b32_e32 v186, v160
	v_pk_add_f32 v[152:153], v[164:165], v[162:163]
	v_mov_b32_e32 v188, v161
	v_pk_add_f32 v[150:151], v[150:151], v[152:153]
	v_pk_add_f32 v[152:153], v[186:187], v[188:189]
	v_pk_add_f32 v[154:155], v[158:159], v[156:157]
	v_mov_b32_e32 v3, v193
	v_pk_add_f32 v[152:153], v[154:155], v[152:153]
	s_nop 0
	v_pk_add_f32 v[152:153], v[152:153], v[2:3]
	s_nop 0
	v_pk_add_f32 v[150:151], v[150:151], v[152:153]
	ds_bpermute_b32 v152, v179, v150
	ds_bpermute_b32 v153, v179, v151
	s_waitcnt lgkmcnt(0)
	v_pk_add_f32 v[150:151], v[150:151], v[152:153]
	ds_bpermute_b32 v152, v178, v150
	ds_bpermute_b32 v153, v178, v151
	s_and_saveexec_b64 s[0:1], s[4:5]
	s_cbranch_execz .LBB0_466
	v_lshlrev_b64 v[148:149], 8, v[148:149]
	v_lshl_add_u64 v[148:149], s[14:15], 0, v[148:149]
	s_waitcnt lgkmcnt(0)
	v_pk_add_f32 v[150:151], v[150:151], v[152:153]
	v_lshl_add_u64 v[148:149], s[94:95], 3, v[148:149]
	global_store_dwordx2 v[148:149], v[150:151], off
.LBB0_466:
	s_or_b64 exec, exec, s[0:1]
	s_nop 1
	v_mov_b32_e32 v150, v207
	v_add_u32_e32 v148, 0xb0, v142
	v_ashrrev_i32_e32 v149, 31, v148
	v_lshlrev_b64 v[144:145], 12, v[148:149]
	v_lshl_add_u64 v[144:145], s[12:13], 0, v[144:145]
	v_lshl_add_u64 v[144:145], v[144:145], 0, v[146:147]
	s_mov_b32 s0, 0xbb7be14b
	v_pk_mul_f32 v[154:155], v[16:17], v[150:151] op_sel_hi:[1,0]
	s_nop 0
	v_med3_f32 v156, v154, -4.0, 4.0
	v_med3_f32 v157, v155, -4.0, 4.0
	v_pk_mul_f32 v[146:147], v[156:157], v[156:157]
	s_waitcnt lgkmcnt(0)
	v_pk_mul_f32 v[152:153], v[18:19], v[150:151] op_sel_hi:[1,0]
	v_pk_fma_f32 v[158:159], v[146:147], s[72:73], -1.0 op_sel_hi:[1,0,0]
	v_mov_b64_e32 v[146:147], s[0:1]
	v_pk_fma_f32 v[160:161], v[158:159], s[74:75], v[146:147] op_sel_hi:[1,0,0]
	s_mov_b32 s0, 0x3bcff2a2
	v_pk_fma_f32 v[160:161], v[158:159], v[160:161], s[0:1] op_sel_hi:[1,1,0]
	s_nop 0
	v_pk_fma_f32 v[160:161], v[158:159], v[160:161], s[2:3] op_sel_hi:[1,1,0]
	s_nop 0
	v_pk_fma_f32 v[160:161], v[158:159], v[160:161], s[28:29] op_sel_hi:[1,1,0]
	s_nop 0
	v_pk_fma_f32 v[160:161], v[158:159], v[160:161], s[30:31] op_sel_hi:[1,1,0]
	s_nop 0
	v_pk_fma_f32 v[160:161], v[158:159], v[160:161], s[48:49] op_sel_hi:[1,1,0]
	s_nop 0
	v_pk_fma_f32 v[160:161], v[158:159], v[160:161], s[50:51] op_sel_hi:[1,1,0]
	s_nop 0
	v_pk_fma_f32 v[158:159], v[158:159], v[160:161], s[52:53] op_sel_hi:[1,1,0]
	s_nop 0
	v_pk_fma_f32 v[156:157], v[156:157], v[158:159], 0.5 op_sel_hi:[1,1,0]
	s_nop 0
	v_pk_mul_f32 v[164:165], v[154:155], v[156:157]
	v_med3_f32 v154, v152, -4.0, 4.0
	v_med3_f32 v155, v153, -4.0, 4.0
	v_pk_mul_f32 v[156:157], v[154:155], v[154:155]
	s_nop 0
	v_pk_fma_f32 v[156:157], v[156:157], s[72:73], -1.0 op_sel_hi:[1,0,0]
	s_nop 0
	v_pk_fma_f32 v[158:159], v[156:157], s[74:75], v[146:147] op_sel_hi:[1,0,0]
	s_nop 0
	v_pk_fma_f32 v[158:159], v[156:157], v[158:159], s[0:1] op_sel_hi:[1,1,0]
	s_nop 0
	v_pk_fma_f32 v[158:159], v[156:157], v[158:159], s[2:3] op_sel_hi:[1,1,0]
	s_nop 0
	v_pk_fma_f32 v[158:159], v[156:157], v[158:159], s[28:29] op_sel_hi:[1,1,0]
	s_nop 0
	v_pk_fma_f32 v[158:159], v[156:157], v[158:159], s[30:31] op_sel_hi:[1,1,0]
	s_nop 0
	v_pk_fma_f32 v[158:159], v[156:157], v[158:159], s[48:49] op_sel_hi:[1,1,0]
	s_nop 0
	v_pk_fma_f32 v[158:159], v[156:157], v[158:159], s[50:51] op_sel_hi:[1,1,0]
	s_nop 0
	v_pk_fma_f32 v[156:157], v[156:157], v[158:159], s[52:53] op_sel_hi:[1,1,0]
	s_nop 0
	v_pk_fma_f32 v[154:155], v[154:155], v[156:157], 0.5 op_sel_hi:[1,1,0]
	s_nop 0
	v_pk_mul_f32 v[166:167], v[152:153], v[154:155]
	v_pk_mul_f32 v[154:155], v[8:9], v[150:151] op_sel_hi:[1,0]
	v_pk_mul_f32 v[152:153], v[10:11], v[150:151] op_sel_hi:[1,0]
	v_med3_f32 v156, v154, -4.0, 4.0
	v_med3_f32 v157, v155, -4.0, 4.0
	v_pk_mul_f32 v[158:159], v[156:157], v[156:157]
	s_nop 0
	v_pk_fma_f32 v[158:159], v[158:159], s[72:73], -1.0 op_sel_hi:[1,0,0]
	s_nop 0
	v_pk_fma_f32 v[160:161], v[158:159], s[74:75], v[146:147] op_sel_hi:[1,0,0]
	s_nop 0
	v_pk_fma_f32 v[160:161], v[158:159], v[160:161], s[0:1] op_sel_hi:[1,1,0]
	s_nop 0
	v_pk_fma_f32 v[160:161], v[158:159], v[160:161], s[2:3] op_sel_hi:[1,1,0]
	s_nop 0
	v_pk_fma_f32 v[160:161], v[158:159], v[160:161], s[28:29] op_sel_hi:[1,1,0]
	s_nop 0
	v_pk_fma_f32 v[160:161], v[158:159], v[160:161], s[30:31] op_sel_hi:[1,1,0]
	s_nop 0
	v_pk_fma_f32 v[160:161], v[158:159], v[160:161], s[48:49] op_sel_hi:[1,1,0]
	s_nop 0
	v_pk_fma_f32 v[160:161], v[158:159], v[160:161], s[50:51] op_sel_hi:[1,1,0]
	s_nop 0
	v_pk_fma_f32 v[158:159], v[158:159], v[160:161], s[52:53] op_sel_hi:[1,1,0]
	s_nop 0
	v_pk_fma_f32 v[158:159], v[156:157], v[158:159], 0.5 op_sel_hi:[1,1,0]
	v_med3_f32 v156, v152, -4.0, 4.0
	v_med3_f32 v157, v153, -4.0, 4.0
	v_pk_mul_f32 v[160:161], v[156:157], v[156:157]
	v_pk_mul_f32 v[168:169], v[154:155], v[158:159]
	v_pk_fma_f32 v[160:161], v[160:161], s[72:73], -1.0 op_sel_hi:[1,0,0]
	v_pk_fma_f32 v[154:155], v[154:155], v[158:159], v[168:169] op_sel:[0,0,1] op_sel_hi:[1,1,0]
	v_pk_fma_f32 v[162:163], v[160:161], s[74:75], v[146:147] op_sel_hi:[1,0,0]
	s_nop 0
	v_pk_fma_f32 v[162:163], v[160:161], v[162:163], s[0:1] op_sel_hi:[1,1,0]
	s_nop 0
	v_pk_fma_f32 v[162:163], v[160:161], v[162:163], s[2:3] op_sel_hi:[1,1,0]
	s_nop 0
	v_pk_fma_f32 v[162:163], v[160:161], v[162:163], s[28:29] op_sel_hi:[1,1,0]
	s_nop 0
	v_pk_fma_f32 v[162:163], v[160:161], v[162:163], s[30:31] op_sel_hi:[1,1,0]
	s_nop 0
	v_pk_fma_f32 v[162:163], v[160:161], v[162:163], s[48:49] op_sel_hi:[1,1,0]
	s_nop 0
	v_pk_fma_f32 v[162:163], v[160:161], v[162:163], s[50:51] op_sel_hi:[1,1,0]
	s_nop 0
	v_pk_fma_f32 v[160:161], v[160:161], v[162:163], s[52:53] op_sel_hi:[1,1,0]
	v_mov_b32_e32 v162, v165
	v_mov_b32_e32 v163, v167
	v_pk_fma_f32 v[156:157], v[156:157], v[160:161], 0.5 op_sel_hi:[1,1,0]
	v_mov_b32_e32 v160, v164
	v_mov_b32_e32 v161, v166
	v_pk_mul_f32 v[158:159], v[162:163], v[162:163]
	v_pk_mul_f32 v[156:157], v[152:153], v[156:157]
	v_pk_fma_f32 v[158:159], v[160:161], v[160:161], v[158:159]
	v_cvt_pk_bf16_f32 v164, v164, v165
	v_pk_add_f32 v[158:159], v[158:159], v[158:159] op_sel_hi:[0,1]
	v_cvt_pk_bf16_f32 v165, v166, v167
	v_cvt_pk_bf16_f32 v166, v168, v169
	v_cvt_pk_bf16_f32 v167, v156, v157
	v_mul_f32_e32 v158, v168, v168
	global_store_dwordx4 v[144:145], v[164:167], off
	v_pk_add_f32 v[152:153], v[160:161], v[162:163]
	v_pk_fma_f32 v[160:161], v[168:169], v[168:169], v[158:159] op_sel_hi:[1,1,0]
	v_pk_mul_f32 v[166:167], v[12:13], v[150:151] op_sel_hi:[1,0]
	v_pk_mul_f32 v[164:165], v[14:15], v[150:151] op_sel_hi:[1,0]
	v_med3_f32 v168, v166, -4.0, 4.0
	v_med3_f32 v169, v167, -4.0, 4.0
	v_pk_mul_f32 v[170:171], v[168:169], v[168:169]
	v_pk_mul_f32 v[162:163], v[156:157], v[156:157]
	v_pk_fma_f32 v[170:171], v[170:171], s[72:73], -1.0 op_sel_hi:[1,0,0]
	v_pk_add_f32 v[152:153], v[152:153], v[152:153] op_sel:[0,1] op_sel_hi:[1,0]
	v_pk_fma_f32 v[172:173], v[170:171], s[74:75], v[146:147] op_sel_hi:[1,0,0]
	s_nop 0
	v_pk_fma_f32 v[172:173], v[170:171], v[172:173], s[0:1] op_sel_hi:[1,1,0]
	s_nop 0
	v_pk_fma_f32 v[172:173], v[170:171], v[172:173], s[2:3] op_sel_hi:[1,1,0]
	s_nop 0
	v_pk_fma_f32 v[172:173], v[170:171], v[172:173], s[28:29] op_sel_hi:[1,1,0]
	s_nop 0
	v_pk_fma_f32 v[172:173], v[170:171], v[172:173], s[30:31] op_sel_hi:[1,1,0]
	s_nop 0
	v_pk_fma_f32 v[172:173], v[170:171], v[172:173], s[48:49] op_sel_hi:[1,1,0]
	s_nop 0
	v_pk_fma_f32 v[172:173], v[170:171], v[172:173], s[50:51] op_sel_hi:[1,1,0]
	s_nop 0
	v_pk_fma_f32 v[170:171], v[170:171], v[172:173], s[52:53] op_sel_hi:[1,1,0]
	s_nop 0
	v_pk_fma_f32 v[168:169], v[168:169], v[170:171], 0.5 op_sel_hi:[1,1,0]
	s_nop 0
	v_pk_mul_f32 v[166:167], v[166:167], v[168:169]
	v_med3_f32 v168, v164, -4.0, 4.0
	v_med3_f32 v169, v165, -4.0, 4.0
	v_pk_mul_f32 v[170:171], v[168:169], v[168:169]
	v_mul_f32_e32 v158, v166, v166
	v_pk_fma_f32 v[170:171], v[170:171], s[72:73], -1.0 op_sel_hi:[1,0,0]
	s_nop 0
	v_pk_fma_f32 v[172:173], v[170:171], s[74:75], v[146:147] op_sel_hi:[1,0,0]
	s_nop 0
	v_pk_fma_f32 v[172:173], v[170:171], v[172:173], s[0:1] op_sel_hi:[1,1,0]
	s_nop 0
	v_pk_fma_f32 v[172:173], v[170:171], v[172:173], s[2:3] op_sel_hi:[1,1,0]
	s_nop 0
	v_pk_fma_f32 v[172:173], v[170:171], v[172:173], s[28:29] op_sel_hi:[1,1,0]
	s_nop 0
	v_pk_fma_f32 v[172:173], v[170:171], v[172:173], s[30:31] op_sel_hi:[1,1,0]
	s_nop 0
	v_pk_fma_f32 v[172:173], v[170:171], v[172:173], s[48:49] op_sel_hi:[1,1,0]
	s_nop 0
	v_pk_fma_f32 v[172:173], v[170:171], v[172:173], s[50:51] op_sel_hi:[1,1,0]
	s_nop 0
	v_pk_fma_f32 v[170:171], v[170:171], v[172:173], s[52:53] op_sel_hi:[1,1,0]
	s_nop 0
	v_pk_fma_f32 v[168:169], v[168:169], v[170:171], 0.5 op_sel_hi:[1,1,0]
	s_nop 0
	v_pk_mul_f32 v[168:169], v[164:165], v[168:169]
	v_pk_mul_f32 v[164:165], v[6:7], v[150:151] op_sel_hi:[1,0]
	v_pk_mul_f32 v[150:151], v[4:5], v[150:151] op_sel_hi:[1,0]
	s_nop 0
	v_med3_f32 v170, v150, -4.0, 4.0
	v_med3_f32 v171, v151, -4.0, 4.0
	v_pk_mul_f32 v[172:173], v[170:171], v[170:171]
	s_nop 0
	v_pk_fma_f32 v[172:173], v[172:173], s[72:73], -1.0 op_sel_hi:[1,0,0]
	s_nop 0
	v_pk_fma_f32 v[180:181], v[172:173], s[74:75], v[146:147] op_sel_hi:[1,0,0]
	s_nop 0
	v_pk_fma_f32 v[180:181], v[172:173], v[180:181], s[0:1] op_sel_hi:[1,1,0]
	s_nop 0
	v_pk_fma_f32 v[180:181], v[172:173], v[180:181], s[2:3] op_sel_hi:[1,1,0]
	s_nop 0
	v_pk_fma_f32 v[180:181], v[172:173], v[180:181], s[28:29] op_sel_hi:[1,1,0]
	s_nop 0
	v_pk_fma_f32 v[180:181], v[172:173], v[180:181], s[30:31] op_sel_hi:[1,1,0]
	s_nop 0
	v_pk_fma_f32 v[180:181], v[172:173], v[180:181], s[48:49] op_sel_hi:[1,1,0]
	s_nop 0
	v_pk_fma_f32 v[180:181], v[172:173], v[180:181], s[50:51] op_sel_hi:[1,1,0]
	s_nop 0
	v_pk_fma_f32 v[172:173], v[172:173], v[180:181], s[52:53] op_sel_hi:[1,1,0]
	v_med3_f32 v180, v164, -4.0, 4.0
	v_med3_f32 v181, v165, -4.0, 4.0
	v_pk_mul_f32 v[182:183], v[180:181], v[180:181]
	v_pk_fma_f32 v[170:171], v[170:171], v[172:173], 0.5 op_sel_hi:[1,1,0]
	v_pk_fma_f32 v[182:183], v[182:183], s[72:73], -1.0 op_sel_hi:[1,0,0]
	v_pk_mul_f32 v[172:173], v[150:151], v[170:171]
	v_pk_fma_f32 v[146:147], v[182:183], s[74:75], v[146:147] op_sel_hi:[1,0,0]
	v_pk_fma_f32 v[150:151], v[150:151], v[170:171], v[172:173] op_sel:[0,0,1] op_sel_hi:[1,1,0]
	v_pk_fma_f32 v[146:147], v[182:183], v[146:147], s[0:1] op_sel_hi:[1,1,0]
	v_pk_fma_f32 v[170:171], v[166:167], v[166:167], v[158:159] op_sel_hi:[1,1,0]
	v_pk_fma_f32 v[146:147], v[182:183], v[146:147], s[2:3] op_sel_hi:[1,1,0]
	v_mul_f32_e32 v158, v168, v168
	v_pk_fma_f32 v[146:147], v[182:183], v[146:147], s[28:29] op_sel_hi:[1,1,0]
	v_pk_mul_f32 v[184:185], v[172:173], v[172:173]
	v_pk_fma_f32 v[146:147], v[182:183], v[146:147], s[30:31] op_sel_hi:[1,1,0]
	v_mov_b32_e32 v151, v162
	v_pk_fma_f32 v[146:147], v[182:183], v[146:147], s[48:49] op_sel_hi:[1,1,0]
	v_mov_b32_e32 v170, v156
	v_pk_fma_f32 v[146:147], v[182:183], v[146:147], s[50:51] op_sel_hi:[1,1,0]
	v_mov_b32_e32 v155, v184
	v_pk_fma_f32 v[146:147], v[182:183], v[146:147], s[52:53] op_sel_hi:[1,1,0]
	v_pk_fma_f32 v[182:183], v[168:169], v[168:169], v[158:159] op_sel_hi:[1,1,0]
	v_pk_fma_f32 v[146:147], v[180:181], v[146:147], 0.5 op_sel_hi:[1,1,0]
	v_mov_b32_e32 v180, v167
	v_pk_mul_f32 v[146:147], v[164:165], v[146:147]
	v_mov_b32_e32 v164, v166
	v_mov_b32_e32 v165, v168
	v_mov_b32_e32 v181, v169
	v_pk_add_f32 v[164:165], v[164:165], v[180:181]
	v_mul_f32_e32 v158, v146, v146
	v_pk_add_f32 v[180:181], v[164:165], v[164:165] op_sel:[0,1] op_sel_hi:[1,0]
	v_pk_fma_f32 v[186:187], v[146:147], v[146:147], v[158:159] op_sel_hi:[1,1,0]
	v_cvt_pk_bf16_f32 v164, v166, v167
	v_cvt_pk_bf16_f32 v165, v168, v169
	v_cvt_pk_bf16_f32 v166, v172, v173
	v_cvt_pk_bf16_f32 v167, v146, v147
	v_mov_b32_e32 v181, v163
	v_mov_b32_e32 v160, v146
	v_mov_b32_e32 v158, v147
	global_store_dwordx4 v[144:145], v[164:167], off offset:256
	v_pk_add_f32 v[144:145], v[150:151], v[180:181]
	v_pk_add_f32 v[146:147], v[160:161], v[158:159]
	v_mov_b32_e32 v182, v157
	v_mov_b32_e32 v153, v185
	v_pk_add_f32 v[144:145], v[144:145], v[146:147]
	v_pk_add_f32 v[146:147], v[170:171], v[182:183]
	v_pk_add_f32 v[150:151], v[154:155], v[152:153]
	v_mov_b32_e32 v3, v187
	v_pk_add_f32 v[146:147], v[150:151], v[146:147]
	s_nop 0
	v_pk_add_f32 v[146:147], v[146:147], v[2:3]
	s_nop 0
	v_pk_add_f32 v[144:145], v[144:145], v[146:147]
	ds_bpermute_b32 v146, v179, v144
	ds_bpermute_b32 v147, v179, v145
	s_waitcnt lgkmcnt(0)
	v_pk_add_f32 v[144:145], v[144:145], v[146:147]
	ds_bpermute_b32 v146, v178, v144
	ds_bpermute_b32 v147, v178, v145
	s_and_saveexec_b64 s[0:1], s[4:5]
	s_cbranch_execz .LBB0_468
	v_lshlrev_b64 v[148:149], 8, v[148:149]
	s_waitcnt lgkmcnt(0)
	v_pk_add_f32 v[144:145], v[144:145], v[146:147]
	v_lshl_add_u64 v[146:147], s[14:15], 0, v[148:149]
	v_lshl_add_u64 v[146:147], s[94:95], 3, v[146:147]
	global_store_dwordx2 v[146:147], v[144:145], off

.LBB0_469:
	v_lshl_add_u64 v[144:145], v[142:143], 2, s[16:17]
	global_load_dword v148, v[144:145], off
	global_load_dword v201, v[144:145], off offset:64
	global_load_dword v202, v[144:145], off offset:128
	global_load_dword v203, v[144:145], off offset:192
	global_load_dword v204, v[144:145], off offset:512
	global_load_dword v205, v[144:145], off offset:576
	global_load_dword v206, v[144:145], off offset:640
	global_load_dword v207, v[144:145], off offset:704
	s_mov_b32 s0, 0xbb7be14b
	s_mov_b32 s2, 0x3bcff2a2
	s_mov_b32 s28, 0xbc40d0ac
	s_mov_b32 s30, 0x3cb76c34
	s_mov_b32 s48, 0xbd17b858
	s_mov_b32 s50, 0x3d6537d1
	s_mov_b32 s52, 0xbdacab04
	s_mov_b32 s54, 0x3e342bfa
	s_waitcnt lgkmcnt(0)
	v_lshl_or_b32 v146, s47, 7, v176
	v_ashrrev_i32_e32 v147, 31, v146
	s_waitcnt vmcnt(0)
	v_pk_mul_f32 v[150:151], v[128:129], v[148:149] op_sel_hi:[1,0]
	s_nop 0
	v_med3_f32 v152, v150, -4.0, 4.0
	v_med3_f32 v153, v151, -4.0, 4.0
	v_pk_mul_f32 v[128:129], v[152:153], v[152:153]
	v_pk_mul_f32 v[130:131], v[130:131], v[148:149] op_sel_hi:[1,0]
	v_pk_fma_f32 v[154:155], v[128:129], s[72:73], -1.0 op_sel_hi:[1,0,0]
	v_mov_b64_e32 v[128:129], s[0:1]
	v_pk_fma_f32 v[156:157], v[154:155], s[74:75], v[128:129] op_sel_hi:[1,0,0]
	v_pk_mul_f32 v[124:125], v[124:125], v[148:149] op_sel_hi:[1,0]
	v_pk_fma_f32 v[156:157], v[154:155], v[156:157], s[2:3] op_sel_hi:[1,1,0]
	v_mul_f32_e32 v3, 0xbfb8aa3b, v124
	v_pk_fma_f32 v[156:157], v[154:155], v[156:157], s[28:29] op_sel_hi:[1,1,0]
	v_exp_f32_e32 v3, v3
	v_pk_fma_f32 v[156:157], v[154:155], v[156:157], s[30:31] op_sel_hi:[1,1,0]
	v_pk_mul_f32 v[126:127], v[126:127], v[148:149] op_sel_hi:[1,0]
	v_pk_fma_f32 v[156:157], v[154:155], v[156:157], s[48:49] op_sel_hi:[1,1,0]
	v_add_f32_e32 v3, 1.0, v3
	v_pk_fma_f32 v[156:157], v[154:155], v[156:157], s[50:51] op_sel_hi:[1,1,0]
	v_pk_mul_f32 v[120:121], v[120:121], v[148:149] op_sel_hi:[1,0]
	v_pk_fma_f32 v[156:157], v[154:155], v[156:157], s[52:53] op_sel_hi:[1,1,0]
	v_pk_mul_f32 v[122:123], v[122:123], v[148:149] op_sel_hi:[1,0]
	v_pk_fma_f32 v[154:155], v[154:155], v[156:157], s[54:55] op_sel_hi:[1,1,0]
	v_pk_mul_f32 v[116:117], v[116:117], v[148:149] op_sel_hi:[1,0]
	v_pk_fma_f32 v[152:153], v[152:153], v[154:155], 0.5 op_sel_hi:[1,1,0]
	v_pk_mul_f32 v[118:119], v[118:119], v[148:149] op_sel_hi:[1,0]
	v_pk_mul_f32 v[150:151], v[150:151], v[152:153]
	v_med3_f32 v152, v130, -4.0, 4.0
	v_med3_f32 v153, v131, -4.0, 4.0
	v_pk_mul_f32 v[154:155], v[152:153], v[152:153]
	s_mov_b32 s0, 0x80000
	v_pk_fma_f32 v[154:155], v[154:155], s[72:73], -1.0 op_sel_hi:[1,0,0]
	s_nop 0
	v_pk_fma_f32 v[156:157], v[154:155], s[74:75], v[128:129] op_sel_hi:[1,0,0]
	s_nop 0
	v_pk_fma_f32 v[156:157], v[154:155], v[156:157], s[2:3] op_sel_hi:[1,1,0]
	s_nop 0
	v_pk_fma_f32 v[156:157], v[154:155], v[156:157], s[28:29] op_sel_hi:[1,1,0]
	s_nop 0
	v_pk_fma_f32 v[156:157], v[154:155], v[156:157], s[30:31] op_sel_hi:[1,1,0]
	s_nop 0
	v_pk_fma_f32 v[156:157], v[154:155], v[156:157], s[48:49] op_sel_hi:[1,1,0]
	s_nop 0
	v_pk_fma_f32 v[156:157], v[154:155], v[156:157], s[50:51] op_sel_hi:[1,1,0]
	s_nop 0
	v_pk_fma_f32 v[156:157], v[154:155], v[156:157], s[52:53] op_sel_hi:[1,1,0]
	s_nop 0
	v_pk_fma_f32 v[154:155], v[154:155], v[156:157], s[54:55] op_sel_hi:[1,1,0]
	s_nop 0
	v_pk_fma_f32 v[152:153], v[152:153], v[154:155], 0.5 op_sel_hi:[1,1,0]
	s_nop 0
	v_pk_mul_f32 v[130:131], v[130:131], v[152:153]
	v_rcp_f32_e32 v152, v3
	v_mul_f32_e32 v3, 0xbfb8aa3b, v125
	v_exp_f32_e32 v3, v3
	s_nop 0
	v_add_f32_e32 v3, 1.0, v3
	v_rcp_f32_e32 v153, v3
	v_mul_f32_e32 v3, 0xbfb8aa3b, v126
	v_exp_f32_e32 v3, v3
	v_pk_mul_f32 v[152:153], v[124:125], v[152:153]
	v_add_f32_e32 v3, 1.0, v3
	v_rcp_f32_e32 v154, v3
	v_mul_f32_e32 v3, 0xbfb8aa3b, v127
	v_exp_f32_e32 v3, v3
	s_nop 0
	v_add_f32_e32 v3, 1.0, v3
	v_rcp_f32_e32 v155, v3
	v_mul_f32_e32 v3, 0xbfb8aa3b, v116
	v_exp_f32_e32 v3, v3
	v_pk_mul_f32 v[126:127], v[126:127], v[154:155]
	s_nop 0
	v_pk_mul_f32 v[124:125], v[126:127], v[130:131]
	v_med3_f32 v130, v120, -4.0, 4.0
	v_med3_f32 v131, v121, -4.0, 4.0
	v_pk_mul_f32 v[126:127], v[152:153], v[150:151]
	v_pk_mul_f32 v[150:151], v[130:131], v[130:131]
	v_add_f32_e32 v3, 1.0, v3
	v_pk_fma_f32 v[150:151], v[150:151], s[72:73], -1.0 op_sel_hi:[1,0,0]
	s_nop 0
	v_pk_fma_f32 v[152:153], v[150:151], s[74:75], v[128:129] op_sel_hi:[1,0,0]
	s_nop 0
	v_pk_fma_f32 v[152:153], v[150:151], v[152:153], s[2:3] op_sel_hi:[1,1,0]
	s_nop 0
	v_pk_fma_f32 v[152:153], v[150:151], v[152:153], s[28:29] op_sel_hi:[1,1,0]
	s_nop 0
	v_pk_fma_f32 v[152:153], v[150:151], v[152:153], s[30:31] op_sel_hi:[1,1,0]
	s_nop 0
	v_pk_fma_f32 v[152:153], v[150:151], v[152:153], s[48:49] op_sel_hi:[1,1,0]
	s_nop 0
	v_pk_fma_f32 v[152:153], v[150:151], v[152:153], s[50:51] op_sel_hi:[1,1,0]
	s_nop 0
	v_pk_fma_f32 v[152:153], v[150:151], v[152:153], s[52:53] op_sel_hi:[1,1,0]
	s_nop 0
	v_pk_fma_f32 v[150:151], v[150:151], v[152:153], s[54:55] op_sel_hi:[1,1,0]
	s_nop 0
	v_pk_fma_f32 v[130:131], v[130:131], v[150:151], 0.5 op_sel_hi:[1,1,0]
	s_nop 0
	v_pk_mul_f32 v[120:121], v[120:121], v[130:131]
	v_med3_f32 v130, v122, -4.0, 4.0
	v_med3_f32 v131, v123, -4.0, 4.0
	v_pk_mul_f32 v[150:151], v[130:131], v[130:131]
	s_nop 0
	v_pk_fma_f32 v[150:151], v[150:151], s[72:73], -1.0 op_sel_hi:[1,0,0]
	s_nop 0
	v_pk_fma_f32 v[152:153], v[150:151], s[74:75], v[128:129] op_sel_hi:[1,0,0]
	s_nop 0
	v_pk_fma_f32 v[152:153], v[150:151], v[152:153], s[2:3] op_sel_hi:[1,1,0]
	s_nop 0
	v_pk_fma_f32 v[152:153], v[150:151], v[152:153], s[28:29] op_sel_hi:[1,1,0]
	s_nop 0
	v_pk_fma_f32 v[152:153], v[150:151], v[152:153], s[30:31] op_sel_hi:[1,1,0]
	s_nop 0
	v_pk_fma_f32 v[152:153], v[150:151], v[152:153], s[48:49] op_sel_hi:[1,1,0]
	s_nop 0
	v_pk_fma_f32 v[152:153], v[150:151], v[152:153], s[50:51] op_sel_hi:[1,1,0]
	s_nop 0
	v_pk_fma_f32 v[152:153], v[150:151], v[152:153], s[52:53] op_sel_hi:[1,1,0]
	s_nop 0
	v_pk_fma_f32 v[150:151], v[150:151], v[152:153], s[54:55] op_sel_hi:[1,1,0]
	s_nop 0
	v_pk_fma_f32 v[130:131], v[130:131], v[150:151], 0.5 op_sel_hi:[1,1,0]
	s_nop 0
	v_pk_mul_f32 v[122:123], v[122:123], v[130:131]
	v_rcp_f32_e32 v130, v3
	v_mul_f32_e32 v3, 0xbfb8aa3b, v117
	v_exp_f32_e32 v3, v3
	s_nop 0
	v_add_f32_e32 v3, 1.0, v3
	v_rcp_f32_e32 v131, v3
	v_mul_f32_e32 v3, 0xbfb8aa3b, v118
	v_exp_f32_e32 v3, v3
	v_pk_mul_f32 v[116:117], v[116:117], v[130:131]
	s_nop 0
	v_pk_mul_f32 v[116:117], v[116:117], v[120:121]
	v_add_f32_e32 v3, 1.0, v3
	v_rcp_f32_e32 v148, v3
	v_mul_f32_e32 v3, 0xbfb8aa3b, v119
	v_exp_f32_e32 v3, v3
	v_cvt_pk_bf16_f32 v120, v126, v127
	v_cvt_pk_bf16_f32 v121, v124, v125
	v_add_f32_e32 v3, 1.0, v3
	v_rcp_f32_e32 v149, v3
	s_nop 0
	v_pk_mul_f32 v[118:119], v[118:119], v[148:149]
	s_nop 0
	v_pk_mul_f32 v[118:119], v[118:119], v[122:123]
	v_cvt_pk_bf16_f32 v122, v116, v117
	v_lshlrev_b64 v[116:117], 12, v[142:143]
	v_cvt_pk_bf16_f32 v123, v118, v119
	v_lshl_add_u64 v[116:117], s[10:11], 0, v[116:117]
	v_lshlrev_b64 v[118:119], 1, v[146:147]
	v_lshl_add_u64 v[116:117], v[116:117], 0, v[118:119]
	global_store_dwordx4 v[116:117], v[120:123], off
	s_nop 1
	v_or_b32_e32 v120, 16, v142
	v_ashrrev_i32_e32 v121, 31, v120
	v_lshl_add_u64 v[122:123], v[120:121], 2, s[16:17]
	s_nop 1
	v_mov_b32_e32 v122, v201
	v_pk_mul_f32 v[112:113], v[112:113], v[122:123] op_sel_hi:[1,0]
	s_nop 0
	v_med3_f32 v124, v112, -4.0, 4.0
	v_med3_f32 v125, v113, -4.0, 4.0
	v_pk_mul_f32 v[126:127], v[124:125], v[124:125]
	v_pk_mul_f32 v[114:115], v[114:115], v[122:123] op_sel_hi:[1,0]
	v_pk_fma_f32 v[126:127], v[126:127], s[72:73], -1.0 op_sel_hi:[1,0,0]
	v_pk_mul_f32 v[108:109], v[108:109], v[122:123] op_sel_hi:[1,0]
	v_pk_fma_f32 v[130:131], v[126:127], s[74:75], v[128:129] op_sel_hi:[1,0,0]
	v_mul_f32_e32 v3, 0xbfb8aa3b, v108
	v_pk_fma_f32 v[130:131], v[126:127], v[130:131], s[2:3] op_sel_hi:[1,1,0]
	v_exp_f32_e32 v3, v3
	v_pk_fma_f32 v[130:131], v[126:127], v[130:131], s[28:29] op_sel_hi:[1,1,0]
	v_pk_mul_f32 v[110:111], v[110:111], v[122:123] op_sel_hi:[1,0]
	v_pk_fma_f32 v[130:131], v[126:127], v[130:131], s[30:31] op_sel_hi:[1,1,0]
	v_add_f32_e32 v3, 1.0, v3
	v_pk_fma_f32 v[130:131], v[126:127], v[130:131], s[48:49] op_sel_hi:[1,1,0]
	v_pk_mul_f32 v[104:105], v[104:105], v[122:123] op_sel_hi:[1,0]
	v_pk_fma_f32 v[130:131], v[126:127], v[130:131], s[50:51] op_sel_hi:[1,1,0]
	v_pk_mul_f32 v[106:107], v[106:107], v[122:123] op_sel_hi:[1,0]
	v_pk_fma_f32 v[130:131], v[126:127], v[130:131], s[52:53] op_sel_hi:[1,1,0]
	v_pk_mul_f32 v[100:101], v[100:101], v[122:123] op_sel_hi:[1,0]
	v_pk_fma_f32 v[126:127], v[126:127], v[130:131], s[54:55] op_sel_hi:[1,1,0]
	v_pk_mul_f32 v[102:103], v[102:103], v[122:123] op_sel_hi:[1,0]
	v_pk_fma_f32 v[124:125], v[124:125], v[126:127], 0.5 op_sel_hi:[1,1,0]
	s_nop 0
	v_pk_mul_f32 v[112:113], v[112:113], v[124:125]
	v_med3_f32 v124, v114, -4.0, 4.0
	v_med3_f32 v125, v115, -4.0, 4.0
	v_pk_mul_f32 v[126:127], v[124:125], v[124:125]
	s_nop 0
	v_pk_fma_f32 v[126:127], v[126:127], s[72:73], -1.0 op_sel_hi:[1,0,0]
	s_nop 0
	v_pk_fma_f32 v[130:131], v[126:127], s[74:75], v[128:129] op_sel_hi:[1,0,0]
	s_nop 0
	v_pk_fma_f32 v[130:131], v[126:127], v[130:131], s[2:3] op_sel_hi:[1,1,0]
	s_nop 0
	v_pk_fma_f32 v[130:131], v[126:127], v[130:131], s[28:29] op_sel_hi:[1,1,0]
	s_nop 0
	v_pk_fma_f32 v[130:131], v[126:127], v[130:131], s[30:31] op_sel_hi:[1,1,0]
	s_nop 0
	v_pk_fma_f32 v[130:131], v[126:127], v[130:131], s[48:49] op_sel_hi:[1,1,0]
	s_nop 0
	v_pk_fma_f32 v[130:131], v[126:127], v[130:131], s[50:51] op_sel_hi:[1,1,0]
	s_nop 0
	v_pk_fma_f32 v[130:131], v[126:127], v[130:131], s[52:53] op_sel_hi:[1,1,0]
	s_nop 0
	v_pk_fma_f32 v[126:127], v[126:127], v[130:131], s[54:55] op_sel_hi:[1,1,0]
	s_nop 0
	v_pk_fma_f32 v[124:125], v[124:125], v[126:127], 0.5 op_sel_hi:[1,1,0]
	s_nop 0
	v_pk_mul_f32 v[114:115], v[114:115], v[124:125]
	v_rcp_f32_e32 v124, v3
	v_mul_f32_e32 v3, 0xbfb8aa3b, v109
	v_exp_f32_e32 v3, v3
	s_nop 0
	v_add_f32_e32 v3, 1.0, v3
	v_rcp_f32_e32 v125, v3
	v_mul_f32_e32 v3, 0xbfb8aa3b, v110
	v_exp_f32_e32 v3, v3
	v_pk_mul_f32 v[124:125], v[108:109], v[124:125]
	v_add_f32_e32 v3, 1.0, v3
	v_rcp_f32_e32 v126, v3
	v_mul_f32_e32 v3, 0xbfb8aa3b, v111
	v_exp_f32_e32 v3, v3
	s_nop 0
	v_add_f32_e32 v3, 1.0, v3
	v_rcp_f32_e32 v127, v3
	v_mul_f32_e32 v3, 0xbfb8aa3b, v100
	v_exp_f32_e32 v3, v3
	v_pk_mul_f32 v[108:109], v[110:111], v[126:127]
	v_pk_mul_f32 v[110:111], v[124:125], v[112:113]
	v_med3_f32 v112, v104, -4.0, 4.0
	v_med3_f32 v113, v105, -4.0, 4.0
	v_pk_mul_f32 v[108:109], v[108:109], v[114:115]
	v_pk_mul_f32 v[114:115], v[112:113], v[112:113]
	v_add_f32_e32 v3, 1.0, v3
	v_pk_fma_f32 v[114:115], v[114:115], s[72:73], -1.0 op_sel_hi:[1,0,0]
	s_nop 0
	v_pk_fma_f32 v[124:125], v[114:115], s[74:75], v[128:129] op_sel_hi:[1,0,0]
	s_nop 0
	v_pk_fma_f32 v[124:125], v[114:115], v[124:125], s[2:3] op_sel_hi:[1,1,0]
	s_nop 0
	v_pk_fma_f32 v[124:125], v[114:115], v[124:125], s[28:29] op_sel_hi:[1,1,0]
	s_nop 0
	v_pk_fma_f32 v[124:125], v[114:115], v[124:125], s[30:31] op_sel_hi:[1,1,0]
	s_nop 0
	v_pk_fma_f32 v[124:125], v[114:115], v[124:125], s[48:49] op_sel_hi:[1,1,0]
	s_nop 0
	v_pk_fma_f32 v[124:125], v[114:115], v[124:125], s[50:51] op_sel_hi:[1,1,0]
	s_nop 0
	v_pk_fma_f32 v[124:125], v[114:115], v[124:125], s[52:53] op_sel_hi:[1,1,0]
	s_nop 0
	v_pk_fma_f32 v[114:115], v[114:115], v[124:125], s[54:55] op_sel_hi:[1,1,0]
	s_nop 0
	v_pk_fma_f32 v[112:113], v[112:113], v[114:115], 0.5 op_sel_hi:[1,1,0]
	s_nop 0
	v_pk_mul_f32 v[104:105], v[104:105], v[112:113]
	v_med3_f32 v112, v106, -4.0, 4.0
	v_med3_f32 v113, v107, -4.0, 4.0
	v_pk_mul_f32 v[114:115], v[112:113], v[112:113]
	s_nop 0
	v_pk_fma_f32 v[114:115], v[114:115], s[72:73], -1.0 op_sel_hi:[1,0,0]
	s_nop 0
	v_pk_fma_f32 v[124:125], v[114:115], s[74:75], v[128:129] op_sel_hi:[1,0,0]
	s_nop 0
	v_pk_fma_f32 v[124:125], v[114:115], v[124:125], s[2:3] op_sel_hi:[1,1,0]
	s_nop 0
	v_pk_fma_f32 v[124:125], v[114:115], v[124:125], s[28:29] op_sel_hi:[1,1,0]
	s_nop 0
	v_pk_fma_f32 v[124:125], v[114:115], v[124:125], s[30:31] op_sel_hi:[1,1,0]
	s_nop 0
	v_pk_fma_f32 v[124:125], v[114:115], v[124:125], s[48:49] op_sel_hi:[1,1,0]
	s_nop 0
	v_pk_fma_f32 v[124:125], v[114:115], v[124:125], s[50:51] op_sel_hi:[1,1,0]
	s_nop 0
	v_pk_fma_f32 v[124:125], v[114:115], v[124:125], s[52:53] op_sel_hi:[1,1,0]
	s_nop 0
	v_pk_fma_f32 v[114:115], v[114:115], v[124:125], s[54:55] op_sel_hi:[1,1,0]
	s_nop 0
	v_pk_fma_f32 v[112:113], v[112:113], v[114:115], 0.5 op_sel_hi:[1,1,0]
	s_nop 0
	v_pk_mul_f32 v[106:107], v[106:107], v[112:113]
	v_rcp_f32_e32 v112, v3
	v_mul_f32_e32 v3, 0xbfb8aa3b, v101
	v_exp_f32_e32 v3, v3
	s_nop 0
	v_add_f32_e32 v3, 1.0, v3
	v_rcp_f32_e32 v113, v3
	v_mul_f32_e32 v3, 0xbfb8aa3b, v102
	v_exp_f32_e32 v3, v3
	v_pk_mul_f32 v[100:101], v[100:101], v[112:113]
	v_add_f32_e32 v3, 1.0, v3
	v_rcp_f32_e32 v114, v3
	v_mul_f32_e32 v3, 0xbfb8aa3b, v103
	v_exp_f32_e32 v3, v3
	s_nop 0
	v_add_f32_e32 v3, 1.0, v3
	v_rcp_f32_e32 v115, v3
	s_nop 0
	v_pk_mul_f32 v[102:103], v[102:103], v[114:115]
	s_nop 0
	v_pk_mul_f32 v[106:107], v[102:103], v[106:107]
	v_pk_mul_f32 v[102:103], v[100:101], v[104:105]
	v_lshlrev_b64 v[104:105], 12, v[120:121]
	v_lshl_add_u64 v[104:105], s[10:11], 0, v[104:105]
	v_cvt_pk_bf16_f32 v100, v110, v111
	v_cvt_pk_bf16_f32 v101, v108, v109
	v_cvt_pk_bf16_f32 v102, v102, v103
	v_cvt_pk_bf16_f32 v103, v106, v107
	v_lshl_add_u64 v[104:105], v[104:105], 0, v[118:119]
	global_store_dwordx4 v[104:105], v[100:103], off
	s_nop 1
	v_or_b32_e32 v100, 32, v142
	v_ashrrev_i32_e32 v101, 31, v100
	v_lshl_add_u64 v[102:103], v[100:101], 2, s[16:17]
	s_nop 1
	v_mov_b32_e32 v102, v202
	v_pk_mul_f32 v[96:97], v[96:97], v[102:103] op_sel_hi:[1,0]
	s_nop 0
	v_med3_f32 v104, v96, -4.0, 4.0
	v_med3_f32 v105, v97, -4.0, 4.0
	v_pk_mul_f32 v[106:107], v[104:105], v[104:105]
	v_pk_mul_f32 v[98:99], v[98:99], v[102:103] op_sel_hi:[1,0]
	v_pk_fma_f32 v[106:107], v[106:107], s[72:73], -1.0 op_sel_hi:[1,0,0]
	v_pk_mul_f32 v[92:93], v[92:93], v[102:103] op_sel_hi:[1,0]
	v_pk_fma_f32 v[108:109], v[106:107], s[74:75], v[128:129] op_sel_hi:[1,0,0]
	v_mul_f32_e32 v3, 0xbfb8aa3b, v92
	v_pk_fma_f32 v[108:109], v[106:107], v[108:109], s[2:3] op_sel_hi:[1,1,0]
	v_exp_f32_e32 v3, v3
	v_pk_fma_f32 v[108:109], v[106:107], v[108:109], s[28:29] op_sel_hi:[1,1,0]
	v_pk_mul_f32 v[94:95], v[94:95], v[102:103] op_sel_hi:[1,0]
	v_pk_fma_f32 v[108:109], v[106:107], v[108:109], s[30:31] op_sel_hi:[1,1,0]
	v_add_f32_e32 v3, 1.0, v3
	v_pk_fma_f32 v[108:109], v[106:107], v[108:109], s[48:49] op_sel_hi:[1,1,0]
	v_pk_mul_f32 v[88:89], v[88:89], v[102:103] op_sel_hi:[1,0]
	v_pk_fma_f32 v[108:109], v[106:107], v[108:109], s[50:51] op_sel_hi:[1,1,0]
	v_pk_mul_f32 v[90:91], v[90:91], v[102:103] op_sel_hi:[1,0]
	v_pk_fma_f32 v[108:109], v[106:107], v[108:109], s[52:53] op_sel_hi:[1,1,0]
	v_pk_mul_f32 v[84:85], v[84:85], v[102:103] op_sel_hi:[1,0]
	v_pk_fma_f32 v[106:107], v[106:107], v[108:109], s[54:55] op_sel_hi:[1,1,0]
	v_pk_mul_f32 v[86:87], v[86:87], v[102:103] op_sel_hi:[1,0]
	v_pk_fma_f32 v[104:105], v[104:105], v[106:107], 0.5 op_sel_hi:[1,1,0]
	s_nop 0
	v_pk_mul_f32 v[96:97], v[96:97], v[104:105]
	v_med3_f32 v104, v98, -4.0, 4.0
	v_med3_f32 v105, v99, -4.0, 4.0
	v_pk_mul_f32 v[106:107], v[104:105], v[104:105]
	s_nop 0
	v_pk_fma_f32 v[106:107], v[106:107], s[72:73], -1.0 op_sel_hi:[1,0,0]
	s_nop 0
	v_pk_fma_f32 v[108:109], v[106:107], s[74:75], v[128:129] op_sel_hi:[1,0,0]
	s_nop 0
	v_pk_fma_f32 v[108:109], v[106:107], v[108:109], s[2:3] op_sel_hi:[1,1,0]
	s_nop 0
	v_pk_fma_f32 v[108:109], v[106:107], v[108:109], s[28:29] op_sel_hi:[1,1,0]
	s_nop 0
	v_pk_fma_f32 v[108:109], v[106:107], v[108:109], s[30:31] op_sel_hi:[1,1,0]
	s_nop 0
	v_pk_fma_f32 v[108:109], v[106:107], v[108:109], s[48:49] op_sel_hi:[1,1,0]
	s_nop 0
	v_pk_fma_f32 v[108:109], v[106:107], v[108:109], s[50:51] op_sel_hi:[1,1,0]
	s_nop 0
	v_pk_fma_f32 v[108:109], v[106:107], v[108:109], s[52:53] op_sel_hi:[1,1,0]
	s_nop 0
	v_pk_fma_f32 v[106:107], v[106:107], v[108:109], s[54:55] op_sel_hi:[1,1,0]
	s_nop 0
	v_pk_fma_f32 v[104:105], v[104:105], v[106:107], 0.5 op_sel_hi:[1,1,0]
	s_nop 0
	v_pk_mul_f32 v[98:99], v[98:99], v[104:105]
	v_rcp_f32_e32 v104, v3
	v_mul_f32_e32 v3, 0xbfb8aa3b, v93
	v_exp_f32_e32 v3, v3
	s_nop 0
	v_add_f32_e32 v3, 1.0, v3
	v_rcp_f32_e32 v105, v3
	v_mul_f32_e32 v3, 0xbfb8aa3b, v94
	v_exp_f32_e32 v3, v3
	v_pk_mul_f32 v[92:93], v[92:93], v[104:105]
	s_nop 0
	v_pk_mul_f32 v[92:93], v[92:93], v[96:97]
	v_add_f32_e32 v3, 1.0, v3
	v_rcp_f32_e32 v106, v3
	v_mul_f32_e32 v3, 0xbfb8aa3b, v95
	v_exp_f32_e32 v3, v3
	v_med3_f32 v96, v88, -4.0, 4.0
	v_med3_f32 v97, v89, -4.0, 4.0
	v_add_f32_e32 v3, 1.0, v3
	v_rcp_f32_e32 v107, v3
	v_mul_f32_e32 v3, 0xbfb8aa3b, v84
	v_exp_f32_e32 v3, v3
	v_pk_mul_f32 v[94:95], v[94:95], v[106:107]
	s_nop 0
	v_pk_mul_f32 v[94:95], v[94:95], v[98:99]
	v_pk_mul_f32 v[98:99], v[96:97], v[96:97]
	v_add_f32_e32 v3, 1.0, v3
	v_pk_fma_f32 v[98:99], v[98:99], s[72:73], -1.0 op_sel_hi:[1,0,0]
	s_nop 0
	v_pk_fma_f32 v[104:105], v[98:99], s[74:75], v[128:129] op_sel_hi:[1,0,0]
	s_nop 0
	v_pk_fma_f32 v[104:105], v[98:99], v[104:105], s[2:3] op_sel_hi:[1,1,0]
	s_nop 0
	v_pk_fma_f32 v[104:105], v[98:99], v[104:105], s[28:29] op_sel_hi:[1,1,0]
	s_nop 0
	v_pk_fma_f32 v[104:105], v[98:99], v[104:105], s[30:31] op_sel_hi:[1,1,0]
	s_nop 0
	v_pk_fma_f32 v[104:105], v[98:99], v[104:105], s[48:49] op_sel_hi:[1,1,0]
	s_nop 0
	v_pk_fma_f32 v[104:105], v[98:99], v[104:105], s[50:51] op_sel_hi:[1,1,0]
	s_nop 0
	v_pk_fma_f32 v[104:105], v[98:99], v[104:105], s[52:53] op_sel_hi:[1,1,0]
	s_nop 0
	v_pk_fma_f32 v[98:99], v[98:99], v[104:105], s[54:55] op_sel_hi:[1,1,0]
	s_nop 0
	v_pk_fma_f32 v[96:97], v[96:97], v[98:99], 0.5 op_sel_hi:[1,1,0]
	s_nop 0
	v_pk_mul_f32 v[88:89], v[88:89], v[96:97]
	v_med3_f32 v96, v90, -4.0, 4.0
	v_med3_f32 v97, v91, -4.0, 4.0
	v_pk_mul_f32 v[98:99], v[96:97], v[96:97]
	s_nop 0
	v_pk_fma_f32 v[98:99], v[98:99], s[72:73], -1.0 op_sel_hi:[1,0,0]
	s_nop 0
	v_pk_fma_f32 v[104:105], v[98:99], s[74:75], v[128:129] op_sel_hi:[1,0,0]
	s_nop 0
	v_pk_fma_f32 v[104:105], v[98:99], v[104:105], s[2:3] op_sel_hi:[1,1,0]
	s_nop 0
	v_pk_fma_f32 v[104:105], v[98:99], v[104:105], s[28:29] op_sel_hi:[1,1,0]
	s_nop 0
	v_pk_fma_f32 v[104:105], v[98:99], v[104:105], s[30:31] op_sel_hi:[1,1,0]
	s_nop 0
	v_pk_fma_f32 v[104:105], v[98:99], v[104:105], s[48:49] op_sel_hi:[1,1,0]
	s_nop 0
	v_pk_fma_f32 v[104:105], v[98:99], v[104:105], s[50:51] op_sel_hi:[1,1,0]
	s_nop 0
	v_pk_fma_f32 v[104:105], v[98:99], v[104:105], s[52:53] op_sel_hi:[1,1,0]
	s_nop 0
	v_pk_fma_f32 v[98:99], v[98:99], v[104:105], s[54:55] op_sel_hi:[1,1,0]
	s_nop 0
	v_pk_fma_f32 v[96:97], v[96:97], v[98:99], 0.5 op_sel_hi:[1,1,0]
	s_nop 0
	v_pk_mul_f32 v[90:91], v[90:91], v[96:97]
	v_rcp_f32_e32 v96, v3
	v_mul_f32_e32 v3, 0xbfb8aa3b, v85
	v_exp_f32_e32 v3, v3
	s_nop 0
	v_add_f32_e32 v3, 1.0, v3
	v_rcp_f32_e32 v97, v3
	v_mul_f32_e32 v3, 0xbfb8aa3b, v86
	v_exp_f32_e32 v3, v3
	v_pk_mul_f32 v[84:85], v[84:85], v[96:97]
	v_add_f32_e32 v3, 1.0, v3
	v_rcp_f32_e32 v98, v3
	v_mul_f32_e32 v3, 0xbfb8aa3b, v87
	v_exp_f32_e32 v3, v3
	s_nop 0
	v_add_f32_e32 v3, 1.0, v3
	v_rcp_f32_e32 v99, v3
	s_nop 0
	v_pk_mul_f32 v[86:87], v[86:87], v[98:99]
	s_nop 0
	v_pk_mul_f32 v[90:91], v[86:87], v[90:91]
	v_pk_mul_f32 v[86:87], v[84:85], v[88:89]
	v_lshlrev_b64 v[88:89], 12, v[100:101]
	v_lshl_add_u64 v[88:89], s[10:11], 0, v[88:89]
	v_cvt_pk_bf16_f32 v84, v92, v93
	v_cvt_pk_bf16_f32 v85, v94, v95
	v_cvt_pk_bf16_f32 v86, v86, v87
	v_cvt_pk_bf16_f32 v87, v90, v91
	v_lshl_add_u64 v[88:89], v[88:89], 0, v[118:119]
	global_store_dwordx4 v[88:89], v[84:87], off
	s_nop 1
	v_or_b32_e32 v84, 48, v142
	v_ashrrev_i32_e32 v85, 31, v84
	v_lshl_add_u64 v[86:87], v[84:85], 2, s[16:17]
	s_nop 1
	v_mov_b32_e32 v86, v203
	v_pk_mul_f32 v[80:81], v[80:81], v[86:87] op_sel_hi:[1,0]
	s_nop 0
	v_med3_f32 v88, v80, -4.0, 4.0
	v_med3_f32 v89, v81, -4.0, 4.0
	v_pk_mul_f32 v[90:91], v[88:89], v[88:89]
	v_pk_mul_f32 v[82:83], v[82:83], v[86:87] op_sel_hi:[1,0]
	v_pk_fma_f32 v[90:91], v[90:91], s[72:73], -1.0 op_sel_hi:[1,0,0]
	v_pk_mul_f32 v[76:77], v[76:77], v[86:87] op_sel_hi:[1,0]
	v_pk_fma_f32 v[92:93], v[90:91], s[74:75], v[128:129] op_sel_hi:[1,0,0]
	v_mul_f32_e32 v3, 0xbfb8aa3b, v76
	v_pk_fma_f32 v[92:93], v[90:91], v[92:93], s[2:3] op_sel_hi:[1,1,0]
	v_exp_f32_e32 v3, v3
	v_pk_fma_f32 v[92:93], v[90:91], v[92:93], s[28:29] op_sel_hi:[1,1,0]
	v_pk_mul_f32 v[78:79], v[78:79], v[86:87] op_sel_hi:[1,0]
	v_pk_fma_f32 v[92:93], v[90:91], v[92:93], s[30:31] op_sel_hi:[1,1,0]
	v_add_f32_e32 v3, 1.0, v3
	v_pk_fma_f32 v[92:93], v[90:91], v[92:93], s[48:49] op_sel_hi:[1,1,0]
	v_pk_mul_f32 v[72:73], v[72:73], v[86:87] op_sel_hi:[1,0]
	v_pk_fma_f32 v[92:93], v[90:91], v[92:93], s[50:51] op_sel_hi:[1,1,0]
	v_pk_mul_f32 v[74:75], v[74:75], v[86:87] op_sel_hi:[1,0]
	v_pk_fma_f32 v[92:93], v[90:91], v[92:93], s[52:53] op_sel_hi:[1,1,0]
	v_pk_mul_f32 v[68:69], v[68:69], v[86:87] op_sel_hi:[1,0]
	v_pk_fma_f32 v[90:91], v[90:91], v[92:93], s[54:55] op_sel_hi:[1,1,0]
	v_pk_mul_f32 v[70:71], v[70:71], v[86:87] op_sel_hi:[1,0]
	v_pk_fma_f32 v[88:89], v[88:89], v[90:91], 0.5 op_sel_hi:[1,1,0]
	s_nop 0
	v_pk_mul_f32 v[80:81], v[80:81], v[88:89]
	v_med3_f32 v88, v82, -4.0, 4.0
	v_med3_f32 v89, v83, -4.0, 4.0
	v_pk_mul_f32 v[90:91], v[88:89], v[88:89]
	s_nop 0
	v_pk_fma_f32 v[90:91], v[90:91], s[72:73], -1.0 op_sel_hi:[1,0,0]
	s_nop 0
	v_pk_fma_f32 v[92:93], v[90:91], s[74:75], v[128:129] op_sel_hi:[1,0,0]
	s_nop 0
	v_pk_fma_f32 v[92:93], v[90:91], v[92:93], s[2:3] op_sel_hi:[1,1,0]
	s_nop 0
	v_pk_fma_f32 v[92:93], v[90:91], v[92:93], s[28:29] op_sel_hi:[1,1,0]
	s_nop 0
	v_pk_fma_f32 v[92:93], v[90:91], v[92:93], s[30:31] op_sel_hi:[1,1,0]
	s_nop 0
	v_pk_fma_f32 v[92:93], v[90:91], v[92:93], s[48:49] op_sel_hi:[1,1,0]
	s_nop 0
	v_pk_fma_f32 v[92:93], v[90:91], v[92:93], s[50:51] op_sel_hi:[1,1,0]
	s_nop 0
	v_pk_fma_f32 v[92:93], v[90:91], v[92:93], s[52:53] op_sel_hi:[1,1,0]
	s_nop 0
	v_pk_fma_f32 v[90:91], v[90:91], v[92:93], s[54:55] op_sel_hi:[1,1,0]
	s_nop 0
	v_pk_fma_f32 v[88:89], v[88:89], v[90:91], 0.5 op_sel_hi:[1,1,0]
	s_nop 0
	v_pk_mul_f32 v[82:83], v[82:83], v[88:89]
	v_rcp_f32_e32 v88, v3
	v_mul_f32_e32 v3, 0xbfb8aa3b, v77
	v_exp_f32_e32 v3, v3
	s_nop 0
	v_add_f32_e32 v3, 1.0, v3
	v_rcp_f32_e32 v89, v3
	v_mul_f32_e32 v3, 0xbfb8aa3b, v78
	v_exp_f32_e32 v3, v3
	v_pk_mul_f32 v[76:77], v[76:77], v[88:89]
	s_nop 0
	v_pk_mul_f32 v[76:77], v[76:77], v[80:81]
	v_add_f32_e32 v3, 1.0, v3
	v_rcp_f32_e32 v90, v3
	v_mul_f32_e32 v3, 0xbfb8aa3b, v79
	v_exp_f32_e32 v3, v3
	v_med3_f32 v80, v72, -4.0, 4.0
	v_med3_f32 v81, v73, -4.0, 4.0
	v_add_f32_e32 v3, 1.0, v3
	v_rcp_f32_e32 v91, v3
	v_mul_f32_e32 v3, 0xbfb8aa3b, v68
	v_exp_f32_e32 v3, v3
	v_pk_mul_f32 v[78:79], v[78:79], v[90:91]
	s_nop 0
	v_pk_mul_f32 v[78:79], v[78:79], v[82:83]
	v_pk_mul_f32 v[82:83], v[80:81], v[80:81]
	v_add_f32_e32 v3, 1.0, v3
	v_pk_fma_f32 v[82:83], v[82:83], s[72:73], -1.0 op_sel_hi:[1,0,0]
	s_nop 0
	v_pk_fma_f32 v[88:89], v[82:83], s[74:75], v[128:129] op_sel_hi:[1,0,0]
	s_nop 0
	v_pk_fma_f32 v[88:89], v[82:83], v[88:89], s[2:3] op_sel_hi:[1,1,0]
	s_nop 0
	v_pk_fma_f32 v[88:89], v[82:83], v[88:89], s[28:29] op_sel_hi:[1,1,0]
	s_nop 0
	v_pk_fma_f32 v[88:89], v[82:83], v[88:89], s[30:31] op_sel_hi:[1,1,0]
	s_nop 0
	v_pk_fma_f32 v[88:89], v[82:83], v[88:89], s[48:49] op_sel_hi:[1,1,0]
	s_nop 0
	v_pk_fma_f32 v[88:89], v[82:83], v[88:89], s[50:51] op_sel_hi:[1,1,0]
	s_nop 0
	v_pk_fma_f32 v[88:89], v[82:83], v[88:89], s[52:53] op_sel_hi:[1,1,0]
	s_nop 0
	v_pk_fma_f32 v[82:83], v[82:83], v[88:89], s[54:55] op_sel_hi:[1,1,0]
	s_nop 0
	v_pk_fma_f32 v[80:81], v[80:81], v[82:83], 0.5 op_sel_hi:[1,1,0]
	s_nop 0
	v_pk_mul_f32 v[72:73], v[72:73], v[80:81]
	v_med3_f32 v80, v74, -4.0, 4.0
	v_med3_f32 v81, v75, -4.0, 4.0
	v_pk_mul_f32 v[82:83], v[80:81], v[80:81]
	s_nop 0
	v_pk_fma_f32 v[82:83], v[82:83], s[72:73], -1.0 op_sel_hi:[1,0,0]
	s_nop 0
	v_pk_fma_f32 v[88:89], v[82:83], s[74:75], v[128:129] op_sel_hi:[1,0,0]
	s_nop 0
	v_pk_fma_f32 v[88:89], v[82:83], v[88:89], s[2:3] op_sel_hi:[1,1,0]
	s_nop 0
	v_pk_fma_f32 v[88:89], v[82:83], v[88:89], s[28:29] op_sel_hi:[1,1,0]
	s_nop 0
	v_pk_fma_f32 v[88:89], v[82:83], v[88:89], s[30:31] op_sel_hi:[1,1,0]
	s_nop 0
	v_pk_fma_f32 v[88:89], v[82:83], v[88:89], s[48:49] op_sel_hi:[1,1,0]
	s_nop 0
	v_pk_fma_f32 v[88:89], v[82:83], v[88:89], s[50:51] op_sel_hi:[1,1,0]
	s_nop 0
	v_pk_fma_f32 v[88:89], v[82:83], v[88:89], s[52:53] op_sel_hi:[1,1,0]
	s_nop 0
	v_pk_fma_f32 v[82:83], v[82:83], v[88:89], s[54:55] op_sel_hi:[1,1,0]
	s_nop 0
	v_pk_fma_f32 v[80:81], v[80:81], v[82:83], 0.5 op_sel_hi:[1,1,0]
	s_nop 0
	v_pk_mul_f32 v[74:75], v[74:75], v[80:81]
	v_rcp_f32_e32 v80, v3
	v_mul_f32_e32 v3, 0xbfb8aa3b, v69
	v_exp_f32_e32 v3, v3
	s_nop 0
	v_add_f32_e32 v3, 1.0, v3
	v_rcp_f32_e32 v81, v3
	v_mul_f32_e32 v3, 0xbfb8aa3b, v70
	v_exp_f32_e32 v3, v3
	v_pk_mul_f32 v[68:69], v[68:69], v[80:81]
	v_add_f32_e32 v3, 1.0, v3
	v_rcp_f32_e32 v82, v3
	v_mul_f32_e32 v3, 0xbfb8aa3b, v71
	v_exp_f32_e32 v3, v3
	s_nop 0
	v_add_f32_e32 v3, 1.0, v3
	v_rcp_f32_e32 v83, v3
	s_nop 0
	v_pk_mul_f32 v[70:71], v[70:71], v[82:83]
	s_nop 0
	v_pk_mul_f32 v[74:75], v[70:71], v[74:75]
	v_pk_mul_f32 v[70:71], v[68:69], v[72:73]
	v_lshlrev_b64 v[72:73], 12, v[84:85]
	v_lshl_add_u64 v[72:73], s[10:11], 0, v[72:73]
	v_cvt_pk_bf16_f32 v68, v76, v77
	v_cvt_pk_bf16_f32 v69, v78, v79
	v_cvt_pk_bf16_f32 v70, v70, v71
	v_cvt_pk_bf16_f32 v71, v74, v75
	v_lshl_add_u64 v[72:73], v[72:73], 0, v[118:119]
	global_store_dwordx4 v[72:73], v[68:71], off
	s_nop 1
	v_mov_b32_e32 v68, v204
	v_pk_mul_f32 v[64:65], v[64:65], v[68:69] op_sel_hi:[1,0]
	s_nop 0
	v_med3_f32 v70, v64, -4.0, 4.0
	v_med3_f32 v71, v65, -4.0, 4.0
	v_pk_mul_f32 v[72:73], v[70:71], v[70:71]
	v_pk_mul_f32 v[66:67], v[66:67], v[68:69] op_sel_hi:[1,0]
	v_pk_fma_f32 v[72:73], v[72:73], s[72:73], -1.0 op_sel_hi:[1,0,0]
	v_pk_mul_f32 v[60:61], v[60:61], v[68:69] op_sel_hi:[1,0]
	v_pk_fma_f32 v[74:75], v[72:73], s[74:75], v[128:129] op_sel_hi:[1,0,0]
	v_mul_f32_e32 v3, 0xbfb8aa3b, v60
	v_pk_fma_f32 v[74:75], v[72:73], v[74:75], s[2:3] op_sel_hi:[1,1,0]
	v_exp_f32_e32 v3, v3
	v_pk_fma_f32 v[74:75], v[72:73], v[74:75], s[28:29] op_sel_hi:[1,1,0]
	v_pk_mul_f32 v[62:63], v[62:63], v[68:69] op_sel_hi:[1,0]
	v_pk_fma_f32 v[74:75], v[72:73], v[74:75], s[30:31] op_sel_hi:[1,1,0]
	v_add_f32_e32 v3, 1.0, v3
	v_pk_fma_f32 v[74:75], v[72:73], v[74:75], s[48:49] op_sel_hi:[1,1,0]
	v_pk_mul_f32 v[56:57], v[56:57], v[68:69] op_sel_hi:[1,0]
	v_pk_fma_f32 v[74:75], v[72:73], v[74:75], s[50:51] op_sel_hi:[1,1,0]
	v_pk_mul_f32 v[58:59], v[58:59], v[68:69] op_sel_hi:[1,0]
	v_pk_fma_f32 v[74:75], v[72:73], v[74:75], s[52:53] op_sel_hi:[1,1,0]
	v_pk_mul_f32 v[52:53], v[52:53], v[68:69] op_sel_hi:[1,0]
	v_pk_fma_f32 v[72:73], v[72:73], v[74:75], s[54:55] op_sel_hi:[1,1,0]
	v_pk_mul_f32 v[54:55], v[54:55], v[68:69] op_sel_hi:[1,0]
	v_pk_fma_f32 v[70:71], v[70:71], v[72:73], 0.5 op_sel_hi:[1,1,0]
	s_nop 0
	v_pk_mul_f32 v[64:65], v[64:65], v[70:71]
	v_med3_f32 v70, v66, -4.0, 4.0
	v_med3_f32 v71, v67, -4.0, 4.0
	v_pk_mul_f32 v[72:73], v[70:71], v[70:71]
	s_nop 0
	v_pk_fma_f32 v[72:73], v[72:73], s[72:73], -1.0 op_sel_hi:[1,0,0]
	s_nop 0
	v_pk_fma_f32 v[74:75], v[72:73], s[74:75], v[128:129] op_sel_hi:[1,0,0]
	s_nop 0
	v_pk_fma_f32 v[74:75], v[72:73], v[74:75], s[2:3] op_sel_hi:[1,1,0]
	s_nop 0
	v_pk_fma_f32 v[74:75], v[72:73], v[74:75], s[28:29] op_sel_hi:[1,1,0]
	s_nop 0
	v_pk_fma_f32 v[74:75], v[72:73], v[74:75], s[30:31] op_sel_hi:[1,1,0]
	s_nop 0
	v_pk_fma_f32 v[74:75], v[72:73], v[74:75], s[48:49] op_sel_hi:[1,1,0]
	s_nop 0
	v_pk_fma_f32 v[74:75], v[72:73], v[74:75], s[50:51] op_sel_hi:[1,1,0]
	s_nop 0
	v_pk_fma_f32 v[74:75], v[72:73], v[74:75], s[52:53] op_sel_hi:[1,1,0]
	s_nop 0
	v_pk_fma_f32 v[72:73], v[72:73], v[74:75], s[54:55] op_sel_hi:[1,1,0]
	s_nop 0
	v_pk_fma_f32 v[70:71], v[70:71], v[72:73], 0.5 op_sel_hi:[1,1,0]
	s_nop 0
	v_pk_mul_f32 v[66:67], v[66:67], v[70:71]
	v_rcp_f32_e32 v70, v3
	v_mul_f32_e32 v3, 0xbfb8aa3b, v61
	v_exp_f32_e32 v3, v3
	s_nop 0
	v_add_f32_e32 v3, 1.0, v3
	v_rcp_f32_e32 v71, v3
	v_mul_f32_e32 v3, 0xbfb8aa3b, v62
	v_exp_f32_e32 v3, v3
	v_pk_mul_f32 v[60:61], v[60:61], v[70:71]
	s_nop 0
	v_pk_mul_f32 v[60:61], v[60:61], v[64:65]
	v_add_f32_e32 v3, 1.0, v3
	v_rcp_f32_e32 v72, v3
	v_mul_f32_e32 v3, 0xbfb8aa3b, v63
	v_exp_f32_e32 v3, v3
	v_med3_f32 v64, v56, -4.0, 4.0
	v_med3_f32 v65, v57, -4.0, 4.0
	v_add_f32_e32 v3, 1.0, v3
	v_rcp_f32_e32 v73, v3
	v_mul_f32_e32 v3, 0xbfb8aa3b, v52
	v_exp_f32_e32 v3, v3
	v_pk_mul_f32 v[62:63], v[62:63], v[72:73]
	s_nop 0
	v_pk_mul_f32 v[62:63], v[62:63], v[66:67]
	v_pk_mul_f32 v[66:67], v[64:65], v[64:65]
	v_add_f32_e32 v3, 1.0, v3
	v_pk_fma_f32 v[66:67], v[66:67], s[72:73], -1.0 op_sel_hi:[1,0,0]
	s_nop 0
	v_pk_fma_f32 v[70:71], v[66:67], s[74:75], v[128:129] op_sel_hi:[1,0,0]
	s_nop 0
	v_pk_fma_f32 v[70:71], v[66:67], v[70:71], s[2:3] op_sel_hi:[1,1,0]
	s_nop 0
	v_pk_fma_f32 v[70:71], v[66:67], v[70:71], s[28:29] op_sel_hi:[1,1,0]
	s_nop 0
	v_pk_fma_f32 v[70:71], v[66:67], v[70:71], s[30:31] op_sel_hi:[1,1,0]
	s_nop 0
	v_pk_fma_f32 v[70:71], v[66:67], v[70:71], s[48:49] op_sel_hi:[1,1,0]
	s_nop 0
	v_pk_fma_f32 v[70:71], v[66:67], v[70:71], s[50:51] op_sel_hi:[1,1,0]
	s_nop 0
	v_pk_fma_f32 v[70:71], v[66:67], v[70:71], s[52:53] op_sel_hi:[1,1,0]
	s_nop 0
	v_pk_fma_f32 v[66:67], v[66:67], v[70:71], s[54:55] op_sel_hi:[1,1,0]
	s_nop 0
	v_pk_fma_f32 v[64:65], v[64:65], v[66:67], 0.5 op_sel_hi:[1,1,0]
	s_nop 0
	v_pk_mul_f32 v[56:57], v[56:57], v[64:65]
	v_med3_f32 v64, v58, -4.0, 4.0
	v_med3_f32 v65, v59, -4.0, 4.0
	v_pk_mul_f32 v[66:67], v[64:65], v[64:65]
	s_nop 0
	v_pk_fma_f32 v[66:67], v[66:67], s[72:73], -1.0 op_sel_hi:[1,0,0]
	s_nop 0
	v_pk_fma_f32 v[70:71], v[66:67], s[74:75], v[128:129] op_sel_hi:[1,0,0]
	s_nop 0
	v_pk_fma_f32 v[70:71], v[66:67], v[70:71], s[2:3] op_sel_hi:[1,1,0]
	s_nop 0
	v_pk_fma_f32 v[70:71], v[66:67], v[70:71], s[28:29] op_sel_hi:[1,1,0]
	s_nop 0
	v_pk_fma_f32 v[70:71], v[66:67], v[70:71], s[30:31] op_sel_hi:[1,1,0]
	s_nop 0
	v_pk_fma_f32 v[70:71], v[66:67], v[70:71], s[48:49] op_sel_hi:[1,1,0]
	s_nop 0
	v_pk_fma_f32 v[70:71], v[66:67], v[70:71], s[50:51] op_sel_hi:[1,1,0]
	s_nop 0
	v_pk_fma_f32 v[70:71], v[66:67], v[70:71], s[52:53] op_sel_hi:[1,1,0]
	s_nop 0
	v_pk_fma_f32 v[66:67], v[66:67], v[70:71], s[54:55] op_sel_hi:[1,1,0]
	s_nop 0
	v_pk_fma_f32 v[64:65], v[64:65], v[66:67], 0.5 op_sel_hi:[1,1,0]
	s_nop 0
	v_pk_mul_f32 v[58:59], v[58:59], v[64:65]
	v_rcp_f32_e32 v64, v3
	v_mul_f32_e32 v3, 0xbfb8aa3b, v53
	v_exp_f32_e32 v3, v3
	s_nop 0
	v_add_f32_e32 v3, 1.0, v3
	v_rcp_f32_e32 v65, v3
	v_mul_f32_e32 v3, 0xbfb8aa3b, v54
	v_exp_f32_e32 v3, v3
	v_pk_mul_f32 v[52:53], v[52:53], v[64:65]
	v_add_f32_e32 v3, 1.0, v3
	v_rcp_f32_e32 v66, v3
	v_mul_f32_e32 v3, 0xbfb8aa3b, v55
	v_exp_f32_e32 v3, v3
	s_nop 0
	v_add_f32_e32 v3, 1.0, v3
	v_rcp_f32_e32 v67, v3
	s_nop 0
	v_pk_mul_f32 v[54:55], v[54:55], v[66:67]
	s_nop 0
	v_pk_mul_f32 v[58:59], v[54:55], v[58:59]
	v_pk_mul_f32 v[54:55], v[52:53], v[56:57]
	v_add_co_u32_e32 v56, vcc, s0, v116
	v_cvt_pk_bf16_f32 v52, v60, v61
	v_cvt_pk_bf16_f32 v53, v62, v63
	v_cvt_pk_bf16_f32 v54, v54, v55
	v_cvt_pk_bf16_f32 v55, v58, v59
	v_addc_co_u32_e32 v57, vcc, 0, v117, vcc
	global_store_dwordx4 v[56:57], v[52:55], off
	s_nop 1
	v_mov_b32_e32 v52, v205
	s_mov_b32 s0, 0x90000
	v_pk_mul_f32 v[48:49], v[48:49], v[52:53] op_sel_hi:[1,0]
	s_nop 0
	v_med3_f32 v54, v48, -4.0, 4.0
	v_med3_f32 v55, v49, -4.0, 4.0
	v_pk_mul_f32 v[56:57], v[54:55], v[54:55]
	v_pk_mul_f32 v[50:51], v[50:51], v[52:53] op_sel_hi:[1,0]
	v_pk_fma_f32 v[56:57], v[56:57], s[72:73], -1.0 op_sel_hi:[1,0,0]
	v_pk_mul_f32 v[44:45], v[44:45], v[52:53] op_sel_hi:[1,0]
	v_pk_fma_f32 v[58:59], v[56:57], s[74:75], v[128:129] op_sel_hi:[1,0,0]
	v_mul_f32_e32 v3, 0xbfb8aa3b, v44
	v_pk_fma_f32 v[58:59], v[56:57], v[58:59], s[2:3] op_sel_hi:[1,1,0]
	v_exp_f32_e32 v3, v3
	v_pk_fma_f32 v[58:59], v[56:57], v[58:59], s[28:29] op_sel_hi:[1,1,0]
	v_pk_mul_f32 v[46:47], v[46:47], v[52:53] op_sel_hi:[1,0]
	v_pk_fma_f32 v[58:59], v[56:57], v[58:59], s[30:31] op_sel_hi:[1,1,0]
	v_add_f32_e32 v3, 1.0, v3
	v_pk_fma_f32 v[58:59], v[56:57], v[58:59], s[48:49] op_sel_hi:[1,1,0]
	v_pk_mul_f32 v[40:41], v[40:41], v[52:53] op_sel_hi:[1,0]
	v_pk_fma_f32 v[58:59], v[56:57], v[58:59], s[50:51] op_sel_hi:[1,1,0]
	v_pk_mul_f32 v[42:43], v[42:43], v[52:53] op_sel_hi:[1,0]
	v_pk_fma_f32 v[58:59], v[56:57], v[58:59], s[52:53] op_sel_hi:[1,1,0]
	v_pk_mul_f32 v[36:37], v[36:37], v[52:53] op_sel_hi:[1,0]
	v_pk_fma_f32 v[56:57], v[56:57], v[58:59], s[54:55] op_sel_hi:[1,1,0]
	v_pk_mul_f32 v[38:39], v[38:39], v[52:53] op_sel_hi:[1,0]
	v_pk_fma_f32 v[54:55], v[54:55], v[56:57], 0.5 op_sel_hi:[1,1,0]
	s_nop 0
	v_pk_mul_f32 v[48:49], v[48:49], v[54:55]
	v_med3_f32 v54, v50, -4.0, 4.0
	v_med3_f32 v55, v51, -4.0, 4.0
	v_pk_mul_f32 v[56:57], v[54:55], v[54:55]
	s_nop 0
	v_pk_fma_f32 v[56:57], v[56:57], s[72:73], -1.0 op_sel_hi:[1,0,0]
	s_nop 0
	v_pk_fma_f32 v[58:59], v[56:57], s[74:75], v[128:129] op_sel_hi:[1,0,0]
	s_nop 0
	v_pk_fma_f32 v[58:59], v[56:57], v[58:59], s[2:3] op_sel_hi:[1,1,0]
	s_nop 0
	v_pk_fma_f32 v[58:59], v[56:57], v[58:59], s[28:29] op_sel_hi:[1,1,0]
	s_nop 0
	v_pk_fma_f32 v[58:59], v[56:57], v[58:59], s[30:31] op_sel_hi:[1,1,0]
	s_nop 0
	v_pk_fma_f32 v[58:59], v[56:57], v[58:59], s[48:49] op_sel_hi:[1,1,0]
	s_nop 0
	v_pk_fma_f32 v[58:59], v[56:57], v[58:59], s[50:51] op_sel_hi:[1,1,0]
	s_nop 0
	v_pk_fma_f32 v[58:59], v[56:57], v[58:59], s[52:53] op_sel_hi:[1,1,0]
	s_nop 0
	v_pk_fma_f32 v[56:57], v[56:57], v[58:59], s[54:55] op_sel_hi:[1,1,0]
	s_nop 0
	v_pk_fma_f32 v[54:55], v[54:55], v[56:57], 0.5 op_sel_hi:[1,1,0]
	s_nop 0
	v_pk_mul_f32 v[50:51], v[50:51], v[54:55]
	v_rcp_f32_e32 v54, v3
	v_mul_f32_e32 v3, 0xbfb8aa3b, v45
	v_exp_f32_e32 v3, v3
	s_nop 0
	v_add_f32_e32 v3, 1.0, v3
	v_rcp_f32_e32 v55, v3
	v_mul_f32_e32 v3, 0xbfb8aa3b, v46
	v_exp_f32_e32 v3, v3
	v_pk_mul_f32 v[44:45], v[44:45], v[54:55]
	s_nop 0
	v_pk_mul_f32 v[44:45], v[44:45], v[48:49]
	v_add_f32_e32 v3, 1.0, v3
	v_rcp_f32_e32 v56, v3
	v_mul_f32_e32 v3, 0xbfb8aa3b, v47
	v_exp_f32_e32 v3, v3
	v_med3_f32 v48, v40, -4.0, 4.0
	v_med3_f32 v49, v41, -4.0, 4.0
	v_add_f32_e32 v3, 1.0, v3
	v_rcp_f32_e32 v57, v3
	v_mul_f32_e32 v3, 0xbfb8aa3b, v36
	v_exp_f32_e32 v3, v3
	v_pk_mul_f32 v[46:47], v[46:47], v[56:57]
	s_nop 0
	v_pk_mul_f32 v[46:47], v[46:47], v[50:51]
	v_pk_mul_f32 v[50:51], v[48:49], v[48:49]
	v_add_f32_e32 v3, 1.0, v3
	v_pk_fma_f32 v[50:51], v[50:51], s[72:73], -1.0 op_sel_hi:[1,0,0]
	s_nop 0
	v_pk_fma_f32 v[54:55], v[50:51], s[74:75], v[128:129] op_sel_hi:[1,0,0]
	s_nop 0
	v_pk_fma_f32 v[54:55], v[50:51], v[54:55], s[2:3] op_sel_hi:[1,1,0]
	s_nop 0
	v_pk_fma_f32 v[54:55], v[50:51], v[54:55], s[28:29] op_sel_hi:[1,1,0]
	s_nop 0
	v_pk_fma_f32 v[54:55], v[50:51], v[54:55], s[30:31] op_sel_hi:[1,1,0]
	s_nop 0
	v_pk_fma_f32 v[54:55], v[50:51], v[54:55], s[48:49] op_sel_hi:[1,1,0]
	s_nop 0
	v_pk_fma_f32 v[54:55], v[50:51], v[54:55], s[50:51] op_sel_hi:[1,1,0]
	s_nop 0
	v_pk_fma_f32 v[54:55], v[50:51], v[54:55], s[52:53] op_sel_hi:[1,1,0]
	s_nop 0
	v_pk_fma_f32 v[50:51], v[50:51], v[54:55], s[54:55] op_sel_hi:[1,1,0]
	s_nop 0
	v_pk_fma_f32 v[48:49], v[48:49], v[50:51], 0.5 op_sel_hi:[1,1,0]
	s_nop 0
	v_pk_mul_f32 v[40:41], v[40:41], v[48:49]
	v_med3_f32 v48, v42, -4.0, 4.0
	v_med3_f32 v49, v43, -4.0, 4.0
	v_pk_mul_f32 v[50:51], v[48:49], v[48:49]
	s_nop 0
	v_pk_fma_f32 v[50:51], v[50:51], s[72:73], -1.0 op_sel_hi:[1,0,0]
	s_nop 0
	v_pk_fma_f32 v[54:55], v[50:51], s[74:75], v[128:129] op_sel_hi:[1,0,0]
	s_nop 0
	v_pk_fma_f32 v[54:55], v[50:51], v[54:55], s[2:3] op_sel_hi:[1,1,0]
	s_nop 0
	v_pk_fma_f32 v[54:55], v[50:51], v[54:55], s[28:29] op_sel_hi:[1,1,0]
	s_nop 0
	v_pk_fma_f32 v[54:55], v[50:51], v[54:55], s[30:31] op_sel_hi:[1,1,0]
	s_nop 0
	v_pk_fma_f32 v[54:55], v[50:51], v[54:55], s[48:49] op_sel_hi:[1,1,0]
	s_nop 0
	v_pk_fma_f32 v[54:55], v[50:51], v[54:55], s[50:51] op_sel_hi:[1,1,0]
	s_nop 0
	v_pk_fma_f32 v[54:55], v[50:51], v[54:55], s[52:53] op_sel_hi:[1,1,0]
	s_nop 0
	v_pk_fma_f32 v[50:51], v[50:51], v[54:55], s[54:55] op_sel_hi:[1,1,0]
	s_nop 0
	v_pk_fma_f32 v[48:49], v[48:49], v[50:51], 0.5 op_sel_hi:[1,1,0]
	s_nop 0
	v_pk_mul_f32 v[42:43], v[42:43], v[48:49]
	v_rcp_f32_e32 v48, v3
	v_mul_f32_e32 v3, 0xbfb8aa3b, v37
	v_exp_f32_e32 v3, v3
	s_nop 0
	v_add_f32_e32 v3, 1.0, v3
	v_rcp_f32_e32 v49, v3
	v_mul_f32_e32 v3, 0xbfb8aa3b, v38
	v_exp_f32_e32 v3, v3
	v_pk_mul_f32 v[36:37], v[36:37], v[48:49]
	v_add_f32_e32 v3, 1.0, v3
	v_rcp_f32_e32 v50, v3
	v_mul_f32_e32 v3, 0xbfb8aa3b, v39
	v_exp_f32_e32 v3, v3
	s_nop 0
	v_add_f32_e32 v3, 1.0, v3
	v_rcp_f32_e32 v51, v3
	s_nop 0
	v_pk_mul_f32 v[38:39], v[38:39], v[50:51]
	s_nop 0
	v_pk_mul_f32 v[42:43], v[38:39], v[42:43]
	v_pk_mul_f32 v[38:39], v[36:37], v[40:41]
	v_add_co_u32_e32 v40, vcc, s0, v116
	v_cvt_pk_bf16_f32 v36, v44, v45
	v_cvt_pk_bf16_f32 v37, v46, v47
	v_cvt_pk_bf16_f32 v38, v38, v39
	v_cvt_pk_bf16_f32 v39, v42, v43
	v_addc_co_u32_e32 v41, vcc, 0, v117, vcc
	global_store_dwordx4 v[40:41], v[36:39], off
	s_nop 1
	v_mov_b32_e32 v36, v206
	s_mov_b32 s0, 0xa0000
	v_pk_mul_f32 v[32:33], v[32:33], v[36:37] op_sel_hi:[1,0]
	s_nop 0
	v_med3_f32 v38, v32, -4.0, 4.0
	v_med3_f32 v39, v33, -4.0, 4.0
	v_pk_mul_f32 v[40:41], v[38:39], v[38:39]
	v_pk_mul_f32 v[34:35], v[34:35], v[36:37] op_sel_hi:[1,0]
	v_pk_fma_f32 v[40:41], v[40:41], s[72:73], -1.0 op_sel_hi:[1,0,0]
	v_pk_mul_f32 v[28:29], v[28:29], v[36:37] op_sel_hi:[1,0]
	v_pk_fma_f32 v[42:43], v[40:41], s[74:75], v[128:129] op_sel_hi:[1,0,0]
	v_mul_f32_e32 v3, 0xbfb8aa3b, v28
	v_pk_fma_f32 v[42:43], v[40:41], v[42:43], s[2:3] op_sel_hi:[1,1,0]
	v_exp_f32_e32 v3, v3
	v_pk_fma_f32 v[42:43], v[40:41], v[42:43], s[28:29] op_sel_hi:[1,1,0]
	v_pk_mul_f32 v[30:31], v[30:31], v[36:37] op_sel_hi:[1,0]
	v_pk_fma_f32 v[42:43], v[40:41], v[42:43], s[30:31] op_sel_hi:[1,1,0]
	v_add_f32_e32 v3, 1.0, v3
	v_pk_fma_f32 v[42:43], v[40:41], v[42:43], s[48:49] op_sel_hi:[1,1,0]
	v_pk_mul_f32 v[24:25], v[24:25], v[36:37] op_sel_hi:[1,0]
	v_pk_fma_f32 v[42:43], v[40:41], v[42:43], s[50:51] op_sel_hi:[1,1,0]
	v_pk_mul_f32 v[26:27], v[26:27], v[36:37] op_sel_hi:[1,0]
	v_pk_fma_f32 v[42:43], v[40:41], v[42:43], s[52:53] op_sel_hi:[1,1,0]
	v_pk_mul_f32 v[20:21], v[20:21], v[36:37] op_sel_hi:[1,0]
	v_pk_fma_f32 v[40:41], v[40:41], v[42:43], s[54:55] op_sel_hi:[1,1,0]
	v_pk_mul_f32 v[22:23], v[22:23], v[36:37] op_sel_hi:[1,0]
	v_pk_fma_f32 v[38:39], v[38:39], v[40:41], 0.5 op_sel_hi:[1,1,0]
	s_nop 0
	v_pk_mul_f32 v[32:33], v[32:33], v[38:39]
	v_med3_f32 v38, v34, -4.0, 4.0
	v_med3_f32 v39, v35, -4.0, 4.0
	v_pk_mul_f32 v[40:41], v[38:39], v[38:39]
	s_nop 0
	v_pk_fma_f32 v[40:41], v[40:41], s[72:73], -1.0 op_sel_hi:[1,0,0]
	s_nop 0
	v_pk_fma_f32 v[42:43], v[40:41], s[74:75], v[128:129] op_sel_hi:[1,0,0]
	s_nop 0
	v_pk_fma_f32 v[42:43], v[40:41], v[42:43], s[2:3] op_sel_hi:[1,1,0]
	s_nop 0
	v_pk_fma_f32 v[42:43], v[40:41], v[42:43], s[28:29] op_sel_hi:[1,1,0]
	s_nop 0
	v_pk_fma_f32 v[42:43], v[40:41], v[42:43], s[30:31] op_sel_hi:[1,1,0]
	s_nop 0
	v_pk_fma_f32 v[42:43], v[40:41], v[42:43], s[48:49] op_sel_hi:[1,1,0]
	s_nop 0
	v_pk_fma_f32 v[42:43], v[40:41], v[42:43], s[50:51] op_sel_hi:[1,1,0]
	s_nop 0
	v_pk_fma_f32 v[42:43], v[40:41], v[42:43], s[52:53] op_sel_hi:[1,1,0]
	s_nop 0
	v_pk_fma_f32 v[40:41], v[40:41], v[42:43], s[54:55] op_sel_hi:[1,1,0]
	s_nop 0
	v_pk_fma_f32 v[38:39], v[38:39], v[40:41], 0.5 op_sel_hi:[1,1,0]
	s_nop 0
	v_pk_mul_f32 v[34:35], v[34:35], v[38:39]
	v_rcp_f32_e32 v38, v3
	v_mul_f32_e32 v3, 0xbfb8aa3b, v29
	v_exp_f32_e32 v3, v3
	s_nop 0
	v_add_f32_e32 v3, 1.0, v3
	v_rcp_f32_e32 v39, v3
	v_mul_f32_e32 v3, 0xbfb8aa3b, v30
	v_exp_f32_e32 v3, v3
	v_pk_mul_f32 v[28:29], v[28:29], v[38:39]
	s_nop 0
	v_pk_mul_f32 v[28:29], v[28:29], v[32:33]
	v_add_f32_e32 v3, 1.0, v3
	v_rcp_f32_e32 v40, v3
	v_mul_f32_e32 v3, 0xbfb8aa3b, v31
	v_exp_f32_e32 v3, v3
	v_med3_f32 v32, v24, -4.0, 4.0
	v_med3_f32 v33, v25, -4.0, 4.0
	v_add_f32_e32 v3, 1.0, v3
	v_rcp_f32_e32 v41, v3
	v_mul_f32_e32 v3, 0xbfb8aa3b, v20
	v_exp_f32_e32 v3, v3
	v_pk_mul_f32 v[30:31], v[30:31], v[40:41]
	s_nop 0
	v_pk_mul_f32 v[30:31], v[30:31], v[34:35]
	v_pk_mul_f32 v[34:35], v[32:33], v[32:33]
	v_add_f32_e32 v3, 1.0, v3
	v_pk_fma_f32 v[34:35], v[34:35], s[72:73], -1.0 op_sel_hi:[1,0,0]
	s_nop 0
	v_pk_fma_f32 v[38:39], v[34:35], s[74:75], v[128:129] op_sel_hi:[1,0,0]
	s_nop 0
	v_pk_fma_f32 v[38:39], v[34:35], v[38:39], s[2:3] op_sel_hi:[1,1,0]
	s_nop 0
	v_pk_fma_f32 v[38:39], v[34:35], v[38:39], s[28:29] op_sel_hi:[1,1,0]
	s_nop 0
	v_pk_fma_f32 v[38:39], v[34:35], v[38:39], s[30:31] op_sel_hi:[1,1,0]
	s_nop 0
	v_pk_fma_f32 v[38:39], v[34:35], v[38:39], s[48:49] op_sel_hi:[1,1,0]
	s_nop 0
	v_pk_fma_f32 v[38:39], v[34:35], v[38:39], s[50:51] op_sel_hi:[1,1,0]
	s_nop 0
	v_pk_fma_f32 v[38:39], v[34:35], v[38:39], s[52:53] op_sel_hi:[1,1,0]
	s_nop 0
	v_pk_fma_f32 v[34:35], v[34:35], v[38:39], s[54:55] op_sel_hi:[1,1,0]
	s_nop 0
	v_pk_fma_f32 v[32:33], v[32:33], v[34:35], 0.5 op_sel_hi:[1,1,0]
	s_nop 0
	v_pk_mul_f32 v[24:25], v[24:25], v[32:33]
	v_med3_f32 v32, v26, -4.0, 4.0
	v_med3_f32 v33, v27, -4.0, 4.0
	v_pk_mul_f32 v[34:35], v[32:33], v[32:33]
	s_nop 0
	v_pk_fma_f32 v[34:35], v[34:35], s[72:73], -1.0 op_sel_hi:[1,0,0]
	s_nop 0
	v_pk_fma_f32 v[38:39], v[34:35], s[74:75], v[128:129] op_sel_hi:[1,0,0]
	s_nop 0
	v_pk_fma_f32 v[38:39], v[34:35], v[38:39], s[2:3] op_sel_hi:[1,1,0]
	s_nop 0
	v_pk_fma_f32 v[38:39], v[34:35], v[38:39], s[28:29] op_sel_hi:[1,1,0]
	s_nop 0
	v_pk_fma_f32 v[38:39], v[34:35], v[38:39], s[30:31] op_sel_hi:[1,1,0]
	s_nop 0
	v_pk_fma_f32 v[38:39], v[34:35], v[38:39], s[48:49] op_sel_hi:[1,1,0]
	s_nop 0
	v_pk_fma_f32 v[38:39], v[34:35], v[38:39], s[50:51] op_sel_hi:[1,1,0]
	s_nop 0
	v_pk_fma_f32 v[38:39], v[34:35], v[38:39], s[52:53] op_sel_hi:[1,1,0]
	s_nop 0
	v_pk_fma_f32 v[34:35], v[34:35], v[38:39], s[54:55] op_sel_hi:[1,1,0]
	s_nop 0
	v_pk_fma_f32 v[32:33], v[32:33], v[34:35], 0.5 op_sel_hi:[1,1,0]
	s_nop 0
	v_pk_mul_f32 v[26:27], v[26:27], v[32:33]
	v_rcp_f32_e32 v32, v3
	v_mul_f32_e32 v3, 0xbfb8aa3b, v21
	v_exp_f32_e32 v3, v3
	s_nop 0
	v_add_f32_e32 v3, 1.0, v3
	v_rcp_f32_e32 v33, v3
	v_mul_f32_e32 v3, 0xbfb8aa3b, v22
	v_exp_f32_e32 v3, v3
	v_pk_mul_f32 v[20:21], v[20:21], v[32:33]
	v_add_f32_e32 v3, 1.0, v3
	v_rcp_f32_e32 v34, v3
	v_mul_f32_e32 v3, 0xbfb8aa3b, v23
	v_exp_f32_e32 v3, v3
	s_nop 0
	v_add_f32_e32 v3, 1.0, v3
	v_rcp_f32_e32 v35, v3
	s_nop 0
	v_pk_mul_f32 v[22:23], v[22:23], v[34:35]
	s_nop 0
	v_pk_mul_f32 v[26:27], v[22:23], v[26:27]
	v_pk_mul_f32 v[22:23], v[20:21], v[24:25]
	v_add_co_u32_e32 v24, vcc, s0, v116
	v_cvt_pk_bf16_f32 v20, v28, v29
	v_cvt_pk_bf16_f32 v21, v30, v31
	v_cvt_pk_bf16_f32 v22, v22, v23
	v_cvt_pk_bf16_f32 v23, v26, v27
	v_addc_co_u32_e32 v25, vcc, 0, v117, vcc
	global_store_dwordx4 v[24:25], v[20:23], off
	s_nop 1
	v_mov_b32_e32 v20, v207
	v_pk_mul_f32 v[16:17], v[16:17], v[20:21] op_sel_hi:[1,0]
	s_nop 0
	v_med3_f32 v22, v16, -4.0, 4.0
	v_med3_f32 v23, v17, -4.0, 4.0
	v_pk_mul_f32 v[24:25], v[22:23], v[22:23]
	v_pk_mul_f32 v[18:19], v[18:19], v[20:21] op_sel_hi:[1,0]
	v_pk_fma_f32 v[24:25], v[24:25], s[72:73], -1.0 op_sel_hi:[1,0,0]
	v_pk_mul_f32 v[12:13], v[12:13], v[20:21] op_sel_hi:[1,0]
	v_pk_fma_f32 v[26:27], v[24:25], s[74:75], v[128:129] op_sel_hi:[1,0,0]
	v_mul_f32_e32 v3, 0xbfb8aa3b, v12
	v_pk_fma_f32 v[26:27], v[24:25], v[26:27], s[2:3] op_sel_hi:[1,1,0]
	v_exp_f32_e32 v3, v3
	v_pk_fma_f32 v[26:27], v[24:25], v[26:27], s[28:29] op_sel_hi:[1,1,0]
	v_pk_mul_f32 v[14:15], v[14:15], v[20:21] op_sel_hi:[1,0]
	v_pk_fma_f32 v[26:27], v[24:25], v[26:27], s[30:31] op_sel_hi:[1,1,0]
	v_add_f32_e32 v3, 1.0, v3
	v_pk_fma_f32 v[26:27], v[24:25], v[26:27], s[48:49] op_sel_hi:[1,1,0]
	v_pk_mul_f32 v[8:9], v[8:9], v[20:21] op_sel_hi:[1,0]
	v_pk_fma_f32 v[26:27], v[24:25], v[26:27], s[50:51] op_sel_hi:[1,1,0]
	v_pk_mul_f32 v[10:11], v[10:11], v[20:21] op_sel_hi:[1,0]
	v_pk_fma_f32 v[26:27], v[24:25], v[26:27], s[52:53] op_sel_hi:[1,1,0]
	v_pk_mul_f32 v[4:5], v[4:5], v[20:21] op_sel_hi:[1,0]
	v_pk_fma_f32 v[24:25], v[24:25], v[26:27], s[54:55] op_sel_hi:[1,1,0]
	v_pk_mul_f32 v[6:7], v[6:7], v[20:21] op_sel_hi:[1,0]
	v_pk_fma_f32 v[22:23], v[22:23], v[24:25], 0.5 op_sel_hi:[1,1,0]
	s_nop 0
	v_pk_mul_f32 v[16:17], v[16:17], v[22:23]
	v_med3_f32 v22, v18, -4.0, 4.0
	v_med3_f32 v23, v19, -4.0, 4.0
	v_pk_mul_f32 v[24:25], v[22:23], v[22:23]
	s_nop 0
	v_pk_fma_f32 v[24:25], v[24:25], s[72:73], -1.0 op_sel_hi:[1,0,0]
	s_nop 0
	v_pk_fma_f32 v[26:27], v[24:25], s[74:75], v[128:129] op_sel_hi:[1,0,0]
	s_nop 0
	v_pk_fma_f32 v[26:27], v[24:25], v[26:27], s[2:3] op_sel_hi:[1,1,0]
	s_nop 0
	v_pk_fma_f32 v[26:27], v[24:25], v[26:27], s[28:29] op_sel_hi:[1,1,0]
	s_nop 0
	v_pk_fma_f32 v[26:27], v[24:25], v[26:27], s[30:31] op_sel_hi:[1,1,0]
	s_nop 0
	v_pk_fma_f32 v[26:27], v[24:25], v[26:27], s[48:49] op_sel_hi:[1,1,0]
	s_nop 0
	v_pk_fma_f32 v[26:27], v[24:25], v[26:27], s[50:51] op_sel_hi:[1,1,0]
	s_nop 0
	v_pk_fma_f32 v[26:27], v[24:25], v[26:27], s[52:53] op_sel_hi:[1,1,0]
	s_nop 0
	v_pk_fma_f32 v[24:25], v[24:25], v[26:27], s[54:55] op_sel_hi:[1,1,0]
	s_nop 0
	v_pk_fma_f32 v[22:23], v[22:23], v[24:25], 0.5 op_sel_hi:[1,1,0]
	s_nop 0
	v_pk_mul_f32 v[18:19], v[18:19], v[22:23]
	v_rcp_f32_e32 v22, v3
	v_mul_f32_e32 v3, 0xbfb8aa3b, v13
	v_exp_f32_e32 v3, v3
	s_nop 0
	v_add_f32_e32 v3, 1.0, v3
	v_rcp_f32_e32 v23, v3
	v_mul_f32_e32 v3, 0xbfb8aa3b, v14
	v_exp_f32_e32 v3, v3
	v_pk_mul_f32 v[12:13], v[12:13], v[22:23]
	s_nop 0
	v_pk_mul_f32 v[12:13], v[12:13], v[16:17]
	v_add_f32_e32 v3, 1.0, v3
	v_rcp_f32_e32 v24, v3
	v_mul_f32_e32 v3, 0xbfb8aa3b, v15
	v_exp_f32_e32 v3, v3
	v_med3_f32 v16, v8, -4.0, 4.0
	v_med3_f32 v17, v9, -4.0, 4.0
	v_add_f32_e32 v3, 1.0, v3
	v_rcp_f32_e32 v25, v3
	v_mul_f32_e32 v3, 0xbfb8aa3b, v4
	v_exp_f32_e32 v3, v3
	v_pk_mul_f32 v[14:15], v[14:15], v[24:25]
	s_nop 0
	v_pk_mul_f32 v[14:15], v[14:15], v[18:19]
	v_pk_mul_f32 v[18:19], v[16:17], v[16:17]
	v_add_f32_e32 v3, 1.0, v3
	v_pk_fma_f32 v[18:19], v[18:19], s[72:73], -1.0 op_sel_hi:[1,0,0]
	s_nop 0
	v_pk_fma_f32 v[22:23], v[18:19], s[74:75], v[128:129] op_sel_hi:[1,0,0]
	s_nop 0
	v_pk_fma_f32 v[22:23], v[18:19], v[22:23], s[2:3] op_sel_hi:[1,1,0]
	s_nop 0
	v_pk_fma_f32 v[22:23], v[18:19], v[22:23], s[28:29] op_sel_hi:[1,1,0]
	s_nop 0
	v_pk_fma_f32 v[22:23], v[18:19], v[22:23], s[30:31] op_sel_hi:[1,1,0]
	s_nop 0
	v_pk_fma_f32 v[22:23], v[18:19], v[22:23], s[48:49] op_sel_hi:[1,1,0]
	s_nop 0
	v_pk_fma_f32 v[22:23], v[18:19], v[22:23], s[50:51] op_sel_hi:[1,1,0]
	s_nop 0
	v_pk_fma_f32 v[22:23], v[18:19], v[22:23], s[52:53] op_sel_hi:[1,1,0]
	s_nop 0
	v_pk_fma_f32 v[18:19], v[18:19], v[22:23], s[54:55] op_sel_hi:[1,1,0]
	s_nop 0
	v_pk_fma_f32 v[16:17], v[16:17], v[18:19], 0.5 op_sel_hi:[1,1,0]
	s_nop 0
	v_pk_mul_f32 v[8:9], v[8:9], v[16:17]
	v_med3_f32 v16, v10, -4.0, 4.0
	v_med3_f32 v17, v11, -4.0, 4.0
	v_pk_mul_f32 v[18:19], v[16:17], v[16:17]
	s_nop 0
	v_pk_fma_f32 v[18:19], v[18:19], s[72:73], -1.0 op_sel_hi:[1,0,0]
	s_nop 0
	v_pk_fma_f32 v[22:23], v[18:19], s[74:75], v[128:129] op_sel_hi:[1,0,0]
	s_nop 0
	v_pk_fma_f32 v[22:23], v[18:19], v[22:23], s[2:3] op_sel_hi:[1,1,0]
	s_nop 0
	v_pk_fma_f32 v[22:23], v[18:19], v[22:23], s[28:29] op_sel_hi:[1,1,0]
	s_nop 0
	v_pk_fma_f32 v[22:23], v[18:19], v[22:23], s[30:31] op_sel_hi:[1,1,0]
	s_nop 0
	v_pk_fma_f32 v[22:23], v[18:19], v[22:23], s[48:49] op_sel_hi:[1,1,0]
	s_nop 0
	v_pk_fma_f32 v[22:23], v[18:19], v[22:23], s[50:51] op_sel_hi:[1,1,0]
	s_nop 0
	v_pk_fma_f32 v[22:23], v[18:19], v[22:23], s[52:53] op_sel_hi:[1,1,0]
	s_nop 0
	v_pk_fma_f32 v[18:19], v[18:19], v[22:23], s[54:55] op_sel_hi:[1,1,0]
	s_nop 0
	v_pk_fma_f32 v[16:17], v[16:17], v[18:19], 0.5 op_sel_hi:[1,1,0]
	s_nop 0
	v_pk_mul_f32 v[10:11], v[10:11], v[16:17]
	v_rcp_f32_e32 v16, v3
	v_mul_f32_e32 v3, 0xbfb8aa3b, v5
	v_exp_f32_e32 v3, v3
	s_nop 0
	v_add_f32_e32 v3, 1.0, v3
	v_rcp_f32_e32 v17, v3
	v_mul_f32_e32 v3, 0xbfb8aa3b, v6
	v_exp_f32_e32 v3, v3
	v_pk_mul_f32 v[4:5], v[4:5], v[16:17]
	v_add_f32_e32 v3, 1.0, v3
	v_rcp_f32_e32 v18, v3
	v_mul_f32_e32 v3, 0xbfb8aa3b, v7
	v_exp_f32_e32 v3, v3
	s_nop 0
	v_add_f32_e32 v3, 1.0, v3
	v_rcp_f32_e32 v19, v3
	s_nop 0
	v_pk_mul_f32 v[6:7], v[6:7], v[18:19]
	s_nop 0
	v_pk_mul_f32 v[10:11], v[6:7], v[10:11]
	v_pk_mul_f32 v[6:7], v[4:5], v[8:9]
	v_add_co_u32_e32 v8, vcc, 0xb0000, v116
	v_cvt_pk_bf16_f32 v4, v12, v13
	v_cvt_pk_bf16_f32 v5, v14, v15
	v_cvt_pk_bf16_f32 v6, v6, v7
	v_cvt_pk_bf16_f32 v7, v10, v11
	v_addc_co_u32_e32 v9, vcc, 0, v117, vcc
	global_store_dwordx4 v[8:9], v[4:7], off
	s_andn2_b64 vcc, exec, s[6:7]
	s_mov_b64 s[0:1], -1
	s_cbranch_vccnz .LBB0_442
